# SGU group epilogue: second spatial-bias scalar load issued together with the first (one L2 round trip less per group iteration)
# baseline (speedup 1.0000x reference)
; __device__ __forceinline__ unsigned pk2(float lo, float hi) { f32x2 v = {lo, hi}; bf16x2_t b = __builtin_convertvector(v, bf16x2_t); return __builtin_bit_cast(unsigned, b); }
; #define MFMA32(a, b, c) __builtin_amdgcn_mfma_f32_32x32x16_bf16((a), (b), (c), 0, 0, 0)
; __device__ __forceinline__ void unpack8(const u32x4 w, float* v) { v[0] = bflo(w.x); v[1] = bfhi(w.x); v[2] = bflo(w.y); v[3] = bfhi(w.y); v[4] = bflo(w.z); v[5] = bfhi(w.z); v[6] = bflo(w.w); v[7] = bfhi(w.w); }
; template <int tbA, int tbB> ...
;     for (int gi = 0; gi < 4; ++gi) {
;         const int g = gh * 4 + gi;
;         const int ch = g * 128 + cb * 32 + r;
;         const float gg = lng[ch], bb = lnb[ch];
;         const bf16_t* ap = VCT + (size_t)ch * PT + tok0 + 8 * hh;
;         const bf16_t* wp = Wbf + (size_t)g * 16384 + 8 * hh;
;         constexpr int NSB = (tbB + 1) * 2, NSA = (tbA + 1) * 2;
;         int so = 0; asm volatile("" : "+v"(so));
;         u32x4 raw[NSB]; bf16x8 wB[NSB], wA[NSA];
; #pragma unroll
;         for (int k = 0; k < NSB; ++k) { raw[k] = *(const u32x4*)(ap + 16 * k); wB[k] = *(const bf16x8*)(wp + (size_t)(tbB * 32 + r) * 128 + 16 * k); }
; #pragma unroll
;         for (int k = 0; k < NSA; ++k) wA[k] = *(const bf16x8*)(wp + (size_t)(tbA * 32 + r) * 128 + 16 * k);
;         f32x16 accA, accB;
; #pragma unroll
;         for (int i = 0; i < 16; ++i) { accA[i] = 0.f; accB[i] = 0.f; }
; #pragma unroll
;         for (int k = 0; k < NSB; ++k) {
;             float v[8]; unpack8(raw[k], v);
; #pragma unroll
;             for (int jj = 0; jj < 8; ++jj) { const float mean = stat[(16 * k + 8 * hh + jj) * 2 + so], rstd = stat[(16 * k + 8 * hh + jj) * 2 + 1 + so]; v[jj] = (v[jj] - mean) * rstd * gg + bb; }
;             u32x4 af; af.x = pk2(v[0], v[1]); af.y = pk2(v[2], v[3]); af.z = pk2(v[4], v[5]); af.w = pk2(v[6], v[7]);
;             accB = MFMA32(__builtin_bit_cast(bf16x8, af), wB[k], accB);
;             if (k < NSA) accA = MFMA32(__builtin_bit_cast(bf16x8, af), wA[k < NSA ? k : 0], accA);
;         }
.LBB0_229:
	v_lshl_add_u64 v[8:9], v[52:53], 0, v[148:149]
	v_mov_b32_e32 v14, v133
	global_load_dword v60, v[56:57], off
	global_load_dword v62, v[54:55], off
	global_load_dwordx4 v[0:3], v[8:9], off offset:-96
	v_lshl_add_u64 v[10:11], v[58:59], 0, v[148:149]
	v_add_co_u32_e32 v12, vcc, s95, v10
	v_lshl_add_u32 v74, v14, 2, v158
	s_nop 0
	v_addc_co_u32_e32 v13, vcc, 0, v11, vcc
	v_add_co_u32_e32 v20, vcc, s96, v10
	global_load_dwordx4 v[4:7], v[12:13], off
	global_load_dwordx4 v[68:71], v[8:9], off offset:-64
	global_load_dwordx4 v[76:79], v[12:13], off offset:32
	global_load_dwordx4 v[80:83], v[8:9], off offset:-32
	global_load_dwordx4 v[84:87], v[12:13], off offset:64
	global_load_dwordx4 v[88:91], v[8:9], off
	global_load_dwordx4 v[92:95], v[12:13], off offset:96
	global_load_dwordx4 v[44:47], v[8:9], off offset:32
	global_load_dwordx4 v[40:43], v[12:13], off offset:128
	global_load_dwordx4 v[36:39], v[8:9], off offset:64
	global_load_dwordx4 v[32:35], v[12:13], off offset:160
	v_addc_co_u32_e32 v21, vcc, 0, v11, vcc
	v_add_u32_e32 v12, 0x2000, v74
	global_load_dwordx4 v[96:99], v[20:21], off offset:32
	global_load_dwordx4 v[100:103], v[20:21], off offset:64
	global_load_dwordx4 v[104:107], v[20:21], off offset:96
	v_add_u32_e32 v110, 0x2080, v74
	v_lshl_add_u64 v[58:59], v[58:59], 0, s[58:59]
	v_lshl_add_u64 v[52:53], v[52:53], 0, s[60:61]
	v_lshl_add_u64 v[54:55], v[54:55], 0, s[62:63]
	v_lshl_add_u64 v[56:57], v[56:57], 0, s[62:63]
	s_waitcnt vmcnt(12)
	v_lshlrev_b32_e32 v72, 16, v68
	v_lshlrev_b32_e32 v8, 16, v0
	v_and_b32_e32 v9, 0xffff0000, v0
	v_add_u32_e32 v0, 0x2008, v74
	ds_read2_b32 v[10:11], v0 offset1:1
	ds_read2_b32 v[12:13], v12 offset1:1
	v_lshlrev_b32_e32 v0, 16, v1
	v_and_b32_e32 v1, 0xffff0000, v1
	v_and_b32_e32 v73, 0xffff0000, v68
	s_waitcnt lgkmcnt(1)
	v_mov_b32_e32 v15, v10
	s_waitcnt lgkmcnt(0)
	v_mov_b32_e32 v14, v12
	v_pk_add_f32 v[8:9], v[8:9], v[14:15] neg_lo:[0,1] neg_hi:[0,1]
	v_mov_b32_e32 v10, v13
	v_pk_mul_f32 v[8:9], v[8:9], v[10:11]
	v_add_u32_e32 v12, 0x2010, v74
	v_add_u32_e32 v10, 0x2018, v74
	ds_read2_b32 v[10:11], v10 offset1:1
	ds_read2_b32 v[12:13], v12 offset1:1
	v_add_u32_e32 v68, 0x2088, v74
	v_pk_fma_f32 v[8:9], v[60:61], v[8:9], v[62:63] op_sel_hi:[0,1,0]
	s_waitcnt lgkmcnt(1)
	v_mov_b32_e32 v15, v10
	s_waitcnt lgkmcnt(0)
	v_mov_b32_e32 v14, v12
	v_pk_add_f32 v[0:1], v[0:1], v[14:15] neg_lo:[0,1] neg_hi:[0,1]
	v_mov_b32_e32 v10, v13
	v_pk_mul_f32 v[0:1], v[0:1], v[10:11]
	v_add_u32_e32 v14, 0x2020, v74
	v_lshlrev_b32_e32 v10, 16, v2
	v_and_b32_e32 v11, 0xffff0000, v2
	v_add_u32_e32 v2, 0x2028, v74
	ds_read2_b32 v[12:13], v2 offset1:1
	ds_read2_b32 v[14:15], v14 offset1:1
	v_lshlrev_b32_e32 v2, 16, v3
	v_and_b32_e32 v3, 0xffff0000, v3
	v_pk_fma_f32 v[0:1], v[60:61], v[0:1], v[62:63] op_sel_hi:[0,1,0]
	s_waitcnt lgkmcnt(1)
	v_mov_b32_e32 v17, v12
	s_waitcnt lgkmcnt(0)
	v_mov_b32_e32 v16, v14
	v_pk_add_f32 v[10:11], v[10:11], v[16:17] neg_lo:[0,1] neg_hi:[0,1]
	v_mov_b32_e32 v12, v15
	v_pk_mul_f32 v[10:11], v[10:11], v[12:13]
	v_add_u32_e32 v14, 0x2030, v74
	v_add_u32_e32 v12, 0x2038, v74
	ds_read2_b32 v[12:13], v12 offset1:1
	ds_read2_b32 v[14:15], v14 offset1:1
	global_load_dwordx4 v[20:23], v[20:21], off
	ds_read2_b32 v[108:109], v68 offset1:1
	ds_read2_b32 v[110:111], v110 offset1:1
	v_lshlrev_b32_e32 v68, 16, v69
	v_and_b32_e32 v69, 0xffff0000, v69
	s_waitcnt lgkmcnt(2)
	v_mov_b32_e32 v16, v14
	s_waitcnt lgkmcnt(1)
	v_mov_b32_e32 v113, v108
	s_waitcnt lgkmcnt(0)
	v_mov_b32_e32 v112, v110
	v_pk_add_f32 v[72:73], v[72:73], v[112:113] neg_lo:[0,1] neg_hi:[0,1]
	v_mov_b32_e32 v108, v111
	v_pk_mul_f32 v[72:73], v[72:73], v[108:109]
	v_add_u32_e32 v110, 0x2090, v74
	v_add_u32_e32 v108, 0x2098, v74
	ds_read2_b32 v[108:109], v108 offset1:1
	ds_read2_b32 v[110:111], v110 offset1:1
	v_mov_b32_e32 v17, v12
	v_pk_add_f32 v[2:3], v[2:3], v[16:17] neg_lo:[0,1] neg_hi:[0,1]
	v_mov_b32_e32 v12, v15
	s_waitcnt lgkmcnt(1)
	v_mov_b32_e32 v113, v108
	s_waitcnt lgkmcnt(0)
	v_mov_b32_e32 v112, v110
	v_pk_add_f32 v[68:69], v[68:69], v[112:113] neg_lo:[0,1] neg_hi:[0,1]
	v_mov_b32_e32 v108, v111
	v_pk_mul_f32 v[68:69], v[68:69], v[108:109]
	v_add_u32_e32 v112, 0x20a0, v74
	v_pk_fma_f32 v[108:109], v[60:61], v[68:69], v[62:63] op_sel_hi:[0,1,0]
	v_lshlrev_b32_e32 v68, 16, v70
	v_and_b32_e32 v69, 0xffff0000, v70
	v_add_u32_e32 v70, 0x20a8, v74
	ds_read2_b32 v[110:111], v70 offset1:1
	ds_read2_b32 v[112:113], v112 offset1:1
	v_pk_mul_f32 v[2:3], v[2:3], v[12:13]
	v_add_u32_e32 v70, 0x20b8, v74
	v_pk_fma_f32 v[10:11], v[60:61], v[10:11], v[62:63] op_sel_hi:[0,1,0]
	s_waitcnt lgkmcnt(1)
	v_mov_b32_e32 v115, v110
	s_waitcnt lgkmcnt(0)
	v_mov_b32_e32 v114, v112
	v_pk_add_f32 v[68:69], v[68:69], v[114:115] neg_lo:[0,1] neg_hi:[0,1]
	v_mov_b32_e32 v110, v113
	v_pk_mul_f32 v[68:69], v[68:69], v[110:111]
	v_add_u32_e32 v112, 0x20b0, v74
	v_pk_fma_f32 v[2:3], v[60:61], v[2:3], v[62:63] op_sel_hi:[0,1,0]
	v_pk_fma_f32 v[110:111], v[60:61], v[68:69], v[62:63] op_sel_hi:[0,1,0]
	v_lshlrev_b32_e32 v68, 16, v71
	v_and_b32_e32 v69, 0xffff0000, v71
	ds_read2_b32 v[70:71], v70 offset1:1
	ds_read2_b32 v[112:113], v112 offset1:1
	v_cvt_pk_bf16_f32 v16, v8, v9
	v_cvt_pk_bf16_f32 v17, v0, v1
	v_cvt_pk_bf16_f32 v18, v10, v11
	v_cvt_pk_bf16_f32 v19, v2, v3
	s_waitcnt lgkmcnt(0)
	v_mov_b32_e32 v114, v112
	v_mov_b32_e32 v115, v70
	v_mfma_f32_32x32x16_bf16 v[0:15], v[16:19], v[4:7], 0
	v_add_f32_e64 v68, v68, -v114
	v_add_f32_e64 v69, v69, -v115
	v_mov_b32_e32 v70, v113
	v_mul_f32_e64 v68, v68, v70
	v_mul_f32_e64 v69, v69, v71
	v_pk_fma_f32 v[72:73], v[60:61], v[72:73], v[62:63] op_sel_hi:[0,1,0]
	v_pk_fma_f32 v[112:113], v[60:61], v[68:69], v[62:63] op_sel_hi:[0,1,0]
	v_cvt_pk_bf16_f32 v68, v72, v73
	v_cvt_pk_bf16_f32 v69, v108, v109
	v_cvt_pk_bf16_f32 v70, v110, v111
	v_cvt_pk_bf16_f32 v71, v112, v113
	v_add_u32_e32 v72, 0x2100, v74
	s_waitcnt vmcnt(0)
; __device__ __forceinline__ unsigned pk2(float lo, float hi) { f32x2 v = {lo, hi}; bf16x2_t b = __builtin_convertvector(v, bf16x2_t); return __builtin_bit_cast(unsigned, b); }
; #define MFMA32(a, b, c) __builtin_amdgcn_mfma_f32_32x32x16_bf16((a), (b), (c), 0, 0, 0)
; __device__ __forceinline__ void unpack8(const u32x4 w, float* v) { v[0] = bflo(w.x); v[1] = bfhi(w.x); v[2] = bflo(w.y); v[3] = bfhi(w.y); v[4] = bflo(w.z); v[5] = bfhi(w.z); v[6] = bflo(w.w); v[7] = bfhi(w.w); }
; template <int tbA, int tbB> ...
;     ...
; #pragma unroll
;         for (int k = 0; k < NSB; ++k) {
;             float v[8]; unpack8(raw[k], v);
; #pragma unroll
;             for (int jj = 0; jj < 8; ++jj) { const float mean = stat[(16 * k + 8 * hh + jj) * 2 + so], rstd = stat[(16 * k + 8 * hh + jj) * 2 + 1 + so]; v[jj] = (v[jj] - mean) * rstd * gg + bb; }
;             u32x4 af; af.x = pk2(v[0], v[1]); af.y = pk2(v[2], v[3]); af.z = pk2(v[4], v[5]); af.w = pk2(v[6], v[7]);
;             accB = MFMA32(__builtin_bit_cast(bf16x8, af), wB[k], accB);
;             if (k < NSA) accA = MFMA32(__builtin_bit_cast(bf16x8, af), wA[k < NSA ? k : 0], accA);
;         }
	v_mfma_f32_32x32x16_bf16 v[16:31], v[16:19], v[20:23], 0
	v_mfma_f32_32x32x16_bf16 v[0:15], v[68:71], v[76:79], v[0:15]
	v_mfma_f32_32x32x16_bf16 v[16:31], v[68:71], v[96:99], v[16:31]
	v_add_u32_e32 v70, 0x2108, v74
	ds_read2_b32 v[70:71], v70 offset1:1
	ds_read2_b32 v[72:73], v72 offset1:1
	v_lshlrev_b32_e32 v68, 16, v80
	v_and_b32_e32 v69, 0xffff0000, v80
	s_waitcnt lgkmcnt(1)
	v_mov_b32_e32 v77, v70
	s_waitcnt lgkmcnt(0)
	v_mov_b32_e32 v76, v72
	v_pk_add_f32 v[68:69], v[68:69], v[76:77] neg_lo:[0,1] neg_hi:[0,1]
	v_add_u32_e32 v76, 0x2110, v74
	v_add_u32_e32 v72, 0x2118, v74
	v_mov_b32_e32 v70, v73
	ds_read2_b32 v[72:73], v72 offset1:1
	ds_read2_b32 v[76:77], v76 offset1:1
	v_pk_mul_f32 v[68:69], v[68:69], v[70:71]
	v_lshlrev_b32_e32 v70, 16, v81
	v_and_b32_e32 v71, 0xffff0000, v81
	s_waitcnt lgkmcnt(1)
	v_mov_b32_e32 v79, v72
	s_waitcnt lgkmcnt(0)
	v_mov_b32_e32 v78, v76
	v_pk_add_f32 v[70:71], v[70:71], v[78:79] neg_lo:[0,1] neg_hi:[0,1]
	v_add_u32_e32 v78, 0x2120, v74
	v_add_u32_e32 v76, 0x2128, v74
	v_mov_b32_e32 v72, v77
	ds_read2_b32 v[76:77], v76 offset1:1
	ds_read2_b32 v[78:79], v78 offset1:1
	v_pk_mul_f32 v[70:71], v[70:71], v[72:73]
	v_lshlrev_b32_e32 v72, 16, v82
	v_and_b32_e32 v73, 0xffff0000, v82
	s_waitcnt lgkmcnt(1)
	v_mov_b32_e32 v81, v76
	s_waitcnt lgkmcnt(0)
	v_mov_b32_e32 v80, v78
	v_pk_add_f32 v[72:73], v[72:73], v[80:81] neg_lo:[0,1] neg_hi:[0,1]
	v_add_u32_e32 v80, 0x2130, v74
	v_add_u32_e32 v78, 0x2138, v74
	v_mov_b32_e32 v76, v79
	ds_read2_b32 v[78:79], v78 offset1:1
	ds_read2_b32 v[80:81], v80 offset1:1
	v_pk_mul_f32 v[72:73], v[72:73], v[76:77]
	v_lshlrev_b32_e32 v76, 16, v83
	v_and_b32_e32 v77, 0xffff0000, v83
	s_waitcnt lgkmcnt(1)
	v_mov_b32_e32 v83, v78
	s_waitcnt lgkmcnt(0)
	v_mov_b32_e32 v82, v80
	v_pk_add_f32 v[76:77], v[76:77], v[82:83] neg_lo:[0,1] neg_hi:[0,1]
	v_mov_b32_e32 v78, v81
	v_pk_mul_f32 v[76:77], v[76:77], v[78:79]
	v_pk_fma_f32 v[68:69], v[60:61], v[68:69], v[62:63] op_sel_hi:[0,1,0]
	v_pk_fma_f32 v[70:71], v[60:61], v[70:71], v[62:63] op_sel_hi:[0,1,0]
	v_pk_fma_f32 v[72:73], v[60:61], v[72:73], v[62:63] op_sel_hi:[0,1,0]
	v_pk_fma_f32 v[76:77], v[60:61], v[76:77], v[62:63] op_sel_hi:[0,1,0]
	v_cvt_pk_bf16_f32 v68, v68, v69
	v_cvt_pk_bf16_f32 v69, v70, v71
	v_cvt_pk_bf16_f32 v70, v72, v73
	v_cvt_pk_bf16_f32 v71, v76, v77
	v_add_u32_e32 v72, 0x2180, v74
	s_nop 0
	v_mfma_f32_32x32x16_bf16 v[0:15], v[68:71], v[84:87], v[0:15]
	v_mfma_f32_32x32x16_bf16 v[16:31], v[68:71], v[100:103], v[16:31]
	v_add_u32_e32 v70, 0x2188, v74
	ds_read2_b32 v[70:71], v70 offset1:1
	ds_read2_b32 v[72:73], v72 offset1:1
	v_lshlrev_b32_e32 v68, 16, v88
	v_and_b32_e32 v69, 0xffff0000, v88
	s_waitcnt lgkmcnt(1)
	v_mov_b32_e32 v77, v70
	s_waitcnt lgkmcnt(0)
	v_mov_b32_e32 v76, v72
	v_pk_add_f32 v[68:69], v[68:69], v[76:77] neg_lo:[0,1] neg_hi:[0,1]
	v_add_u32_e32 v76, 0x2190, v74
	v_add_u32_e32 v72, 0x2198, v74
	v_mov_b32_e32 v70, v73
	ds_read2_b32 v[72:73], v72 offset1:1
	ds_read2_b32 v[76:77], v76 offset1:1
	v_pk_mul_f32 v[68:69], v[68:69], v[70:71]
	v_lshlrev_b32_e32 v70, 16, v89
	v_and_b32_e32 v71, 0xffff0000, v89
	s_waitcnt lgkmcnt(1)
	v_mov_b32_e32 v79, v72
	s_waitcnt lgkmcnt(0)
	v_mov_b32_e32 v78, v76
	v_pk_add_f32 v[70:71], v[70:71], v[78:79] neg_lo:[0,1] neg_hi:[0,1]
	v_add_u32_e32 v78, 0x21a0, v74
	v_add_u32_e32 v76, 0x21a8, v74
	v_mov_b32_e32 v72, v77
	ds_read2_b32 v[76:77], v76 offset1:1
	ds_read2_b32 v[78:79], v78 offset1:1
	v_pk_mul_f32 v[70:71], v[70:71], v[72:73]
	v_lshlrev_b32_e32 v72, 16, v90
	v_and_b32_e32 v73, 0xffff0000, v90
	s_waitcnt lgkmcnt(1)
	v_mov_b32_e32 v81, v76
	s_waitcnt lgkmcnt(0)
	v_mov_b32_e32 v80, v78
	v_pk_add_f32 v[72:73], v[72:73], v[80:81] neg_lo:[0,1] neg_hi:[0,1]
	v_add_u32_e32 v80, 0x21b0, v74
	v_add_u32_e32 v78, 0x21b8, v74
	v_mov_b32_e32 v76, v79
	ds_read2_b32 v[78:79], v78 offset1:1
	ds_read2_b32 v[80:81], v80 offset1:1
	v_pk_mul_f32 v[72:73], v[72:73], v[76:77]
	v_lshlrev_b32_e32 v76, 16, v91
	v_and_b32_e32 v77, 0xffff0000, v91
	s_waitcnt lgkmcnt(1)
	v_mov_b32_e32 v83, v78
	s_waitcnt lgkmcnt(0)
	v_mov_b32_e32 v82, v80
	v_pk_add_f32 v[76:77], v[76:77], v[82:83] neg_lo:[0,1] neg_hi:[0,1]
	v_mov_b32_e32 v78, v81
	v_pk_mul_f32 v[76:77], v[76:77], v[78:79]
	v_pk_fma_f32 v[68:69], v[60:61], v[68:69], v[62:63] op_sel_hi:[0,1,0]
	v_pk_fma_f32 v[70:71], v[60:61], v[70:71], v[62:63] op_sel_hi:[0,1,0]
	v_pk_fma_f32 v[72:73], v[60:61], v[72:73], v[62:63] op_sel_hi:[0,1,0]
	v_pk_fma_f32 v[76:77], v[60:61], v[76:77], v[62:63] op_sel_hi:[0,1,0]
	v_cvt_pk_bf16_f32 v68, v68, v69
	v_cvt_pk_bf16_f32 v69, v70, v71
	v_cvt_pk_bf16_f32 v70, v72, v73
	v_cvt_pk_bf16_f32 v71, v76, v77
	v_add_u32_e32 v72, 0x2200, v74
	s_nop 0
	v_mfma_f32_32x32x16_bf16 v[0:15], v[68:71], v[92:95], v[0:15]
	v_mfma_f32_32x32x16_bf16 v[16:31], v[68:71], v[104:107], v[16:31]
	v_lshlrev_b32_e32 v68, 16, v44
	v_and_b32_e32 v69, 0xffff0000, v44
	v_add_u32_e32 v44, 0x2208, v74
	ds_read2_b32 v[70:71], v44 offset1:1
	ds_read2_b32 v[72:73], v72 offset1:1
	v_lshlrev_b32_e32 v44, 16, v45
	v_and_b32_e32 v45, 0xffff0000, v45
	s_waitcnt lgkmcnt(1)
	v_mov_b32_e32 v77, v70
	s_waitcnt lgkmcnt(0)
	v_mov_b32_e32 v76, v72
	v_pk_add_f32 v[68:69], v[68:69], v[76:77] neg_lo:[0,1] neg_hi:[0,1]
	v_mov_b32_e32 v70, v73
	v_pk_mul_f32 v[68:69], v[68:69], v[70:71]
	v_add_u32_e32 v72, 0x2210, v74
	v_add_u32_e32 v70, 0x2218, v74
	ds_read2_b32 v[70:71], v70 offset1:1
	ds_read2_b32 v[72:73], v72 offset1:1
	v_pk_fma_f32 v[68:69], v[60:61], v[68:69], v[62:63] op_sel_hi:[0,1,0]
	s_waitcnt lgkmcnt(1)
	v_mov_b32_e32 v77, v70
	s_waitcnt lgkmcnt(0)
; #define LAS __attribute__((address_space(3)))
; __device__ __forceinline__ unsigned pk2(float lo, float hi) { f32x2 v = {lo, hi}; bf16x2_t b = __builtin_convertvector(v, bf16x2_t); return __builtin_bit_cast(unsigned, b); }
; #define MFMA32(a, b, c) __builtin_amdgcn_mfma_f32_32x32x16_bf16((a), (b), (c), 0, 0, 0)
; __device__ __forceinline__ void unpack8(const u32x4 w, float* v) { v[0] = bflo(w.x); v[1] = bfhi(w.x); v[2] = bflo(w.y); v[3] = bfhi(w.y); v[4] = bflo(w.z); v[5] = bfhi(w.z); v[6] = bflo(w.w); v[7] = bfhi(w.w); }
; template <int tbA, int tbB> ...
;     ...
; #pragma unroll
;         for (int k = 0; k < NSB; ++k) {
;             float v[8]; unpack8(raw[k], v);
; #pragma unroll
;             for (int jj = 0; jj < 8; ++jj) { const float mean = stat[(16 * k + 8 * hh + jj) * 2 + so], rstd = stat[(16 * k + 8 * hh + jj) * 2 + 1 + so]; v[jj] = (v[jj] - mean) * rstd * gg + bb; }
;             u32x4 af; af.x = pk2(v[0], v[1]); af.y = pk2(v[2], v[3]); af.z = pk2(v[4], v[5]); af.w = pk2(v[6], v[7]);
;             accB = MFMA32(__builtin_bit_cast(bf16x8, af), wB[k], accB);
;             if (k < NSA) accA = MFMA32(__builtin_bit_cast(bf16x8, af), wA[k < NSA ? k : 0], accA);
;         }
; #pragma unroll
;         for (int which = 0; which < 2; ++which) {
;             const int tb = which ? tbB : tbA; const f32x16& acc = which ? accB : accA;
;             const float sbv = spb[g * 128 + tb * 32 + r];
; #pragma unroll
;             for (int q = 0; q < 4; ++q) {
;                 u32x2 w; w.x = pk2(acc[4 * q + 0] + sbv, acc[4 * q + 1] + sbv); w.y = pk2(acc[4 * q + 2] + sbv, acc[4 * q + 3] + sbv);
;                 *(LAS u32x2*)(stg + which * 2560 + r * 80 + (8 * q + 4 * hh) * 2) = w;
;             }
	v_mov_b32_e32 v76, v72
	v_pk_add_f32 v[44:45], v[44:45], v[76:77] neg_lo:[0,1] neg_hi:[0,1]
	v_mov_b32_e32 v70, v73
	v_pk_mul_f32 v[44:45], v[44:45], v[70:71]
	v_add_u32_e32 v76, 0x2220, v74
	v_pk_fma_f32 v[70:71], v[60:61], v[44:45], v[62:63] op_sel_hi:[0,1,0]
	v_lshlrev_b32_e32 v44, 16, v46
	v_and_b32_e32 v45, 0xffff0000, v46
	v_add_u32_e32 v46, 0x2228, v74
	ds_read2_b32 v[72:73], v46 offset1:1
	ds_read2_b32 v[76:77], v76 offset1:1
	v_add_u32_e32 v46, 0x2238, v74
	s_waitcnt lgkmcnt(1)
	v_mov_b32_e32 v79, v72
	s_waitcnt lgkmcnt(0)
	v_mov_b32_e32 v78, v76
	v_pk_add_f32 v[44:45], v[44:45], v[78:79] neg_lo:[0,1] neg_hi:[0,1]
	v_mov_b32_e32 v72, v77
	v_pk_mul_f32 v[44:45], v[44:45], v[72:73]
	v_add_u32_e32 v76, 0x2230, v74
	v_pk_fma_f32 v[72:73], v[60:61], v[44:45], v[62:63] op_sel_hi:[0,1,0]
	v_lshlrev_b32_e32 v44, 16, v47
	v_and_b32_e32 v45, 0xffff0000, v47
	ds_read2_b32 v[46:47], v46 offset1:1
	ds_read2_b32 v[76:77], v76 offset1:1
	s_waitcnt lgkmcnt(1)
	v_mov_b32_e32 v79, v46
	s_waitcnt lgkmcnt(0)
	v_mov_b32_e32 v78, v76
	v_pk_add_f32 v[44:45], v[44:45], v[78:79] neg_lo:[0,1] neg_hi:[0,1]
	v_mov_b32_e32 v46, v77
	v_pk_mul_f32 v[44:45], v[44:45], v[46:47]
	v_cvt_pk_bf16_f32 v46, v72, v73
	v_pk_fma_f32 v[76:77], v[60:61], v[44:45], v[62:63] op_sel_hi:[0,1,0]
	v_cvt_pk_bf16_f32 v44, v68, v69
	v_cvt_pk_bf16_f32 v45, v70, v71
	v_cvt_pk_bf16_f32 v47, v76, v77
	s_nop 1
	v_mfma_f32_32x32x16_bf16 v[0:15], v[44:47], v[40:43], v[0:15]
	v_add_u32_e32 v44, 0x2280, v74
	v_lshlrev_b32_e32 v40, 16, v36
	v_and_b32_e32 v41, 0xffff0000, v36
	v_add_u32_e32 v36, 0x2288, v74
	ds_read2_b32 v[42:43], v36 offset1:1
	ds_read2_b32 v[44:45], v44 offset1:1
	v_lshlrev_b32_e32 v36, 16, v37
	v_and_b32_e32 v37, 0xffff0000, v37
	s_waitcnt lgkmcnt(1)
	v_mov_b32_e32 v47, v42
	s_waitcnt lgkmcnt(0)
	v_mov_b32_e32 v46, v44
	v_pk_add_f32 v[40:41], v[40:41], v[46:47] neg_lo:[0,1] neg_hi:[0,1]
	v_mov_b32_e32 v42, v45
	v_pk_mul_f32 v[40:41], v[40:41], v[42:43]
	v_add_u32_e32 v44, 0x2290, v74
	v_add_u32_e32 v42, 0x2298, v74
	ds_read2_b32 v[42:43], v42 offset1:1
	ds_read2_b32 v[44:45], v44 offset1:1
	v_pk_fma_f32 v[40:41], v[60:61], v[40:41], v[62:63] op_sel_hi:[0,1,0]
	s_waitcnt lgkmcnt(1)
	v_mov_b32_e32 v47, v42
	s_waitcnt lgkmcnt(0)
	v_mov_b32_e32 v46, v44
	v_pk_add_f32 v[36:37], v[36:37], v[46:47] neg_lo:[0,1] neg_hi:[0,1]
	v_mov_b32_e32 v42, v45
	v_pk_mul_f32 v[36:37], v[36:37], v[42:43]
	v_add_u32_e32 v46, 0x22a0, v74
	v_pk_fma_f32 v[42:43], v[60:61], v[36:37], v[62:63] op_sel_hi:[0,1,0]
	v_lshlrev_b32_e32 v36, 16, v38
	v_and_b32_e32 v37, 0xffff0000, v38
	v_add_u32_e32 v38, 0x22a8, v74
	ds_read2_b32 v[44:45], v38 offset1:1
	ds_read2_b32 v[46:47], v46 offset1:1
	v_add_u32_e32 v38, 0x22b8, v74
	s_waitcnt lgkmcnt(1)
	v_mov_b32_e32 v69, v44
	s_waitcnt lgkmcnt(0)
	v_mov_b32_e32 v68, v46
	v_pk_add_f32 v[36:37], v[36:37], v[68:69] neg_lo:[0,1] neg_hi:[0,1]
	v_mov_b32_e32 v44, v47
	v_pk_mul_f32 v[36:37], v[36:37], v[44:45]
	v_add_u32_e32 v46, 0x22b0, v74
	v_pk_fma_f32 v[44:45], v[60:61], v[36:37], v[62:63] op_sel_hi:[0,1,0]
	v_lshlrev_b32_e32 v36, 16, v39
	v_and_b32_e32 v37, 0xffff0000, v39
	ds_read2_b32 v[38:39], v38 offset1:1
	ds_read2_b32 v[46:47], v46 offset1:1
	s_waitcnt lgkmcnt(1)
	v_mov_b32_e32 v69, v38
	s_waitcnt lgkmcnt(0)
	v_mov_b32_e32 v68, v46
	v_pk_add_f32 v[36:37], v[36:37], v[68:69] neg_lo:[0,1] neg_hi:[0,1]
	v_mov_b32_e32 v38, v47
	v_pk_mul_f32 v[36:37], v[36:37], v[38:39]
	v_cvt_pk_bf16_f32 v38, v44, v45
	v_pk_fma_f32 v[46:47], v[60:61], v[36:37], v[62:63] op_sel_hi:[0,1,0]
	v_cvt_pk_bf16_f32 v36, v40, v41
	v_cvt_pk_bf16_f32 v37, v42, v43
	v_cvt_pk_bf16_f32 v39, v46, v47
	s_nop 1
	v_mfma_f32_32x32x16_bf16 v[0:15], v[36:39], v[32:35], v[0:15]
	v_add_u32_e32 v120, s8, v66
	v_add_u32_e32 v122, 0xfa008000, v120
	v_mov_b32_e32 v123, 0
	v_lshlrev_b64 v[122:123], 1, v[122:123]
	v_lshl_add_u64 v[124:125], s[30:31], 0, v[122:123]
	global_load_dwordx4 v[80:83], v[124:125], off
	v_lshl_add_u64 v[124:125], s[34:35], 0, v[122:123]
	global_load_dwordx4 v[84:87], v[124:125], off
	v_add_u32_e32 v122, 0xfa00c000, v120
	v_mov_b32_e32 v123, 0
	v_lshlrev_b64 v[122:123], 1, v[122:123]
	v_lshl_add_u64 v[124:125], s[30:31], 0, v[122:123]
	global_load_dwordx4 v[88:91], v[124:125], off
	v_lshl_add_u64 v[124:125], s[34:35], 0, v[122:123]
	global_load_dwordx4 v[92:95], v[124:125], off
	v_add_u32_e32 v122, 0xfa010000, v120
	v_mov_b32_e32 v123, 0
	v_lshlrev_b64 v[122:123], 1, v[122:123]
	v_lshl_add_u64 v[124:125], s[30:31], 0, v[122:123]
	global_load_dwordx4 v[96:99], v[124:125], off
	v_lshl_add_u64 v[124:125], s[34:35], 0, v[122:123]
	global_load_dwordx4 v[100:103], v[124:125], off
	v_add_u32_e32 v122, 0xfa014000, v120
	v_mov_b32_e32 v123, 0
	v_lshlrev_b64 v[122:123], 1, v[122:123]
	v_lshl_add_u64 v[124:125], s[30:31], 0, v[122:123]
	global_load_dwordx4 v[104:107], v[124:125], off
	v_lshl_add_u64 v[124:125], s[34:35], 0, v[122:123]
	global_load_dwordx4 v[116:119], v[124:125], off
	global_load_dword v32, v[50:51], off
	global_load_dword v126, v[50:51], off offset:128
	s_waitcnt vmcnt(0)
	v_add_f32_e64 v16, v16, v32
	v_add_f32_e64 v17, v17, v32
	v_add_f32_e64 v18, v18, v32
	v_add_f32_e64 v19, v19, v32
	v_cvt_pk_bf16_f32 v16, v16, v17
	v_cvt_pk_bf16_f32 v17, v18, v19
	v_pk_add_f32 v[18:19], v[20:21], v[32:33] op_sel_hi:[1,0]
	v_pk_add_f32 v[20:21], v[22:23], v[32:33] op_sel_hi:[1,0]
	v_cvt_pk_bf16_f32 v18, v18, v19
	v_cvt_pk_bf16_f32 v19, v20, v21
	v_add_u32_e32 v22, 0x4000, v67
	ds_write2_b64 v22, v[16:17], v[18:19] offset1:2
	v_pk_add_f32 v[16:17], v[24:25], v[32:33] op_sel_hi:[1,0]
	v_pk_add_f32 v[18:19], v[26:27], v[32:33] op_sel_hi:[1,0]
	v_cvt_pk_bf16_f32 v16, v16, v17
	v_cvt_pk_bf16_f32 v17, v18, v19
	v_pk_add_f32 v[18:19], v[28:29], v[32:33] op_sel_hi:[1,0]
	v_pk_add_f32 v[20:21], v[30:31], v[32:33] op_sel_hi:[1,0]
	v_cvt_pk_bf16_f32 v18, v18, v19
	v_cvt_pk_bf16_f32 v19, v20, v21
	ds_write2_b64 v22, v[16:17], v[18:19] offset0:4 offset1:6
	v_add_u32_e32 v18, s8, v66
	v_add_u32_e32 v132, 0xfa008000, v18
	s_addk_i32 s8, 0x80
	v_lshl_add_u64 v[50:51], v[50:51], 0, s[62:63]
	s_cmpk_lg_i32 s8, 0x200
	s_waitcnt vmcnt(0)
; #define LAS __attribute__((address_space(3)))
; __device__ __forceinline__ unsigned pk2(float lo, float hi) { f32x2 v = {lo, hi}; bf16x2_t b = __builtin_convertvector(v, bf16x2_t); return __builtin_bit_cast(unsigned, b); }
; __device__ __forceinline__ float bflo(unsigned u) { return __uint_as_float(u << 16); }
; __device__ __forceinline__ float bfhi(unsigned u) { return __uint_as_float(u & 0xffff0000u); }
; template <int tbA, int tbB> ...
;     ...
; #pragma unroll
;             for (int q = 0; q < 4; ++q) {
;                 u32x2 w; w.x = pk2(acc[4 * q + 0] + sbv, acc[4 * q + 1] + sbv); w.y = pk2(acc[4 * q + 2] + sbv, acc[4 * q + 3] + sbv);
;                 *(LAS u32x2*)(stg + which * 2560 + r * 80 + (8 * q + 4 * hh) * 2) = w;
;             }
;         }
; #pragma unroll
;         for (int which = 0; which < 2; ++which) {
;             const int tb = which ? tbB : tbA;
; #pragma unroll
;             for (int i = 0; i < 2; ++i) {
;                 const int t = (lane >> 2) + 16 * i, ck = lane & 3;
;                 const size_t a = (size_t)(tok0 + tb * 32 + t) * DH + g * 128 + cb * 32 + ck * 8;
;                 const u32x4 uu = *(const u32x4*)(U + a), gc = *(const u32x4*)(GC + a);
;                 const u32x4 mv = *(const LAS u32x4*)(stg + which * 2560 + t * 80 + ck * 16);
;                 u32x4 o; o.x = pk2(bflo(uu.x) * bflo(mv.x) * bflo(gc.x), bfhi(uu.x) * bfhi(mv.x) * bfhi(gc.x)); o.y = pk2(bflo(uu.y) * bflo(mv.y) * bflo(gc.y), bfhi(uu.y) * bfhi(mv.y) * bfhi(gc.y));
;                 o.z = pk2(bflo(uu.z) * bflo(mv.z) * bflo(gc.z), bfhi(uu.z) * bfhi(mv.z) * bfhi(gc.z)); o.w = pk2(bflo(uu.w) * bflo(mv.w) * bflo(gc.w), bfhi(uu.w) * bfhi(mv.w) * bfhi(gc.w));
;                 *(u32x4*)(OC + a) = o;
	v_pk_add_f32 v[0:1], v[0:1], v[126:127] op_sel_hi:[1,0]
	v_pk_add_f32 v[2:3], v[2:3], v[126:127] op_sel_hi:[1,0]
	v_cvt_pk_bf16_f32 v0, v0, v1
	v_cvt_pk_bf16_f32 v1, v2, v3
	v_pk_add_f32 v[2:3], v[4:5], v[126:127] op_sel_hi:[1,0]
	v_pk_add_f32 v[4:5], v[6:7], v[126:127] op_sel_hi:[1,0]
	v_cvt_pk_bf16_f32 v2, v2, v3
	v_cvt_pk_bf16_f32 v3, v4, v5
	v_add_u32_e32 v6, 0x4800, v67
	ds_write2_b64 v6, v[0:1], v[2:3] offset0:64 offset1:66
	v_pk_add_f32 v[0:1], v[8:9], v[126:127] op_sel_hi:[1,0]
	v_pk_add_f32 v[2:3], v[10:11], v[126:127] op_sel_hi:[1,0]
	v_cvt_pk_bf16_f32 v0, v0, v1
	v_cvt_pk_bf16_f32 v1, v2, v3
	v_pk_add_f32 v[2:3], v[12:13], v[126:127] op_sel_hi:[1,0]
	v_pk_add_f32 v[4:5], v[14:15], v[126:127] op_sel_hi:[1,0]
	v_cvt_pk_bf16_f32 v2, v2, v3
	v_cvt_pk_bf16_f32 v3, v4, v5
	v_lshlrev_b64 v[12:13], 1, v[132:133]
	ds_write2_b64 v6, v[0:1], v[2:3] offset0:68 offset1:70
	v_mov_b32_e32 v0, v80
	v_mov_b32_e32 v1, v81
	v_mov_b32_e32 v2, v82
	v_mov_b32_e32 v3, v83
	v_mov_b32_e32 v4, v84
	v_mov_b32_e32 v5, v85
	v_mov_b32_e32 v6, v86
	v_mov_b32_e32 v7, v87
	ds_read_b128 v[8:11], v75 offset:16384
	v_add_u32_e32 v132, 0xfa00c000, v18
	s_waitcnt lgkmcnt(0)
	v_lshlrev_b32_e32 v16, 16, v8
	v_and_b32_e32 v17, 0xffff0000, v8
	v_lshlrev_b32_e32 v8, 16, v9
	v_and_b32_e32 v9, 0xffff0000, v9
	v_lshlrev_b32_e32 v14, 16, v0
	v_and_b32_e32 v15, 0xffff0000, v0
	v_pk_mul_f32 v[14:15], v[14:15], v[16:17]
	v_lshlrev_b32_e32 v16, 16, v4
	v_and_b32_e32 v17, 0xffff0000, v4
	v_pk_mul_f32 v[14:15], v[14:15], v[16:17]
	v_lshlrev_b32_e32 v4, 16, v5
	v_cvt_pk_bf16_f32 v0, v14, v15
	v_lshlrev_b32_e32 v14, 16, v1
	v_and_b32_e32 v15, 0xffff0000, v1
	v_pk_mul_f32 v[8:9], v[14:15], v[8:9]
	v_and_b32_e32 v5, 0xffff0000, v5
	v_pk_mul_f32 v[4:5], v[8:9], v[4:5]
	v_lshlrev_b32_e32 v8, 16, v10
	v_cvt_pk_bf16_f32 v1, v4, v5
	v_lshlrev_b32_e32 v4, 16, v2
	v_and_b32_e32 v5, 0xffff0000, v2
	v_and_b32_e32 v9, 0xffff0000, v10
	v_pk_mul_f32 v[4:5], v[4:5], v[8:9]
	v_lshlrev_b32_e32 v8, 16, v6
	v_and_b32_e32 v9, 0xffff0000, v6
	v_pk_mul_f32 v[4:5], v[4:5], v[8:9]
	v_lshlrev_b32_e32 v8, 16, v11
	v_cvt_pk_bf16_f32 v2, v4, v5
	v_lshlrev_b32_e32 v4, 16, v3
	v_and_b32_e32 v5, 0xffff0000, v3
	v_and_b32_e32 v9, 0xffff0000, v11
	v_pk_mul_f32 v[4:5], v[4:5], v[8:9]
	v_lshlrev_b32_e32 v6, 16, v7
	v_and_b32_e32 v7, 0xffff0000, v7
	v_pk_mul_f32 v[4:5], v[4:5], v[6:7]
	ds_read_b128 v[8:11], v75 offset:17664
	v_cvt_pk_bf16_f32 v3, v4, v5
	v_lshl_add_u64 v[4:5], s[36:37], 0, v[12:13]
	v_lshlrev_b64 v[12:13], 1, v[132:133]
	global_store_dwordx4 v[4:5], v[0:3], off
	v_mov_b32_e32 v4, v92
	v_mov_b32_e32 v5, v93
	v_mov_b32_e32 v6, v94
	v_mov_b32_e32 v7, v95
	v_mov_b32_e32 v0, v88
	v_mov_b32_e32 v1, v89
	v_mov_b32_e32 v2, v90
	v_mov_b32_e32 v3, v91
	s_waitcnt lgkmcnt(0)
	v_lshlrev_b32_e32 v16, 16, v8
	v_and_b32_e32 v17, 0xffff0000, v8
	v_lshlrev_b32_e32 v8, 16, v9
	v_and_b32_e32 v9, 0xffff0000, v9
	v_add_u32_e32 v132, 0xfa010000, v18
	v_lshlrev_b32_e32 v14, 16, v0
	v_and_b32_e32 v15, 0xffff0000, v0
	v_pk_mul_f32 v[14:15], v[14:15], v[16:17]
	v_lshlrev_b32_e32 v16, 16, v4
	v_and_b32_e32 v17, 0xffff0000, v4
	v_pk_mul_f32 v[14:15], v[14:15], v[16:17]
	v_lshlrev_b32_e32 v4, 16, v5
	v_cvt_pk_bf16_f32 v0, v14, v15
	v_lshlrev_b32_e32 v14, 16, v1
	v_and_b32_e32 v15, 0xffff0000, v1
	v_pk_mul_f32 v[8:9], v[14:15], v[8:9]
	v_and_b32_e32 v5, 0xffff0000, v5
	v_pk_mul_f32 v[4:5], v[8:9], v[4:5]
	v_lshlrev_b32_e32 v8, 16, v10
	v_cvt_pk_bf16_f32 v1, v4, v5
	v_lshlrev_b32_e32 v4, 16, v2
	v_and_b32_e32 v5, 0xffff0000, v2
	v_and_b32_e32 v9, 0xffff0000, v10
	v_pk_mul_f32 v[4:5], v[4:5], v[8:9]
	v_lshlrev_b32_e32 v8, 16, v6
	v_and_b32_e32 v9, 0xffff0000, v6
	v_pk_mul_f32 v[4:5], v[4:5], v[8:9]
	v_lshlrev_b32_e32 v8, 16, v11
	v_cvt_pk_bf16_f32 v2, v4, v5
	v_lshlrev_b32_e32 v4, 16, v3
	v_and_b32_e32 v5, 0xffff0000, v3
	v_and_b32_e32 v9, 0xffff0000, v11
	v_pk_mul_f32 v[4:5], v[4:5], v[8:9]
	v_lshlrev_b32_e32 v6, 16, v7
	v_and_b32_e32 v7, 0xffff0000, v7
	v_pk_mul_f32 v[4:5], v[4:5], v[6:7]
	ds_read_b128 v[8:11], v75 offset:18944
	v_cvt_pk_bf16_f32 v3, v4, v5
	v_lshl_add_u64 v[4:5], s[36:37], 0, v[12:13]
	v_lshlrev_b64 v[12:13], 1, v[132:133]
	global_store_dwordx4 v[4:5], v[0:3], off
	v_mov_b32_e32 v4, v100
	v_mov_b32_e32 v5, v101
	v_mov_b32_e32 v6, v102
	v_mov_b32_e32 v7, v103
	v_mov_b32_e32 v0, v96
	v_mov_b32_e32 v1, v97
	v_mov_b32_e32 v2, v98
	v_mov_b32_e32 v3, v99
	s_waitcnt lgkmcnt(0)
; #define LAS __attribute__((address_space(3)))
; __device__ __forceinline__ unsigned pk2(float lo, float hi) { f32x2 v = {lo, hi}; bf16x2_t b = __builtin_convertvector(v, bf16x2_t); return __builtin_bit_cast(unsigned, b); }
; __device__ __forceinline__ float bflo(unsigned u) { return __uint_as_float(u << 16); }
; __device__ __forceinline__ float bfhi(unsigned u) { return __uint_as_float(u & 0xffff0000u); }
; template <int tbA, int tbB> ...
;     ...
;         for (int which = 0; which < 2; ++which) {
;             const int tb = which ? tbB : tbA;
; #pragma unroll
;             for (int i = 0; i < 2; ++i) {
;                 const int t = (lane >> 2) + 16 * i, ck = lane & 3;
;                 const size_t a = (size_t)(tok0 + tb * 32 + t) * DH + g * 128 + cb * 32 + ck * 8;
;                 const u32x4 uu = *(const u32x4*)(U + a), gc = *(const u32x4*)(GC + a);
;                 const u32x4 mv = *(const LAS u32x4*)(stg + which * 2560 + t * 80 + ck * 16);
;                 u32x4 o; o.x = pk2(bflo(uu.x) * bflo(mv.x) * bflo(gc.x), bfhi(uu.x) * bfhi(mv.x) * bfhi(gc.x)); o.y = pk2(bflo(uu.y) * bflo(mv.y) * bflo(gc.y), bfhi(uu.y) * bfhi(mv.y) * bfhi(gc.y));
;                 o.z = pk2(bflo(uu.z) * bflo(mv.z) * bflo(gc.z), bfhi(uu.z) * bfhi(mv.z) * bfhi(gc.z)); o.w = pk2(bflo(uu.w) * bflo(mv.w) * bflo(gc.w), bfhi(uu.w) * bfhi(mv.w) * bfhi(gc.w));
;                 *(u32x4*)(OC + a) = o;
;             }
	v_lshlrev_b32_e32 v16, 16, v8
	v_and_b32_e32 v17, 0xffff0000, v8
	v_lshlrev_b32_e32 v8, 16, v9
	v_and_b32_e32 v9, 0xffff0000, v9
	v_add_u32_e32 v132, 0xfa014000, v18
	v_lshlrev_b32_e32 v14, 16, v0
	v_and_b32_e32 v15, 0xffff0000, v0
	v_pk_mul_f32 v[14:15], v[14:15], v[16:17]
	v_lshlrev_b32_e32 v16, 16, v4
	v_and_b32_e32 v17, 0xffff0000, v4
	v_pk_mul_f32 v[14:15], v[14:15], v[16:17]
	v_lshlrev_b32_e32 v4, 16, v5
	v_cvt_pk_bf16_f32 v0, v14, v15
	v_lshlrev_b32_e32 v14, 16, v1
	v_and_b32_e32 v15, 0xffff0000, v1
	v_pk_mul_f32 v[8:9], v[14:15], v[8:9]
	v_and_b32_e32 v5, 0xffff0000, v5
	v_pk_mul_f32 v[4:5], v[8:9], v[4:5]
	v_lshlrev_b32_e32 v8, 16, v10
	v_cvt_pk_bf16_f32 v1, v4, v5
	v_lshlrev_b32_e32 v4, 16, v2
	v_and_b32_e32 v5, 0xffff0000, v2
	v_and_b32_e32 v9, 0xffff0000, v10
	v_pk_mul_f32 v[4:5], v[4:5], v[8:9]
	v_lshlrev_b32_e32 v8, 16, v6
	v_and_b32_e32 v9, 0xffff0000, v6
	v_pk_mul_f32 v[4:5], v[4:5], v[8:9]
	v_lshlrev_b32_e32 v8, 16, v11
	v_cvt_pk_bf16_f32 v2, v4, v5
	v_lshlrev_b32_e32 v4, 16, v3
	v_and_b32_e32 v5, 0xffff0000, v3
	v_and_b32_e32 v9, 0xffff0000, v11
	v_pk_mul_f32 v[4:5], v[4:5], v[8:9]
	v_lshlrev_b32_e32 v6, 16, v7
	v_and_b32_e32 v7, 0xffff0000, v7
	v_pk_mul_f32 v[4:5], v[4:5], v[6:7]
	ds_read_b128 v[8:11], v75 offset:20224
	v_cvt_pk_bf16_f32 v3, v4, v5
	v_lshl_add_u64 v[4:5], s[36:37], 0, v[12:13]
	v_lshlrev_b64 v[12:13], 1, v[132:133]
	global_store_dwordx4 v[4:5], v[0:3], off
	v_mov_b32_e32 v4, v116
	v_mov_b32_e32 v5, v117
	v_mov_b32_e32 v6, v118
	v_mov_b32_e32 v7, v119
	v_mov_b32_e32 v0, v104
	v_mov_b32_e32 v1, v105
	v_mov_b32_e32 v2, v106
	v_mov_b32_e32 v3, v107
	s_waitcnt lgkmcnt(0)
	v_lshlrev_b32_e32 v16, 16, v8
	v_and_b32_e32 v17, 0xffff0000, v8
	v_lshlrev_b32_e32 v8, 16, v9
	v_and_b32_e32 v9, 0xffff0000, v9
	v_lshlrev_b32_e32 v14, 16, v0
	v_and_b32_e32 v15, 0xffff0000, v0
	v_pk_mul_f32 v[14:15], v[14:15], v[16:17]
	v_lshlrev_b32_e32 v16, 16, v4
	v_and_b32_e32 v17, 0xffff0000, v4
	v_pk_mul_f32 v[14:15], v[14:15], v[16:17]
	v_lshlrev_b32_e32 v4, 16, v5
	v_cvt_pk_bf16_f32 v0, v14, v15
	v_lshlrev_b32_e32 v14, 16, v1
	v_and_b32_e32 v15, 0xffff0000, v1
	v_pk_mul_f32 v[8:9], v[14:15], v[8:9]
	v_and_b32_e32 v5, 0xffff0000, v5
	v_pk_mul_f32 v[4:5], v[8:9], v[4:5]
	v_lshlrev_b32_e32 v8, 16, v10
	v_cvt_pk_bf16_f32 v1, v4, v5
	v_lshlrev_b32_e32 v4, 16, v2
	v_and_b32_e32 v5, 0xffff0000, v2
	v_and_b32_e32 v9, 0xffff0000, v10
	v_pk_mul_f32 v[4:5], v[4:5], v[8:9]
	v_lshlrev_b32_e32 v8, 16, v6
	v_and_b32_e32 v9, 0xffff0000, v6
	v_pk_mul_f32 v[4:5], v[4:5], v[8:9]
	v_lshlrev_b32_e32 v8, 16, v11
	v_cvt_pk_bf16_f32 v2, v4, v5
	v_lshlrev_b32_e32 v4, 16, v3
	v_and_b32_e32 v5, 0xffff0000, v3
	v_and_b32_e32 v9, 0xffff0000, v11
	v_pk_mul_f32 v[4:5], v[4:5], v[8:9]
	v_lshlrev_b32_e32 v6, 16, v7
	v_and_b32_e32 v7, 0xffff0000, v7
	v_pk_mul_f32 v[4:5], v[4:5], v[6:7]
	s_nop 0
	v_cvt_pk_bf16_f32 v3, v4, v5
	v_lshl_add_u64 v[4:5], s[36:37], 0, v[12:13]
	global_store_dwordx4 v[4:5], v[0:3], off
	s_cbranch_scc1 .LBB0_229
	s_mov_b64 s[8:9], 0

; __device__ __forceinline__ unsigned pk2(float lo, float hi) { f32x2 v = {lo, hi}; bf16x2_t b = __builtin_convertvector(v, bf16x2_t); return __builtin_bit_cast(unsigned, b); }
; #define MFMA32(a, b, c) __builtin_amdgcn_mfma_f32_32x32x16_bf16((a), (b), (c), 0, 0, 0)
; __device__ __forceinline__ void unpack8(const u32x4 w, float* v) { v[0] = bflo(w.x); v[1] = bfhi(w.x); v[2] = bflo(w.y); v[3] = bfhi(w.y); v[4] = bflo(w.z); v[5] = bfhi(w.z); v[6] = bflo(w.w); v[7] = bfhi(w.w); }
; template <int tbA, int tbB> ...
;     for (int gi = 0; gi < 4; ++gi) {
;         const int g = gh * 4 + gi;
;         const int ch = g * 128 + cb * 32 + r;
;         const float gg = lng[ch], bb = lnb[ch];
;         const bf16_t* ap = VCT + (size_t)ch * PT + tok0 + 8 * hh;
;         const bf16_t* wp = Wbf + (size_t)g * 16384 + 8 * hh;
;         constexpr int NSB = (tbB + 1) * 2, NSA = (tbA + 1) * 2;
;         int so = 0; asm volatile("" : "+v"(so));
;         u32x4 raw[NSB]; bf16x8 wB[NSB], wA[NSA];
; #pragma unroll
;         for (int k = 0; k < NSB; ++k) { raw[k] = *(const u32x4*)(ap + 16 * k); wB[k] = *(const bf16x8*)(wp + (size_t)(tbB * 32 + r) * 128 + 16 * k); }
; #pragma unroll
;         for (int k = 0; k < NSA; ++k) wA[k] = *(const bf16x8*)(wp + (size_t)(tbA * 32 + r) * 128 + 16 * k);
;         f32x16 accA, accB;
; #pragma unroll
;         for (int i = 0; i < 16; ++i) { accA[i] = 0.f; accB[i] = 0.f; }
; #pragma unroll
;         for (int k = 0; k < NSB; ++k) {
;             float v[8]; unpack8(raw[k], v);
; #pragma unroll
;             for (int jj = 0; jj < 8; ++jj) { const float mean = stat[(16 * k + 8 * hh + jj) * 2 + so], rstd = stat[(16 * k + 8 * hh + jj) * 2 + 1 + so]; v[jj] = (v[jj] - mean) * rstd * gg + bb; }
;             u32x4 af; af.x = pk2(v[0], v[1]); af.y = pk2(v[2], v[3]); af.z = pk2(v[4], v[5]); af.w = pk2(v[6], v[7]);
;             accB = MFMA32(__builtin_bit_cast(bf16x8, af), wB[k], accB);
;             if (k < NSA) accA = MFMA32(__builtin_bit_cast(bf16x8, af), wA[k < NSA ? k : 0], accA);
;         }
.LBB0_233:
	v_lshl_add_u64 v[8:9], v[68:69], 0, v[148:149]
	v_mov_b32_e32 v14, 0
	global_load_dword v74, v[72:73], off
	global_load_dword v76, v[70:71], off
	global_load_dwordx4 v[0:3], v[8:9], off offset:-128
	v_lshl_add_u64 v[10:11], v[64:65], 0, v[148:149]
	v_add_co_u32_e32 v12, vcc, s97, v10
	v_lshl_add_u32 v79, v14, 2, v158
	s_nop 0
	v_addc_co_u32_e32 v13, vcc, 0, v11, vcc
	v_add_co_u32_e32 v20, vcc, s93, v10
	global_load_dwordx4 v[4:7], v[12:13], off
	global_load_dwordx4 v[80:83], v[8:9], off offset:-96
	global_load_dwordx4 v[84:87], v[12:13], off offset:32
	global_load_dwordx4 v[88:91], v[8:9], off offset:-64
	global_load_dwordx4 v[92:95], v[12:13], off offset:64
	global_load_dwordx4 v[96:99], v[8:9], off offset:-32
	global_load_dwordx4 v[100:103], v[12:13], off offset:96
	global_load_dwordx4 v[60:63], v[8:9], off
	global_load_dwordx4 v[56:59], v[12:13], off offset:128
	global_load_dwordx4 v[52:55], v[8:9], off offset:32
	global_load_dwordx4 v[48:51], v[12:13], off offset:160
	global_load_dwordx4 v[44:47], v[8:9], off offset:64
	global_load_dwordx4 v[40:43], v[12:13], off offset:192
	global_load_dwordx4 v[36:39], v[8:9], off offset:96
	global_load_dwordx4 v[32:35], v[12:13], off offset:224
	v_addc_co_u32_e32 v21, vcc, 0, v11, vcc
	v_add_u32_e32 v12, 0x2000, v79
	global_load_dwordx4 v[104:107], v[20:21], off offset:32
	v_add_u32_e32 v112, 0x2080, v79
	v_lshl_add_u64 v[64:65], v[64:65], 0, s[58:59]
	v_lshl_add_u64 v[68:69], v[68:69], 0, s[60:61]
	v_lshl_add_u64 v[70:71], v[70:71], 0, s[62:63]
	v_lshl_add_u64 v[72:73], v[72:73], 0, s[62:63]
	s_waitcnt vmcnt(14)
	v_lshlrev_b32_e32 v108, 16, v80
	v_and_b32_e32 v109, 0xffff0000, v80
	v_add_u32_e32 v80, 0x2088, v79
	v_lshlrev_b32_e32 v8, 16, v0
	v_and_b32_e32 v9, 0xffff0000, v0
	v_add_u32_e32 v0, 0x2008, v79
	ds_read2_b32 v[10:11], v0 offset1:1
	ds_read2_b32 v[12:13], v12 offset1:1
	v_lshlrev_b32_e32 v0, 16, v1
	v_and_b32_e32 v1, 0xffff0000, v1
	s_waitcnt lgkmcnt(1)
	v_mov_b32_e32 v15, v10
	s_waitcnt lgkmcnt(0)
	v_mov_b32_e32 v14, v12
	v_pk_add_f32 v[8:9], v[8:9], v[14:15] neg_lo:[0,1] neg_hi:[0,1]
	v_mov_b32_e32 v10, v13
	v_pk_mul_f32 v[8:9], v[8:9], v[10:11]
	v_add_u32_e32 v12, 0x2010, v79
	v_add_u32_e32 v10, 0x2018, v79
	ds_read2_b32 v[10:11], v10 offset1:1
	ds_read2_b32 v[12:13], v12 offset1:1
	v_pk_fma_f32 v[8:9], v[74:75], v[8:9], v[76:77] op_sel_hi:[0,1,0]
	s_waitcnt lgkmcnt(1)
	v_mov_b32_e32 v15, v10
	s_waitcnt lgkmcnt(0)
	v_mov_b32_e32 v14, v12
	v_pk_add_f32 v[0:1], v[0:1], v[14:15] neg_lo:[0,1] neg_hi:[0,1]
	v_mov_b32_e32 v10, v13
	v_pk_mul_f32 v[0:1], v[0:1], v[10:11]
	v_add_u32_e32 v14, 0x2020, v79
	v_lshlrev_b32_e32 v10, 16, v2
	v_and_b32_e32 v11, 0xffff0000, v2
	v_add_u32_e32 v2, 0x2028, v79
	ds_read2_b32 v[12:13], v2 offset1:1
	ds_read2_b32 v[14:15], v14 offset1:1
	v_lshlrev_b32_e32 v2, 16, v3
	v_and_b32_e32 v3, 0xffff0000, v3
	v_pk_fma_f32 v[0:1], v[74:75], v[0:1], v[76:77] op_sel_hi:[0,1,0]
	s_waitcnt lgkmcnt(1)
	v_mov_b32_e32 v17, v12
	s_waitcnt lgkmcnt(0)
	v_mov_b32_e32 v16, v14
	v_pk_add_f32 v[10:11], v[10:11], v[16:17] neg_lo:[0,1] neg_hi:[0,1]
	v_mov_b32_e32 v12, v15
	v_pk_mul_f32 v[10:11], v[10:11], v[12:13]
	v_add_u32_e32 v14, 0x2030, v79
	v_add_u32_e32 v12, 0x2038, v79
	ds_read2_b32 v[12:13], v12 offset1:1
	ds_read2_b32 v[14:15], v14 offset1:1
	global_load_dwordx4 v[20:23], v[20:21], off
	ds_read2_b32 v[110:111], v80 offset1:1
	ds_read2_b32 v[112:113], v112 offset1:1
	v_lshlrev_b32_e32 v80, 16, v81
	v_and_b32_e32 v81, 0xffff0000, v81
	s_waitcnt lgkmcnt(2)
	v_mov_b32_e32 v16, v14
	s_waitcnt lgkmcnt(1)
	v_mov_b32_e32 v115, v110
	s_waitcnt lgkmcnt(0)
	v_mov_b32_e32 v114, v112
	v_pk_add_f32 v[108:109], v[108:109], v[114:115] neg_lo:[0,1] neg_hi:[0,1]
	v_mov_b32_e32 v110, v113
	v_pk_mul_f32 v[108:109], v[108:109], v[110:111]
	v_add_u32_e32 v112, 0x2090, v79
	v_add_u32_e32 v110, 0x2098, v79
	ds_read2_b32 v[110:111], v110 offset1:1
	ds_read2_b32 v[112:113], v112 offset1:1
	v_mov_b32_e32 v17, v12
	v_pk_add_f32 v[2:3], v[2:3], v[16:17] neg_lo:[0,1] neg_hi:[0,1]
	v_mov_b32_e32 v12, v15
	s_waitcnt lgkmcnt(1)
	v_mov_b32_e32 v115, v110
	s_waitcnt lgkmcnt(0)
	v_mov_b32_e32 v114, v112
	v_pk_add_f32 v[80:81], v[80:81], v[114:115] neg_lo:[0,1] neg_hi:[0,1]
	v_mov_b32_e32 v110, v113
	v_pk_mul_f32 v[80:81], v[80:81], v[110:111]
	v_add_u32_e32 v114, 0x20a0, v79
	v_pk_fma_f32 v[110:111], v[74:75], v[80:81], v[76:77] op_sel_hi:[0,1,0]
	v_lshlrev_b32_e32 v80, 16, v82
	v_and_b32_e32 v81, 0xffff0000, v82
	v_add_u32_e32 v82, 0x20a8, v79
	ds_read2_b32 v[112:113], v82 offset1:1
	ds_read2_b32 v[114:115], v114 offset1:1
	v_pk_mul_f32 v[2:3], v[2:3], v[12:13]
	v_add_u32_e32 v82, 0x20b8, v79
	v_pk_fma_f32 v[10:11], v[74:75], v[10:11], v[76:77] op_sel_hi:[0,1,0]
	s_waitcnt lgkmcnt(1)
	v_mov_b32_e32 v117, v112
	s_waitcnt lgkmcnt(0)
	v_mov_b32_e32 v116, v114
	v_pk_add_f32 v[80:81], v[80:81], v[116:117] neg_lo:[0,1] neg_hi:[0,1]
	v_mov_b32_e32 v112, v115
	v_pk_mul_f32 v[80:81], v[80:81], v[112:113]
	v_add_u32_e32 v114, 0x20b0, v79
	v_pk_fma_f32 v[2:3], v[74:75], v[2:3], v[76:77] op_sel_hi:[0,1,0]
	v_pk_fma_f32 v[112:113], v[74:75], v[80:81], v[76:77] op_sel_hi:[0,1,0]
	v_lshlrev_b32_e32 v80, 16, v83
	v_and_b32_e32 v81, 0xffff0000, v83
	ds_read2_b32 v[82:83], v82 offset1:1
	ds_read2_b32 v[114:115], v114 offset1:1
	v_cvt_pk_bf16_f32 v16, v8, v9
	v_cvt_pk_bf16_f32 v17, v0, v1
	v_cvt_pk_bf16_f32 v18, v10, v11
	v_cvt_pk_bf16_f32 v19, v2, v3
	s_waitcnt lgkmcnt(0)
; __device__ __forceinline__ unsigned pk2(float lo, float hi) { f32x2 v = {lo, hi}; bf16x2_t b = __builtin_convertvector(v, bf16x2_t); return __builtin_bit_cast(unsigned, b); }
; #define MFMA32(a, b, c) __builtin_amdgcn_mfma_f32_32x32x16_bf16((a), (b), (c), 0, 0, 0)
; __device__ __forceinline__ void unpack8(const u32x4 w, float* v) { v[0] = bflo(w.x); v[1] = bfhi(w.x); v[2] = bflo(w.y); v[3] = bfhi(w.y); v[4] = bflo(w.z); v[5] = bfhi(w.z); v[6] = bflo(w.w); v[7] = bfhi(w.w); }
; template <int tbA, int tbB> ...
;     ...
; #pragma unroll
;         for (int k = 0; k < NSB; ++k) {
;             float v[8]; unpack8(raw[k], v);
; #pragma unroll
;             for (int jj = 0; jj < 8; ++jj) { const float mean = stat[(16 * k + 8 * hh + jj) * 2 + so], rstd = stat[(16 * k + 8 * hh + jj) * 2 + 1 + so]; v[jj] = (v[jj] - mean) * rstd * gg + bb; }
;             u32x4 af; af.x = pk2(v[0], v[1]); af.y = pk2(v[2], v[3]); af.z = pk2(v[4], v[5]); af.w = pk2(v[6], v[7]);
;             accB = MFMA32(__builtin_bit_cast(bf16x8, af), wB[k], accB);
;             if (k < NSA) accA = MFMA32(__builtin_bit_cast(bf16x8, af), wA[k < NSA ? k : 0], accA);
;         }
	v_mov_b32_e32 v116, v114
	v_mov_b32_e32 v117, v82
	v_mfma_f32_32x32x16_bf16 v[0:15], v[16:19], v[4:7], 0
	v_add_f32_e64 v80, v80, -v116
	v_add_f32_e64 v81, v81, -v117
	v_mov_b32_e32 v82, v115
	v_mul_f32_e64 v80, v80, v82
	v_mul_f32_e64 v81, v81, v83
	v_pk_fma_f32 v[108:109], v[74:75], v[108:109], v[76:77] op_sel_hi:[0,1,0]
	v_pk_fma_f32 v[114:115], v[74:75], v[80:81], v[76:77] op_sel_hi:[0,1,0]
	v_cvt_pk_bf16_f32 v80, v108, v109
	v_cvt_pk_bf16_f32 v81, v110, v111
	v_cvt_pk_bf16_f32 v82, v112, v113
	v_cvt_pk_bf16_f32 v83, v114, v115
	s_waitcnt vmcnt(0)
	v_mfma_f32_32x32x16_bf16 v[16:31], v[16:19], v[20:23], 0
	v_mfma_f32_32x32x16_bf16 v[0:15], v[80:83], v[84:87], v[0:15]
	v_add_u32_e32 v84, 0x2100, v79
	v_mfma_f32_32x32x16_bf16 v[16:31], v[80:83], v[104:107], v[16:31]
	v_add_u32_e32 v82, 0x2108, v79
	ds_read2_b32 v[82:83], v82 offset1:1
	ds_read2_b32 v[84:85], v84 offset1:1
	v_lshlrev_b32_e32 v80, 16, v88
	v_and_b32_e32 v81, 0xffff0000, v88
	s_waitcnt lgkmcnt(1)
	v_mov_b32_e32 v87, v82
	s_waitcnt lgkmcnt(0)
	v_mov_b32_e32 v86, v84
	v_pk_add_f32 v[80:81], v[80:81], v[86:87] neg_lo:[0,1] neg_hi:[0,1]
	v_add_u32_e32 v86, 0x2110, v79
	v_add_u32_e32 v84, 0x2118, v79
	v_mov_b32_e32 v82, v85
	ds_read2_b32 v[84:85], v84 offset1:1
	ds_read2_b32 v[86:87], v86 offset1:1
	v_pk_mul_f32 v[80:81], v[80:81], v[82:83]
	v_lshlrev_b32_e32 v82, 16, v89
	v_and_b32_e32 v83, 0xffff0000, v89
	s_waitcnt lgkmcnt(1)
	v_mov_b32_e32 v89, v84
	s_waitcnt lgkmcnt(0)
	v_mov_b32_e32 v88, v86
	v_pk_add_f32 v[82:83], v[82:83], v[88:89] neg_lo:[0,1] neg_hi:[0,1]
	v_add_u32_e32 v88, 0x2120, v79
	v_add_u32_e32 v86, 0x2128, v79
	v_mov_b32_e32 v84, v87
	ds_read2_b32 v[86:87], v86 offset1:1
	ds_read2_b32 v[88:89], v88 offset1:1
	v_pk_mul_f32 v[82:83], v[82:83], v[84:85]
	v_lshlrev_b32_e32 v84, 16, v90
	v_and_b32_e32 v85, 0xffff0000, v90
	s_waitcnt lgkmcnt(1)
	v_mov_b32_e32 v105, v86
	s_waitcnt lgkmcnt(0)
	v_mov_b32_e32 v104, v88
	v_pk_add_f32 v[84:85], v[84:85], v[104:105] neg_lo:[0,1] neg_hi:[0,1]
	v_mov_b32_e32 v86, v89
	v_add_u32_e32 v90, 0x2130, v79
	v_add_u32_e32 v88, 0x2138, v79
	v_pk_mul_f32 v[84:85], v[84:85], v[86:87]
	v_lshlrev_b32_e32 v86, 16, v91
	v_and_b32_e32 v87, 0xffff0000, v91
	ds_read2_b32 v[88:89], v88 offset1:1
	ds_read2_b32 v[90:91], v90 offset1:1
	v_pk_fma_f32 v[80:81], v[74:75], v[80:81], v[76:77] op_sel_hi:[0,1,0]
	v_pk_fma_f32 v[82:83], v[74:75], v[82:83], v[76:77] op_sel_hi:[0,1,0]
	v_pk_fma_f32 v[84:85], v[74:75], v[84:85], v[76:77] op_sel_hi:[0,1,0]
	s_waitcnt lgkmcnt(1)
	v_mov_b32_e32 v105, v88
	s_waitcnt lgkmcnt(0)
	v_mov_b32_e32 v104, v90
	v_pk_add_f32 v[86:87], v[86:87], v[104:105] neg_lo:[0,1] neg_hi:[0,1]
	v_mov_b32_e32 v88, v91
	v_pk_mul_f32 v[86:87], v[86:87], v[88:89]
	v_cvt_pk_bf16_f32 v80, v80, v81
	v_pk_fma_f32 v[86:87], v[74:75], v[86:87], v[76:77] op_sel_hi:[0,1,0]
	v_cvt_pk_bf16_f32 v81, v82, v83
	v_cvt_pk_bf16_f32 v82, v84, v85
	v_cvt_pk_bf16_f32 v83, v86, v87
	v_add_u32_e32 v84, 0x2180, v79
	s_nop 0
	v_mfma_f32_32x32x16_bf16 v[0:15], v[80:83], v[92:95], v[0:15]
	v_add_u32_e32 v82, 0x2188, v79
	ds_read2_b32 v[82:83], v82 offset1:1
	ds_read2_b32 v[84:85], v84 offset1:1
	v_lshlrev_b32_e32 v80, 16, v96
	v_and_b32_e32 v81, 0xffff0000, v96
	s_waitcnt lgkmcnt(1)
	v_mov_b32_e32 v87, v82
	s_waitcnt lgkmcnt(0)
	v_mov_b32_e32 v86, v84
	v_pk_add_f32 v[80:81], v[80:81], v[86:87] neg_lo:[0,1] neg_hi:[0,1]
	v_add_u32_e32 v86, 0x2190, v79
	v_add_u32_e32 v84, 0x2198, v79
	v_mov_b32_e32 v82, v85
	ds_read2_b32 v[84:85], v84 offset1:1
	ds_read2_b32 v[86:87], v86 offset1:1
	v_pk_mul_f32 v[80:81], v[80:81], v[82:83]
	v_lshlrev_b32_e32 v82, 16, v97
	v_and_b32_e32 v83, 0xffff0000, v97
	s_waitcnt lgkmcnt(1)
	v_mov_b32_e32 v89, v84
	s_waitcnt lgkmcnt(0)
	v_mov_b32_e32 v88, v86
	v_pk_add_f32 v[82:83], v[82:83], v[88:89] neg_lo:[0,1] neg_hi:[0,1]
	v_add_u32_e32 v88, 0x21a0, v79
	v_add_u32_e32 v86, 0x21a8, v79
	v_mov_b32_e32 v84, v87
	ds_read2_b32 v[86:87], v86 offset1:1
	ds_read2_b32 v[88:89], v88 offset1:1
	v_pk_mul_f32 v[82:83], v[82:83], v[84:85]
	v_lshlrev_b32_e32 v84, 16, v98
	v_and_b32_e32 v85, 0xffff0000, v98
	s_waitcnt lgkmcnt(1)
	v_mov_b32_e32 v91, v86
	s_waitcnt lgkmcnt(0)
	v_mov_b32_e32 v90, v88
	v_pk_add_f32 v[84:85], v[84:85], v[90:91] neg_lo:[0,1] neg_hi:[0,1]
	v_add_u32_e32 v90, 0x21b0, v79
	v_add_u32_e32 v88, 0x21b8, v79
	v_mov_b32_e32 v86, v89
	ds_read2_b32 v[88:89], v88 offset1:1
	ds_read2_b32 v[90:91], v90 offset1:1
	v_pk_mul_f32 v[84:85], v[84:85], v[86:87]
	v_lshlrev_b32_e32 v86, 16, v99
	v_and_b32_e32 v87, 0xffff0000, v99
	s_waitcnt lgkmcnt(1)
	v_mov_b32_e32 v93, v88
	s_waitcnt lgkmcnt(0)
	v_mov_b32_e32 v92, v90
	v_pk_add_f32 v[86:87], v[86:87], v[92:93] neg_lo:[0,1] neg_hi:[0,1]
	v_mov_b32_e32 v88, v91
	v_pk_mul_f32 v[86:87], v[86:87], v[88:89]
	v_pk_fma_f32 v[80:81], v[74:75], v[80:81], v[76:77] op_sel_hi:[0,1,0]
	v_pk_fma_f32 v[82:83], v[74:75], v[82:83], v[76:77] op_sel_hi:[0,1,0]
	v_pk_fma_f32 v[84:85], v[74:75], v[84:85], v[76:77] op_sel_hi:[0,1,0]
	v_pk_fma_f32 v[86:87], v[74:75], v[86:87], v[76:77] op_sel_hi:[0,1,0]
	v_cvt_pk_bf16_f32 v80, v80, v81
	v_cvt_pk_bf16_f32 v81, v82, v83
	v_cvt_pk_bf16_f32 v82, v84, v85
	v_cvt_pk_bf16_f32 v83, v86, v87
	v_add_u32_e32 v84, 0x2200, v79
	s_nop 0
	v_mfma_f32_32x32x16_bf16 v[0:15], v[80:83], v[100:103], v[0:15]
	v_lshlrev_b32_e32 v80, 16, v60
	v_and_b32_e32 v81, 0xffff0000, v60
	v_add_u32_e32 v60, 0x2208, v79
	ds_read2_b32 v[82:83], v60 offset1:1
	ds_read2_b32 v[84:85], v84 offset1:1
	v_lshlrev_b32_e32 v60, 16, v61
	v_and_b32_e32 v61, 0xffff0000, v61
	s_waitcnt lgkmcnt(1)
	v_mov_b32_e32 v87, v82
	s_waitcnt lgkmcnt(0)
; __device__ __forceinline__ unsigned pk2(float lo, float hi) { f32x2 v = {lo, hi}; bf16x2_t b = __builtin_convertvector(v, bf16x2_t); return __builtin_bit_cast(unsigned, b); }
; #define MFMA32(a, b, c) __builtin_amdgcn_mfma_f32_32x32x16_bf16((a), (b), (c), 0, 0, 0)
; __device__ __forceinline__ void unpack8(const u32x4 w, float* v) { v[0] = bflo(w.x); v[1] = bfhi(w.x); v[2] = bflo(w.y); v[3] = bfhi(w.y); v[4] = bflo(w.z); v[5] = bfhi(w.z); v[6] = bflo(w.w); v[7] = bfhi(w.w); }
; template <int tbA, int tbB> ...
;     ...
; #pragma unroll
;         for (int k = 0; k < NSB; ++k) {
;             float v[8]; unpack8(raw[k], v);
; #pragma unroll
;             for (int jj = 0; jj < 8; ++jj) { const float mean = stat[(16 * k + 8 * hh + jj) * 2 + so], rstd = stat[(16 * k + 8 * hh + jj) * 2 + 1 + so]; v[jj] = (v[jj] - mean) * rstd * gg + bb; }
;             u32x4 af; af.x = pk2(v[0], v[1]); af.y = pk2(v[2], v[3]); af.z = pk2(v[4], v[5]); af.w = pk2(v[6], v[7]);
;             accB = MFMA32(__builtin_bit_cast(bf16x8, af), wB[k], accB);
;             if (k < NSA) accA = MFMA32(__builtin_bit_cast(bf16x8, af), wA[k < NSA ? k : 0], accA);
;         }
	v_mov_b32_e32 v86, v84
	v_pk_add_f32 v[80:81], v[80:81], v[86:87] neg_lo:[0,1] neg_hi:[0,1]
	v_mov_b32_e32 v82, v85
	v_pk_mul_f32 v[80:81], v[80:81], v[82:83]
	v_add_u32_e32 v84, 0x2210, v79
	v_add_u32_e32 v82, 0x2218, v79
	ds_read2_b32 v[82:83], v82 offset1:1
	ds_read2_b32 v[84:85], v84 offset1:1
	v_pk_fma_f32 v[80:81], v[74:75], v[80:81], v[76:77] op_sel_hi:[0,1,0]
	s_waitcnt lgkmcnt(1)
	v_mov_b32_e32 v87, v82
	s_waitcnt lgkmcnt(0)
	v_mov_b32_e32 v86, v84
	v_pk_add_f32 v[60:61], v[60:61], v[86:87] neg_lo:[0,1] neg_hi:[0,1]
	v_mov_b32_e32 v82, v85
	v_pk_mul_f32 v[60:61], v[60:61], v[82:83]
	v_add_u32_e32 v86, 0x2220, v79
	v_pk_fma_f32 v[82:83], v[74:75], v[60:61], v[76:77] op_sel_hi:[0,1,0]
	v_lshlrev_b32_e32 v60, 16, v62
	v_and_b32_e32 v61, 0xffff0000, v62
	v_add_u32_e32 v62, 0x2228, v79
	ds_read2_b32 v[84:85], v62 offset1:1
	ds_read2_b32 v[86:87], v86 offset1:1
	v_add_u32_e32 v62, 0x2238, v79
	s_waitcnt lgkmcnt(1)
	v_mov_b32_e32 v89, v84
	s_waitcnt lgkmcnt(0)
	v_mov_b32_e32 v88, v86
	v_pk_add_f32 v[60:61], v[60:61], v[88:89] neg_lo:[0,1] neg_hi:[0,1]
	v_mov_b32_e32 v84, v87
	v_pk_mul_f32 v[60:61], v[60:61], v[84:85]
	v_add_u32_e32 v86, 0x2230, v79
	v_pk_fma_f32 v[84:85], v[74:75], v[60:61], v[76:77] op_sel_hi:[0,1,0]
	v_lshlrev_b32_e32 v60, 16, v63
	v_and_b32_e32 v61, 0xffff0000, v63
	ds_read2_b32 v[62:63], v62 offset1:1
	ds_read2_b32 v[86:87], v86 offset1:1
	s_waitcnt lgkmcnt(1)
	v_mov_b32_e32 v89, v62
	s_waitcnt lgkmcnt(0)
	v_mov_b32_e32 v88, v86
	v_pk_add_f32 v[60:61], v[60:61], v[88:89] neg_lo:[0,1] neg_hi:[0,1]
	v_mov_b32_e32 v62, v87
	v_pk_mul_f32 v[60:61], v[60:61], v[62:63]
	v_cvt_pk_bf16_f32 v62, v84, v85
	v_pk_fma_f32 v[86:87], v[74:75], v[60:61], v[76:77] op_sel_hi:[0,1,0]
	v_cvt_pk_bf16_f32 v60, v80, v81
	v_cvt_pk_bf16_f32 v61, v82, v83
	v_cvt_pk_bf16_f32 v63, v86, v87
	s_nop 1
	v_mfma_f32_32x32x16_bf16 v[0:15], v[60:63], v[56:59], v[0:15]
	v_add_u32_e32 v60, 0x2280, v79
	v_lshlrev_b32_e32 v56, 16, v52
	v_and_b32_e32 v57, 0xffff0000, v52
	v_add_u32_e32 v52, 0x2288, v79
	ds_read2_b32 v[58:59], v52 offset1:1
	ds_read2_b32 v[60:61], v60 offset1:1
	v_lshlrev_b32_e32 v52, 16, v53
	v_and_b32_e32 v53, 0xffff0000, v53
	s_waitcnt lgkmcnt(1)
	v_mov_b32_e32 v63, v58
	s_waitcnt lgkmcnt(0)
	v_mov_b32_e32 v62, v60
	v_pk_add_f32 v[56:57], v[56:57], v[62:63] neg_lo:[0,1] neg_hi:[0,1]
	v_mov_b32_e32 v58, v61
	v_pk_mul_f32 v[56:57], v[56:57], v[58:59]
	v_add_u32_e32 v60, 0x2290, v79
	v_add_u32_e32 v58, 0x2298, v79
	ds_read2_b32 v[58:59], v58 offset1:1
	ds_read2_b32 v[60:61], v60 offset1:1
	v_pk_fma_f32 v[56:57], v[74:75], v[56:57], v[76:77] op_sel_hi:[0,1,0]
	s_waitcnt lgkmcnt(1)
	v_mov_b32_e32 v63, v58
	s_waitcnt lgkmcnt(0)
	v_mov_b32_e32 v62, v60
	v_pk_add_f32 v[52:53], v[52:53], v[62:63] neg_lo:[0,1] neg_hi:[0,1]
	v_mov_b32_e32 v58, v61
	v_pk_mul_f32 v[52:53], v[52:53], v[58:59]
	v_add_u32_e32 v62, 0x22a0, v79
	v_pk_fma_f32 v[58:59], v[74:75], v[52:53], v[76:77] op_sel_hi:[0,1,0]
	v_lshlrev_b32_e32 v52, 16, v54
	v_and_b32_e32 v53, 0xffff0000, v54
	v_add_u32_e32 v54, 0x22a8, v79
	ds_read2_b32 v[60:61], v54 offset1:1
	ds_read2_b32 v[62:63], v62 offset1:1
	v_add_u32_e32 v54, 0x22b8, v79
	s_waitcnt lgkmcnt(1)
	v_mov_b32_e32 v81, v60
	s_waitcnt lgkmcnt(0)
	v_mov_b32_e32 v80, v62
	v_pk_add_f32 v[52:53], v[52:53], v[80:81] neg_lo:[0,1] neg_hi:[0,1]
	v_mov_b32_e32 v60, v63
	v_pk_mul_f32 v[52:53], v[52:53], v[60:61]
	v_add_u32_e32 v62, 0x22b0, v79
	v_pk_fma_f32 v[60:61], v[74:75], v[52:53], v[76:77] op_sel_hi:[0,1,0]
	v_lshlrev_b32_e32 v52, 16, v55
	v_and_b32_e32 v53, 0xffff0000, v55
	ds_read2_b32 v[54:55], v54 offset1:1
	ds_read2_b32 v[62:63], v62 offset1:1
	s_waitcnt lgkmcnt(1)
	v_mov_b32_e32 v81, v54
	s_waitcnt lgkmcnt(0)
	v_mov_b32_e32 v80, v62
	v_pk_add_f32 v[52:53], v[52:53], v[80:81] neg_lo:[0,1] neg_hi:[0,1]
	v_mov_b32_e32 v54, v63
	v_pk_mul_f32 v[52:53], v[52:53], v[54:55]
	v_cvt_pk_bf16_f32 v54, v60, v61
	v_pk_fma_f32 v[62:63], v[74:75], v[52:53], v[76:77] op_sel_hi:[0,1,0]
	v_cvt_pk_bf16_f32 v52, v56, v57
	v_cvt_pk_bf16_f32 v53, v58, v59
	v_cvt_pk_bf16_f32 v55, v62, v63
	s_nop 1
	v_mfma_f32_32x32x16_bf16 v[0:15], v[52:55], v[48:51], v[0:15]
	v_add_u32_e32 v52, 0x2300, v79
	v_lshlrev_b32_e32 v48, 16, v44
	v_and_b32_e32 v49, 0xffff0000, v44
	v_add_u32_e32 v44, 0x2308, v79
	ds_read2_b32 v[50:51], v44 offset1:1
	ds_read2_b32 v[52:53], v52 offset1:1
	v_lshlrev_b32_e32 v44, 16, v45
	v_and_b32_e32 v45, 0xffff0000, v45
	s_waitcnt lgkmcnt(1)
	v_mov_b32_e32 v55, v50
	s_waitcnt lgkmcnt(0)
	v_mov_b32_e32 v54, v52
	v_pk_add_f32 v[48:49], v[48:49], v[54:55] neg_lo:[0,1] neg_hi:[0,1]
	v_mov_b32_e32 v50, v53
	v_pk_mul_f32 v[48:49], v[48:49], v[50:51]
	v_add_u32_e32 v52, 0x2310, v79
	v_add_u32_e32 v50, 0x2318, v79
	ds_read2_b32 v[50:51], v50 offset1:1
	ds_read2_b32 v[52:53], v52 offset1:1
	v_pk_fma_f32 v[48:49], v[74:75], v[48:49], v[76:77] op_sel_hi:[0,1,0]
	s_waitcnt lgkmcnt(1)
	v_mov_b32_e32 v55, v50
	s_waitcnt lgkmcnt(0)
	v_mov_b32_e32 v54, v52
	v_pk_add_f32 v[44:45], v[44:45], v[54:55] neg_lo:[0,1] neg_hi:[0,1]
	v_mov_b32_e32 v50, v53
	v_pk_mul_f32 v[44:45], v[44:45], v[50:51]
	v_add_u32_e32 v54, 0x2320, v79
	v_pk_fma_f32 v[50:51], v[74:75], v[44:45], v[76:77] op_sel_hi:[0,1,0]
	v_lshlrev_b32_e32 v44, 16, v46
	v_and_b32_e32 v45, 0xffff0000, v46
	v_add_u32_e32 v46, 0x2328, v79
	ds_read2_b32 v[52:53], v46 offset1:1
	ds_read2_b32 v[54:55], v54 offset1:1
	v_add_u32_e32 v46, 0x2338, v79
	s_waitcnt lgkmcnt(1)
	v_mov_b32_e32 v57, v52
	s_waitcnt lgkmcnt(0)
; #define LAS __attribute__((address_space(3)))
; __device__ __forceinline__ unsigned pk2(float lo, float hi) { f32x2 v = {lo, hi}; bf16x2_t b = __builtin_convertvector(v, bf16x2_t); return __builtin_bit_cast(unsigned, b); }
; #define MFMA32(a, b, c) __builtin_amdgcn_mfma_f32_32x32x16_bf16((a), (b), (c), 0, 0, 0)
; __device__ __forceinline__ void unpack8(const u32x4 w, float* v) { v[0] = bflo(w.x); v[1] = bfhi(w.x); v[2] = bflo(w.y); v[3] = bfhi(w.y); v[4] = bflo(w.z); v[5] = bfhi(w.z); v[6] = bflo(w.w); v[7] = bfhi(w.w); }
; template <int tbA, int tbB> ...
;     ...
; #pragma unroll
;         for (int k = 0; k < NSB; ++k) {
;             float v[8]; unpack8(raw[k], v);
; #pragma unroll
;             for (int jj = 0; jj < 8; ++jj) { const float mean = stat[(16 * k + 8 * hh + jj) * 2 + so], rstd = stat[(16 * k + 8 * hh + jj) * 2 + 1 + so]; v[jj] = (v[jj] - mean) * rstd * gg + bb; }
;             u32x4 af; af.x = pk2(v[0], v[1]); af.y = pk2(v[2], v[3]); af.z = pk2(v[4], v[5]); af.w = pk2(v[6], v[7]);
;             accB = MFMA32(__builtin_bit_cast(bf16x8, af), wB[k], accB);
;             if (k < NSA) accA = MFMA32(__builtin_bit_cast(bf16x8, af), wA[k < NSA ? k : 0], accA);
;         }
; #pragma unroll
;         for (int which = 0; which < 2; ++which) {
;             const int tb = which ? tbB : tbA; const f32x16& acc = which ? accB : accA;
;             const float sbv = spb[g * 128 + tb * 32 + r];
; #pragma unroll
;             for (int q = 0; q < 4; ++q) {
;                 u32x2 w; w.x = pk2(acc[4 * q + 0] + sbv, acc[4 * q + 1] + sbv); w.y = pk2(acc[4 * q + 2] + sbv, acc[4 * q + 3] + sbv);
;                 *(LAS u32x2*)(stg + which * 2560 + r * 80 + (8 * q + 4 * hh) * 2) = w;
;             }
	v_mov_b32_e32 v56, v54
	v_pk_add_f32 v[44:45], v[44:45], v[56:57] neg_lo:[0,1] neg_hi:[0,1]
	v_mov_b32_e32 v52, v55
	v_pk_mul_f32 v[44:45], v[44:45], v[52:53]
	v_add_u32_e32 v54, 0x2330, v79
	v_pk_fma_f32 v[52:53], v[74:75], v[44:45], v[76:77] op_sel_hi:[0,1,0]
	v_lshlrev_b32_e32 v44, 16, v47
	v_and_b32_e32 v45, 0xffff0000, v47
	ds_read2_b32 v[46:47], v46 offset1:1
	ds_read2_b32 v[54:55], v54 offset1:1
	s_waitcnt lgkmcnt(1)
	v_mov_b32_e32 v57, v46
	s_waitcnt lgkmcnt(0)
	v_mov_b32_e32 v56, v54
	v_pk_add_f32 v[44:45], v[44:45], v[56:57] neg_lo:[0,1] neg_hi:[0,1]
	v_mov_b32_e32 v46, v55
	v_pk_mul_f32 v[44:45], v[44:45], v[46:47]
	v_cvt_pk_bf16_f32 v46, v52, v53
	v_pk_fma_f32 v[54:55], v[74:75], v[44:45], v[76:77] op_sel_hi:[0,1,0]
	v_cvt_pk_bf16_f32 v44, v48, v49
	v_cvt_pk_bf16_f32 v45, v50, v51
	v_cvt_pk_bf16_f32 v47, v54, v55
	s_nop 1
	v_mfma_f32_32x32x16_bf16 v[0:15], v[44:47], v[40:43], v[0:15]
	v_add_u32_e32 v44, 0x2380, v79
	v_lshlrev_b32_e32 v40, 16, v36
	v_and_b32_e32 v41, 0xffff0000, v36
	v_add_u32_e32 v36, 0x2388, v79
	ds_read2_b32 v[42:43], v36 offset1:1
	ds_read2_b32 v[44:45], v44 offset1:1
	v_lshlrev_b32_e32 v36, 16, v37
	v_and_b32_e32 v37, 0xffff0000, v37
	s_waitcnt lgkmcnt(1)
	v_mov_b32_e32 v47, v42
	s_waitcnt lgkmcnt(0)
	v_mov_b32_e32 v46, v44
	v_pk_add_f32 v[40:41], v[40:41], v[46:47] neg_lo:[0,1] neg_hi:[0,1]
	v_mov_b32_e32 v42, v45
	v_pk_mul_f32 v[40:41], v[40:41], v[42:43]
	v_add_u32_e32 v44, 0x2390, v79
	v_add_u32_e32 v42, 0x2398, v79
	ds_read2_b32 v[42:43], v42 offset1:1
	ds_read2_b32 v[44:45], v44 offset1:1
	v_pk_fma_f32 v[40:41], v[74:75], v[40:41], v[76:77] op_sel_hi:[0,1,0]
	s_waitcnt lgkmcnt(1)
	v_mov_b32_e32 v47, v42
	s_waitcnt lgkmcnt(0)
	v_mov_b32_e32 v46, v44
	v_pk_add_f32 v[36:37], v[36:37], v[46:47] neg_lo:[0,1] neg_hi:[0,1]
	v_mov_b32_e32 v42, v45
	v_pk_mul_f32 v[36:37], v[36:37], v[42:43]
	v_add_u32_e32 v46, 0x23a0, v79
	v_pk_fma_f32 v[42:43], v[74:75], v[36:37], v[76:77] op_sel_hi:[0,1,0]
	v_lshlrev_b32_e32 v36, 16, v38
	v_and_b32_e32 v37, 0xffff0000, v38
	v_add_u32_e32 v38, 0x23a8, v79
	ds_read2_b32 v[44:45], v38 offset1:1
	ds_read2_b32 v[46:47], v46 offset1:1
	v_add_u32_e32 v38, 0x23b8, v79
	s_waitcnt lgkmcnt(1)
	v_mov_b32_e32 v49, v44
	s_waitcnt lgkmcnt(0)
	v_mov_b32_e32 v48, v46
	v_pk_add_f32 v[36:37], v[36:37], v[48:49] neg_lo:[0,1] neg_hi:[0,1]
	v_mov_b32_e32 v44, v47
	v_pk_mul_f32 v[36:37], v[36:37], v[44:45]
	v_add_u32_e32 v46, 0x23b0, v79
	v_pk_fma_f32 v[44:45], v[74:75], v[36:37], v[76:77] op_sel_hi:[0,1,0]
	v_lshlrev_b32_e32 v36, 16, v39
	v_and_b32_e32 v37, 0xffff0000, v39
	ds_read2_b32 v[38:39], v38 offset1:1
	ds_read2_b32 v[46:47], v46 offset1:1
	s_waitcnt lgkmcnt(1)
	v_mov_b32_e32 v49, v38
	s_waitcnt lgkmcnt(0)
	v_mov_b32_e32 v48, v46
	v_pk_add_f32 v[36:37], v[36:37], v[48:49] neg_lo:[0,1] neg_hi:[0,1]
	v_mov_b32_e32 v38, v47
	v_pk_mul_f32 v[36:37], v[36:37], v[38:39]
	v_cvt_pk_bf16_f32 v38, v44, v45
	v_pk_fma_f32 v[46:47], v[74:75], v[36:37], v[76:77] op_sel_hi:[0,1,0]
	v_cvt_pk_bf16_f32 v36, v40, v41
	v_cvt_pk_bf16_f32 v37, v42, v43
	v_cvt_pk_bf16_f32 v39, v46, v47
	s_nop 1
	v_mfma_f32_32x32x16_bf16 v[0:15], v[36:39], v[32:35], v[0:15]
	v_add_u32_e32 v120, s8, v77
	v_add_u32_e32 v122, 0xfa000000, v120
	v_mov_b32_e32 v123, 0
	v_lshlrev_b64 v[122:123], 1, v[122:123]
	v_lshl_add_u64 v[124:125], s[30:31], 0, v[122:123]
	global_load_dwordx4 v[80:83], v[124:125], off
	v_lshl_add_u64 v[124:125], s[34:35], 0, v[122:123]
	global_load_dwordx4 v[84:87], v[124:125], off
	v_add_u32_e32 v122, 0xfa004000, v120
	v_mov_b32_e32 v123, 0
	v_lshlrev_b64 v[122:123], 1, v[122:123]
	v_lshl_add_u64 v[124:125], s[30:31], 0, v[122:123]
	global_load_dwordx4 v[88:91], v[124:125], off
	v_lshl_add_u64 v[124:125], s[34:35], 0, v[122:123]
	global_load_dwordx4 v[92:95], v[124:125], off
	v_add_u32_e32 v122, 0xfa018000, v120
	v_mov_b32_e32 v123, 0
	v_lshlrev_b64 v[122:123], 1, v[122:123]
	v_lshl_add_u64 v[124:125], s[30:31], 0, v[122:123]
	global_load_dwordx4 v[96:99], v[124:125], off
	v_lshl_add_u64 v[124:125], s[34:35], 0, v[122:123]
	global_load_dwordx4 v[100:103], v[124:125], off
	v_add_u32_e32 v122, 0xfa01c000, v120
	v_mov_b32_e32 v123, 0
	v_lshlrev_b64 v[122:123], 1, v[122:123]
	v_lshl_add_u64 v[124:125], s[30:31], 0, v[122:123]
	global_load_dwordx4 v[104:107], v[124:125], off
	v_lshl_add_u64 v[124:125], s[34:35], 0, v[122:123]
	global_load_dwordx4 v[116:119], v[124:125], off
	global_load_dword v32, v[66:67], off offset:-384
	global_load_dword v126, v[66:67], off
	s_waitcnt vmcnt(0)
	v_add_f32_e64 v16, v16, v32
	v_add_f32_e64 v17, v17, v32
	v_add_f32_e64 v18, v18, v32
	v_add_f32_e64 v19, v19, v32
	v_cvt_pk_bf16_f32 v16, v16, v17
	v_cvt_pk_bf16_f32 v17, v18, v19
	v_pk_add_f32 v[18:19], v[20:21], v[32:33] op_sel_hi:[1,0]
	v_pk_add_f32 v[20:21], v[22:23], v[32:33] op_sel_hi:[1,0]
	v_cvt_pk_bf16_f32 v18, v18, v19
	v_cvt_pk_bf16_f32 v19, v20, v21
	v_add_u32_e32 v22, 0x4000, v78
	ds_write2_b64 v22, v[16:17], v[18:19] offset1:2
	v_pk_add_f32 v[16:17], v[24:25], v[32:33] op_sel_hi:[1,0]
	v_pk_add_f32 v[18:19], v[26:27], v[32:33] op_sel_hi:[1,0]
	v_cvt_pk_bf16_f32 v16, v16, v17
	v_cvt_pk_bf16_f32 v17, v18, v19
	v_pk_add_f32 v[18:19], v[28:29], v[32:33] op_sel_hi:[1,0]
	v_pk_add_f32 v[20:21], v[30:31], v[32:33] op_sel_hi:[1,0]
	v_cvt_pk_bf16_f32 v18, v18, v19
	v_cvt_pk_bf16_f32 v19, v20, v21
	ds_write2_b64 v22, v[16:17], v[18:19] offset0:4 offset1:6
	v_add_u32_e32 v18, s8, v77
	v_add_u32_e32 v132, 0xfa000000, v18
	s_addk_i32 s8, 0x80
	v_lshl_add_u64 v[66:67], v[66:67], 0, s[62:63]
	s_cmpk_eq_i32 s8, 0x200
	s_waitcnt vmcnt(0)
; #define LAS __attribute__((address_space(3)))
; __device__ __forceinline__ unsigned pk2(float lo, float hi) { f32x2 v = {lo, hi}; bf16x2_t b = __builtin_convertvector(v, bf16x2_t); return __builtin_bit_cast(unsigned, b); }
; __device__ __forceinline__ float bflo(unsigned u) { return __uint_as_float(u << 16); }
; __device__ __forceinline__ float bfhi(unsigned u) { return __uint_as_float(u & 0xffff0000u); }
; template <int tbA, int tbB> ...
;     ...
; #pragma unroll
;             for (int q = 0; q < 4; ++q) {
;                 u32x2 w; w.x = pk2(acc[4 * q + 0] + sbv, acc[4 * q + 1] + sbv); w.y = pk2(acc[4 * q + 2] + sbv, acc[4 * q + 3] + sbv);
;                 *(LAS u32x2*)(stg + which * 2560 + r * 80 + (8 * q + 4 * hh) * 2) = w;
;             }
;         }
; #pragma unroll
;         for (int which = 0; which < 2; ++which) {
;             const int tb = which ? tbB : tbA;
; #pragma unroll
;             for (int i = 0; i < 2; ++i) {
;                 const int t = (lane >> 2) + 16 * i, ck = lane & 3;
;                 const size_t a = (size_t)(tok0 + tb * 32 + t) * DH + g * 128 + cb * 32 + ck * 8;
;                 const u32x4 uu = *(const u32x4*)(U + a), gc = *(const u32x4*)(GC + a);
;                 const u32x4 mv = *(const LAS u32x4*)(stg + which * 2560 + t * 80 + ck * 16);
;                 u32x4 o; o.x = pk2(bflo(uu.x) * bflo(mv.x) * bflo(gc.x), bfhi(uu.x) * bfhi(mv.x) * bfhi(gc.x)); o.y = pk2(bflo(uu.y) * bflo(mv.y) * bflo(gc.y), bfhi(uu.y) * bfhi(mv.y) * bfhi(gc.y));
;                 o.z = pk2(bflo(uu.z) * bflo(mv.z) * bflo(gc.z), bfhi(uu.z) * bfhi(mv.z) * bfhi(gc.z)); o.w = pk2(bflo(uu.w) * bflo(mv.w) * bflo(gc.w), bfhi(uu.w) * bfhi(mv.w) * bfhi(gc.w));
;                 *(u32x4*)(OC + a) = o;
	v_pk_add_f32 v[0:1], v[0:1], v[126:127] op_sel_hi:[1,0]
	v_pk_add_f32 v[2:3], v[2:3], v[126:127] op_sel_hi:[1,0]
	v_cvt_pk_bf16_f32 v0, v0, v1
	v_cvt_pk_bf16_f32 v1, v2, v3
	v_pk_add_f32 v[2:3], v[4:5], v[126:127] op_sel_hi:[1,0]
	v_pk_add_f32 v[4:5], v[6:7], v[126:127] op_sel_hi:[1,0]
	v_cvt_pk_bf16_f32 v2, v2, v3
	v_cvt_pk_bf16_f32 v3, v4, v5
	v_add_u32_e32 v6, 0x4800, v78
	ds_write2_b64 v6, v[0:1], v[2:3] offset0:64 offset1:66
	v_pk_add_f32 v[0:1], v[8:9], v[126:127] op_sel_hi:[1,0]
	v_pk_add_f32 v[2:3], v[10:11], v[126:127] op_sel_hi:[1,0]
	v_cvt_pk_bf16_f32 v0, v0, v1
	v_cvt_pk_bf16_f32 v1, v2, v3
	v_pk_add_f32 v[2:3], v[12:13], v[126:127] op_sel_hi:[1,0]
	v_pk_add_f32 v[4:5], v[14:15], v[126:127] op_sel_hi:[1,0]
	v_cvt_pk_bf16_f32 v2, v2, v3
	v_cvt_pk_bf16_f32 v3, v4, v5
	v_lshlrev_b64 v[12:13], 1, v[132:133]
	ds_write2_b64 v6, v[0:1], v[2:3] offset0:68 offset1:70
	v_mov_b32_e32 v0, v80
	v_mov_b32_e32 v1, v81
	v_mov_b32_e32 v2, v82
	v_mov_b32_e32 v3, v83
	v_mov_b32_e32 v4, v84
	v_mov_b32_e32 v5, v85
	v_mov_b32_e32 v6, v86
	v_mov_b32_e32 v7, v87
	ds_read_b128 v[8:11], v75 offset:16384
	v_add_u32_e32 v132, 0xfa004000, v18
	s_waitcnt lgkmcnt(0)
	v_lshlrev_b32_e32 v16, 16, v8
	v_and_b32_e32 v17, 0xffff0000, v8
	v_lshlrev_b32_e32 v8, 16, v9
	v_and_b32_e32 v9, 0xffff0000, v9
	v_lshlrev_b32_e32 v14, 16, v0
	v_and_b32_e32 v15, 0xffff0000, v0
	v_pk_mul_f32 v[14:15], v[14:15], v[16:17]
	v_lshlrev_b32_e32 v16, 16, v4
	v_and_b32_e32 v17, 0xffff0000, v4
	v_pk_mul_f32 v[14:15], v[14:15], v[16:17]
	v_lshlrev_b32_e32 v4, 16, v5
	v_cvt_pk_bf16_f32 v0, v14, v15
	v_lshlrev_b32_e32 v14, 16, v1
	v_and_b32_e32 v15, 0xffff0000, v1
	v_pk_mul_f32 v[8:9], v[14:15], v[8:9]
	v_and_b32_e32 v5, 0xffff0000, v5
	v_pk_mul_f32 v[4:5], v[8:9], v[4:5]
	v_lshlrev_b32_e32 v8, 16, v10
	v_cvt_pk_bf16_f32 v1, v4, v5
	v_lshlrev_b32_e32 v4, 16, v2
	v_and_b32_e32 v5, 0xffff0000, v2
	v_and_b32_e32 v9, 0xffff0000, v10
	v_pk_mul_f32 v[4:5], v[4:5], v[8:9]
	v_lshlrev_b32_e32 v8, 16, v6
	v_and_b32_e32 v9, 0xffff0000, v6
	v_pk_mul_f32 v[4:5], v[4:5], v[8:9]
	v_lshlrev_b32_e32 v8, 16, v11
	v_cvt_pk_bf16_f32 v2, v4, v5
	v_lshlrev_b32_e32 v4, 16, v3
	v_and_b32_e32 v5, 0xffff0000, v3
	v_and_b32_e32 v9, 0xffff0000, v11
	v_pk_mul_f32 v[4:5], v[4:5], v[8:9]
	v_lshlrev_b32_e32 v6, 16, v7
	v_and_b32_e32 v7, 0xffff0000, v7
	v_pk_mul_f32 v[4:5], v[4:5], v[6:7]
	ds_read_b128 v[8:11], v75 offset:17664
	v_cvt_pk_bf16_f32 v3, v4, v5
	v_lshl_add_u64 v[4:5], s[36:37], 0, v[12:13]
	v_lshlrev_b64 v[12:13], 1, v[132:133]
	global_store_dwordx4 v[4:5], v[0:3], off
	v_mov_b32_e32 v4, v92
	v_mov_b32_e32 v5, v93
	v_mov_b32_e32 v6, v94
	v_mov_b32_e32 v7, v95
	v_mov_b32_e32 v0, v88
	v_mov_b32_e32 v1, v89
	v_mov_b32_e32 v2, v90
	v_mov_b32_e32 v3, v91
	s_waitcnt lgkmcnt(0)
	v_lshlrev_b32_e32 v16, 16, v8
	v_and_b32_e32 v17, 0xffff0000, v8
	v_lshlrev_b32_e32 v8, 16, v9
	v_and_b32_e32 v9, 0xffff0000, v9
	v_add_u32_e32 v132, 0xfa018000, v18
	v_lshlrev_b32_e32 v14, 16, v0
	v_and_b32_e32 v15, 0xffff0000, v0
	v_pk_mul_f32 v[14:15], v[14:15], v[16:17]
	v_lshlrev_b32_e32 v16, 16, v4
	v_and_b32_e32 v17, 0xffff0000, v4
	v_pk_mul_f32 v[14:15], v[14:15], v[16:17]
	v_lshlrev_b32_e32 v4, 16, v5
	v_cvt_pk_bf16_f32 v0, v14, v15
	v_lshlrev_b32_e32 v14, 16, v1
	v_and_b32_e32 v15, 0xffff0000, v1
	v_pk_mul_f32 v[8:9], v[14:15], v[8:9]
	v_and_b32_e32 v5, 0xffff0000, v5
	v_pk_mul_f32 v[4:5], v[8:9], v[4:5]
	v_lshlrev_b32_e32 v8, 16, v10
	v_cvt_pk_bf16_f32 v1, v4, v5
	v_lshlrev_b32_e32 v4, 16, v2
	v_and_b32_e32 v5, 0xffff0000, v2
	v_and_b32_e32 v9, 0xffff0000, v10
	v_pk_mul_f32 v[4:5], v[4:5], v[8:9]
	v_lshlrev_b32_e32 v8, 16, v6
	v_and_b32_e32 v9, 0xffff0000, v6
	v_pk_mul_f32 v[4:5], v[4:5], v[8:9]
	v_lshlrev_b32_e32 v8, 16, v11
	v_cvt_pk_bf16_f32 v2, v4, v5
	v_lshlrev_b32_e32 v4, 16, v3
	v_and_b32_e32 v5, 0xffff0000, v3
	v_and_b32_e32 v9, 0xffff0000, v11
	v_pk_mul_f32 v[4:5], v[4:5], v[8:9]
	v_lshlrev_b32_e32 v6, 16, v7
	v_and_b32_e32 v7, 0xffff0000, v7
	v_pk_mul_f32 v[4:5], v[4:5], v[6:7]
	ds_read_b128 v[8:11], v75 offset:18944
	v_cvt_pk_bf16_f32 v3, v4, v5
	v_lshl_add_u64 v[4:5], s[36:37], 0, v[12:13]
	v_lshlrev_b64 v[12:13], 1, v[132:133]
	global_store_dwordx4 v[4:5], v[0:3], off
	v_mov_b32_e32 v4, v100
	v_mov_b32_e32 v5, v101
	v_mov_b32_e32 v6, v102
	v_mov_b32_e32 v7, v103
	v_mov_b32_e32 v0, v96
	v_mov_b32_e32 v1, v97
	v_mov_b32_e32 v2, v98
	v_mov_b32_e32 v3, v99
	s_waitcnt lgkmcnt(0)
; #define LAS __attribute__((address_space(3)))
; __device__ __forceinline__ unsigned pk2(float lo, float hi) { f32x2 v = {lo, hi}; bf16x2_t b = __builtin_convertvector(v, bf16x2_t); return __builtin_bit_cast(unsigned, b); }
; __device__ __forceinline__ float bflo(unsigned u) { return __uint_as_float(u << 16); }
; __device__ __forceinline__ float bfhi(unsigned u) { return __uint_as_float(u & 0xffff0000u); }
; template <int tbA, int tbB> ...
;     ...
;         for (int which = 0; which < 2; ++which) {
;             const int tb = which ? tbB : tbA;
; #pragma unroll
;             for (int i = 0; i < 2; ++i) {
;                 const int t = (lane >> 2) + 16 * i, ck = lane & 3;
;                 const size_t a = (size_t)(tok0 + tb * 32 + t) * DH + g * 128 + cb * 32 + ck * 8;
;                 const u32x4 uu = *(const u32x4*)(U + a), gc = *(const u32x4*)(GC + a);
;                 const u32x4 mv = *(const LAS u32x4*)(stg + which * 2560 + t * 80 + ck * 16);
;                 u32x4 o; o.x = pk2(bflo(uu.x) * bflo(mv.x) * bflo(gc.x), bfhi(uu.x) * bfhi(mv.x) * bfhi(gc.x)); o.y = pk2(bflo(uu.y) * bflo(mv.y) * bflo(gc.y), bfhi(uu.y) * bfhi(mv.y) * bfhi(gc.y));
;                 o.z = pk2(bflo(uu.z) * bflo(mv.z) * bflo(gc.z), bfhi(uu.z) * bfhi(mv.z) * bfhi(gc.z)); o.w = pk2(bflo(uu.w) * bflo(mv.w) * bflo(gc.w), bfhi(uu.w) * bfhi(mv.w) * bfhi(gc.w));
;                 *(u32x4*)(OC + a) = o;
;             }
	v_lshlrev_b32_e32 v16, 16, v8
	v_and_b32_e32 v17, 0xffff0000, v8
	v_lshlrev_b32_e32 v8, 16, v9
	v_and_b32_e32 v9, 0xffff0000, v9
	v_add_u32_e32 v132, 0xfa01c000, v18
	v_lshlrev_b32_e32 v14, 16, v0
	v_and_b32_e32 v15, 0xffff0000, v0
	v_pk_mul_f32 v[14:15], v[14:15], v[16:17]
	v_lshlrev_b32_e32 v16, 16, v4
	v_and_b32_e32 v17, 0xffff0000, v4
	v_pk_mul_f32 v[14:15], v[14:15], v[16:17]
	v_lshlrev_b32_e32 v4, 16, v5
	v_cvt_pk_bf16_f32 v0, v14, v15
	v_lshlrev_b32_e32 v14, 16, v1
	v_and_b32_e32 v15, 0xffff0000, v1
	v_pk_mul_f32 v[8:9], v[14:15], v[8:9]
	v_and_b32_e32 v5, 0xffff0000, v5
	v_pk_mul_f32 v[4:5], v[8:9], v[4:5]
	v_lshlrev_b32_e32 v8, 16, v10
	v_cvt_pk_bf16_f32 v1, v4, v5
	v_lshlrev_b32_e32 v4, 16, v2
	v_and_b32_e32 v5, 0xffff0000, v2
	v_and_b32_e32 v9, 0xffff0000, v10
	v_pk_mul_f32 v[4:5], v[4:5], v[8:9]
	v_lshlrev_b32_e32 v8, 16, v6
	v_and_b32_e32 v9, 0xffff0000, v6
	v_pk_mul_f32 v[4:5], v[4:5], v[8:9]
	v_lshlrev_b32_e32 v8, 16, v11
	v_cvt_pk_bf16_f32 v2, v4, v5
	v_lshlrev_b32_e32 v4, 16, v3
	v_and_b32_e32 v5, 0xffff0000, v3
	v_and_b32_e32 v9, 0xffff0000, v11
	v_pk_mul_f32 v[4:5], v[4:5], v[8:9]
	v_lshlrev_b32_e32 v6, 16, v7
	v_and_b32_e32 v7, 0xffff0000, v7
	v_pk_mul_f32 v[4:5], v[4:5], v[6:7]
	ds_read_b128 v[8:11], v75 offset:20224
	v_cvt_pk_bf16_f32 v3, v4, v5
	v_lshl_add_u64 v[4:5], s[36:37], 0, v[12:13]
	v_lshlrev_b64 v[12:13], 1, v[132:133]
	global_store_dwordx4 v[4:5], v[0:3], off
	v_mov_b32_e32 v4, v116
	v_mov_b32_e32 v5, v117
	v_mov_b32_e32 v6, v118
	v_mov_b32_e32 v7, v119
	v_mov_b32_e32 v0, v104
	v_mov_b32_e32 v1, v105
	v_mov_b32_e32 v2, v106
	v_mov_b32_e32 v3, v107
	s_waitcnt lgkmcnt(0)
	v_lshlrev_b32_e32 v16, 16, v8
	v_and_b32_e32 v17, 0xffff0000, v8
	v_lshlrev_b32_e32 v8, 16, v9
	v_and_b32_e32 v9, 0xffff0000, v9
	v_lshlrev_b32_e32 v14, 16, v0
	v_and_b32_e32 v15, 0xffff0000, v0
	v_pk_mul_f32 v[14:15], v[14:15], v[16:17]
	v_lshlrev_b32_e32 v16, 16, v4
	v_and_b32_e32 v17, 0xffff0000, v4
	v_pk_mul_f32 v[14:15], v[14:15], v[16:17]
	v_lshlrev_b32_e32 v4, 16, v5
	v_cvt_pk_bf16_f32 v0, v14, v15
	v_lshlrev_b32_e32 v14, 16, v1
	v_and_b32_e32 v15, 0xffff0000, v1
	v_pk_mul_f32 v[8:9], v[14:15], v[8:9]
	v_and_b32_e32 v5, 0xffff0000, v5
	v_pk_mul_f32 v[4:5], v[8:9], v[4:5]
	v_lshlrev_b32_e32 v8, 16, v10
	v_cvt_pk_bf16_f32 v1, v4, v5
	v_lshlrev_b32_e32 v4, 16, v2
	v_and_b32_e32 v5, 0xffff0000, v2
	v_and_b32_e32 v9, 0xffff0000, v10
	v_pk_mul_f32 v[4:5], v[4:5], v[8:9]
	v_lshlrev_b32_e32 v8, 16, v6
	v_and_b32_e32 v9, 0xffff0000, v6
	v_pk_mul_f32 v[4:5], v[4:5], v[8:9]
	v_lshlrev_b32_e32 v8, 16, v11
	v_cvt_pk_bf16_f32 v2, v4, v5
	v_lshlrev_b32_e32 v4, 16, v3
	v_and_b32_e32 v5, 0xffff0000, v3
	v_and_b32_e32 v9, 0xffff0000, v11
	v_pk_mul_f32 v[4:5], v[4:5], v[8:9]
	v_lshlrev_b32_e32 v6, 16, v7
	v_and_b32_e32 v7, 0xffff0000, v7
	v_pk_mul_f32 v[4:5], v[4:5], v[6:7]
	s_nop 0
	v_cvt_pk_bf16_f32 v3, v4, v5
	v_lshl_add_u64 v[4:5], s[36:37], 0, v[12:13]
	global_store_dwordx4 v[4:5], v[0:3], off
	s_cbranch_scc0 .LBB0_233

; __device__ __forceinline__ unsigned pk2(float lo, float hi) { f32x2 v = {lo, hi}; bf16x2_t b = __builtin_convertvector(v, bf16x2_t); return __builtin_bit_cast(unsigned, b); }
; #define MFMA32(a, b, c) __builtin_amdgcn_mfma_f32_32x32x16_bf16((a), (b), (c), 0, 0, 0)
; __device__ __forceinline__ void unpack8(const u32x4 w, float* v) { v[0] = bflo(w.x); v[1] = bfhi(w.x); v[2] = bflo(w.y); v[3] = bfhi(w.y); v[4] = bflo(w.z); v[5] = bfhi(w.z); v[6] = bflo(w.w); v[7] = bfhi(w.w); }
; template <int tbA, int tbB> ...
;     for (int gi = 0; gi < 4; ++gi) {
;         const int g = gh * 4 + gi;
;         const int ch = g * 128 + cb * 32 + r;
;         const float gg = lng[ch], bb = lnb[ch];
;         const bf16_t* ap = VCT + (size_t)ch * PT + tok0 + 8 * hh;
;         const bf16_t* wp = Wbf + (size_t)g * 16384 + 8 * hh;
;         constexpr int NSB = (tbB + 1) * 2, NSA = (tbA + 1) * 2;
;         int so = 0; asm volatile("" : "+v"(so));
;         u32x4 raw[NSB]; bf16x8 wB[NSB], wA[NSA];
; #pragma unroll
;         for (int k = 0; k < NSB; ++k) { raw[k] = *(const u32x4*)(ap + 16 * k); wB[k] = *(const bf16x8*)(wp + (size_t)(tbB * 32 + r) * 128 + 16 * k); }
; #pragma unroll
;         for (int k = 0; k < NSA; ++k) wA[k] = *(const bf16x8*)(wp + (size_t)(tbA * 32 + r) * 128 + 16 * k);
;         f32x16 accA, accB;
; #pragma unroll
;         for (int i = 0; i < 16; ++i) { accA[i] = 0.f; accB[i] = 0.f; }
; #pragma unroll
;         for (int k = 0; k < NSB; ++k) {
;             float v[8]; unpack8(raw[k], v);
; #pragma unroll
;             for (int jj = 0; jj < 8; ++jj) { const float mean = stat[(16 * k + 8 * hh + jj) * 2 + so], rstd = stat[(16 * k + 8 * hh + jj) * 2 + 1 + so]; v[jj] = (v[jj] - mean) * rstd * gg + bb; }
;             u32x4 af; af.x = pk2(v[0], v[1]); af.y = pk2(v[2], v[3]); af.z = pk2(v[4], v[5]); af.w = pk2(v[6], v[7]);
;             accB = MFMA32(__builtin_bit_cast(bf16x8, af), wB[k], accB);
;             if (k < NSA) accA = MFMA32(__builtin_bit_cast(bf16x8, af), wA[k < NSA ? k : 0], accA);
;         }
.LBB0_653:
	v_lshl_add_u64 v[8:9], v[52:53], 0, v[148:149]
	v_mov_b32_e32 v14, v133
	global_load_dword v60, v[56:57], off
	global_load_dword v62, v[54:55], off
	global_load_dwordx4 v[0:3], v[8:9], off offset:-96
	v_lshl_add_u64 v[10:11], v[58:59], 0, v[148:149]
	v_add_co_u32_e32 v12, vcc, s96, v10
	v_lshl_add_u32 v74, v14, 2, v158
	s_nop 0
	v_addc_co_u32_e32 v13, vcc, 0, v11, vcc
	v_add_co_u32_e32 v20, vcc, s97, v10
	global_load_dwordx4 v[4:7], v[12:13], off
	global_load_dwordx4 v[68:71], v[8:9], off offset:-64
	global_load_dwordx4 v[76:79], v[12:13], off offset:32
	global_load_dwordx4 v[80:83], v[8:9], off offset:-32
	global_load_dwordx4 v[84:87], v[12:13], off offset:64
	global_load_dwordx4 v[88:91], v[8:9], off
	global_load_dwordx4 v[92:95], v[12:13], off offset:96
	global_load_dwordx4 v[44:47], v[8:9], off offset:32
	global_load_dwordx4 v[40:43], v[12:13], off offset:128
	global_load_dwordx4 v[36:39], v[8:9], off offset:64
	global_load_dwordx4 v[32:35], v[12:13], off offset:160
	v_addc_co_u32_e32 v21, vcc, 0, v11, vcc
	v_add_u32_e32 v12, 0x2000, v74
	global_load_dwordx4 v[96:99], v[20:21], off offset:32
	global_load_dwordx4 v[100:103], v[20:21], off offset:64
	global_load_dwordx4 v[104:107], v[20:21], off offset:96
	v_add_u32_e32 v110, 0x2080, v74
	v_lshl_add_u64 v[58:59], v[58:59], 0, s[58:59]
	v_lshl_add_u64 v[52:53], v[52:53], 0, s[60:61]
	v_lshl_add_u64 v[54:55], v[54:55], 0, s[62:63]
	v_lshl_add_u64 v[56:57], v[56:57], 0, s[62:63]
	s_waitcnt vmcnt(12)
	v_lshlrev_b32_e32 v72, 16, v68
	v_lshlrev_b32_e32 v8, 16, v0
	v_and_b32_e32 v9, 0xffff0000, v0
	v_add_u32_e32 v0, 0x2008, v74
	ds_read2_b32 v[10:11], v0 offset1:1
	ds_read2_b32 v[12:13], v12 offset1:1
	v_lshlrev_b32_e32 v0, 16, v1
	v_and_b32_e32 v1, 0xffff0000, v1
	v_and_b32_e32 v73, 0xffff0000, v68
	s_waitcnt lgkmcnt(1)
	v_mov_b32_e32 v15, v10
	s_waitcnt lgkmcnt(0)
	v_mov_b32_e32 v14, v12
	v_pk_add_f32 v[8:9], v[8:9], v[14:15] neg_lo:[0,1] neg_hi:[0,1]
	v_mov_b32_e32 v10, v13
	v_pk_mul_f32 v[8:9], v[8:9], v[10:11]
	v_add_u32_e32 v12, 0x2010, v74
	v_add_u32_e32 v10, 0x2018, v74
	ds_read2_b32 v[10:11], v10 offset1:1
	ds_read2_b32 v[12:13], v12 offset1:1
	v_add_u32_e32 v68, 0x2088, v74
	v_pk_fma_f32 v[8:9], v[60:61], v[8:9], v[62:63] op_sel_hi:[0,1,0]
	s_waitcnt lgkmcnt(1)
	v_mov_b32_e32 v15, v10
	s_waitcnt lgkmcnt(0)
	v_mov_b32_e32 v14, v12
	v_pk_add_f32 v[0:1], v[0:1], v[14:15] neg_lo:[0,1] neg_hi:[0,1]
	v_mov_b32_e32 v10, v13
	v_pk_mul_f32 v[0:1], v[0:1], v[10:11]
	v_add_u32_e32 v14, 0x2020, v74
	v_lshlrev_b32_e32 v10, 16, v2
	v_and_b32_e32 v11, 0xffff0000, v2
	v_add_u32_e32 v2, 0x2028, v74
	ds_read2_b32 v[12:13], v2 offset1:1
	ds_read2_b32 v[14:15], v14 offset1:1
	v_lshlrev_b32_e32 v2, 16, v3
	v_and_b32_e32 v3, 0xffff0000, v3
	v_pk_fma_f32 v[0:1], v[60:61], v[0:1], v[62:63] op_sel_hi:[0,1,0]
	s_waitcnt lgkmcnt(1)
	v_mov_b32_e32 v17, v12
	s_waitcnt lgkmcnt(0)
	v_mov_b32_e32 v16, v14
	v_pk_add_f32 v[10:11], v[10:11], v[16:17] neg_lo:[0,1] neg_hi:[0,1]
	v_mov_b32_e32 v12, v15
	v_pk_mul_f32 v[10:11], v[10:11], v[12:13]
	v_add_u32_e32 v14, 0x2030, v74
	v_add_u32_e32 v12, 0x2038, v74
	ds_read2_b32 v[12:13], v12 offset1:1
	ds_read2_b32 v[14:15], v14 offset1:1
	global_load_dwordx4 v[20:23], v[20:21], off
	ds_read2_b32 v[108:109], v68 offset1:1
	ds_read2_b32 v[110:111], v110 offset1:1
	v_lshlrev_b32_e32 v68, 16, v69
	v_and_b32_e32 v69, 0xffff0000, v69
	s_waitcnt lgkmcnt(2)
	v_mov_b32_e32 v16, v14
	s_waitcnt lgkmcnt(1)
	v_mov_b32_e32 v113, v108
	s_waitcnt lgkmcnt(0)
	v_mov_b32_e32 v112, v110
	v_pk_add_f32 v[72:73], v[72:73], v[112:113] neg_lo:[0,1] neg_hi:[0,1]
	v_mov_b32_e32 v108, v111
	v_pk_mul_f32 v[72:73], v[72:73], v[108:109]
	v_add_u32_e32 v110, 0x2090, v74
	v_add_u32_e32 v108, 0x2098, v74
	ds_read2_b32 v[108:109], v108 offset1:1
	ds_read2_b32 v[110:111], v110 offset1:1
	v_mov_b32_e32 v17, v12
	v_pk_add_f32 v[2:3], v[2:3], v[16:17] neg_lo:[0,1] neg_hi:[0,1]
	v_mov_b32_e32 v12, v15
	s_waitcnt lgkmcnt(1)
	v_mov_b32_e32 v113, v108
	s_waitcnt lgkmcnt(0)
	v_mov_b32_e32 v112, v110
	v_pk_add_f32 v[68:69], v[68:69], v[112:113] neg_lo:[0,1] neg_hi:[0,1]
	v_mov_b32_e32 v108, v111
	v_pk_mul_f32 v[68:69], v[68:69], v[108:109]
	v_add_u32_e32 v112, 0x20a0, v74
	v_pk_fma_f32 v[108:109], v[60:61], v[68:69], v[62:63] op_sel_hi:[0,1,0]
	v_lshlrev_b32_e32 v68, 16, v70
	v_and_b32_e32 v69, 0xffff0000, v70
	v_add_u32_e32 v70, 0x20a8, v74
	ds_read2_b32 v[110:111], v70 offset1:1
	ds_read2_b32 v[112:113], v112 offset1:1
	v_pk_mul_f32 v[2:3], v[2:3], v[12:13]
	v_add_u32_e32 v70, 0x20b8, v74
	v_pk_fma_f32 v[10:11], v[60:61], v[10:11], v[62:63] op_sel_hi:[0,1,0]
	s_waitcnt lgkmcnt(1)
	v_mov_b32_e32 v115, v110
	s_waitcnt lgkmcnt(0)
	v_mov_b32_e32 v114, v112
	v_pk_add_f32 v[68:69], v[68:69], v[114:115] neg_lo:[0,1] neg_hi:[0,1]
	v_mov_b32_e32 v110, v113
	v_pk_mul_f32 v[68:69], v[68:69], v[110:111]
	v_add_u32_e32 v112, 0x20b0, v74
	v_pk_fma_f32 v[2:3], v[60:61], v[2:3], v[62:63] op_sel_hi:[0,1,0]
	v_pk_fma_f32 v[110:111], v[60:61], v[68:69], v[62:63] op_sel_hi:[0,1,0]
	v_lshlrev_b32_e32 v68, 16, v71
	v_and_b32_e32 v69, 0xffff0000, v71
	ds_read2_b32 v[70:71], v70 offset1:1
	ds_read2_b32 v[112:113], v112 offset1:1
	v_cvt_pk_bf16_f32 v16, v8, v9
	v_cvt_pk_bf16_f32 v17, v0, v1
	v_cvt_pk_bf16_f32 v18, v10, v11
	v_cvt_pk_bf16_f32 v19, v2, v3
	s_waitcnt lgkmcnt(0)
	v_mov_b32_e32 v114, v112
	v_mov_b32_e32 v115, v70
	v_mfma_f32_32x32x16_bf16 v[0:15], v[16:19], v[4:7], 0
	v_add_f32_e64 v68, v68, -v114
	v_add_f32_e64 v69, v69, -v115
	v_mov_b32_e32 v70, v113
	v_mul_f32_e64 v68, v68, v70
	v_mul_f32_e64 v69, v69, v71
	v_pk_fma_f32 v[72:73], v[60:61], v[72:73], v[62:63] op_sel_hi:[0,1,0]
	v_pk_fma_f32 v[112:113], v[60:61], v[68:69], v[62:63] op_sel_hi:[0,1,0]
	v_cvt_pk_bf16_f32 v68, v72, v73
	v_cvt_pk_bf16_f32 v69, v108, v109
	v_cvt_pk_bf16_f32 v70, v110, v111
	v_cvt_pk_bf16_f32 v71, v112, v113
	v_add_u32_e32 v72, 0x2100, v74
	s_waitcnt vmcnt(0)
; __device__ __forceinline__ unsigned pk2(float lo, float hi) { f32x2 v = {lo, hi}; bf16x2_t b = __builtin_convertvector(v, bf16x2_t); return __builtin_bit_cast(unsigned, b); }
; #define MFMA32(a, b, c) __builtin_amdgcn_mfma_f32_32x32x16_bf16((a), (b), (c), 0, 0, 0)
; __device__ __forceinline__ void unpack8(const u32x4 w, float* v) { v[0] = bflo(w.x); v[1] = bfhi(w.x); v[2] = bflo(w.y); v[3] = bfhi(w.y); v[4] = bflo(w.z); v[5] = bfhi(w.z); v[6] = bflo(w.w); v[7] = bfhi(w.w); }
; template <int tbA, int tbB> ...
;     ...
; #pragma unroll
;         for (int k = 0; k < NSB; ++k) {
;             float v[8]; unpack8(raw[k], v);
; #pragma unroll
;             for (int jj = 0; jj < 8; ++jj) { const float mean = stat[(16 * k + 8 * hh + jj) * 2 + so], rstd = stat[(16 * k + 8 * hh + jj) * 2 + 1 + so]; v[jj] = (v[jj] - mean) * rstd * gg + bb; }
;             u32x4 af; af.x = pk2(v[0], v[1]); af.y = pk2(v[2], v[3]); af.z = pk2(v[4], v[5]); af.w = pk2(v[6], v[7]);
;             accB = MFMA32(__builtin_bit_cast(bf16x8, af), wB[k], accB);
;             if (k < NSA) accA = MFMA32(__builtin_bit_cast(bf16x8, af), wA[k < NSA ? k : 0], accA);
;         }
	v_mfma_f32_32x32x16_bf16 v[16:31], v[16:19], v[20:23], 0
	v_mfma_f32_32x32x16_bf16 v[0:15], v[68:71], v[76:79], v[0:15]
	v_mfma_f32_32x32x16_bf16 v[16:31], v[68:71], v[96:99], v[16:31]
	v_add_u32_e32 v70, 0x2108, v74
	ds_read2_b32 v[70:71], v70 offset1:1
	ds_read2_b32 v[72:73], v72 offset1:1
	v_lshlrev_b32_e32 v68, 16, v80
	v_and_b32_e32 v69, 0xffff0000, v80
	s_waitcnt lgkmcnt(1)
	v_mov_b32_e32 v77, v70
	s_waitcnt lgkmcnt(0)
	v_mov_b32_e32 v76, v72
	v_pk_add_f32 v[68:69], v[68:69], v[76:77] neg_lo:[0,1] neg_hi:[0,1]
	v_add_u32_e32 v76, 0x2110, v74
	v_add_u32_e32 v72, 0x2118, v74
	v_mov_b32_e32 v70, v73
	ds_read2_b32 v[72:73], v72 offset1:1
	ds_read2_b32 v[76:77], v76 offset1:1
	v_pk_mul_f32 v[68:69], v[68:69], v[70:71]
	v_lshlrev_b32_e32 v70, 16, v81
	v_and_b32_e32 v71, 0xffff0000, v81
	s_waitcnt lgkmcnt(1)
	v_mov_b32_e32 v79, v72
	s_waitcnt lgkmcnt(0)
	v_mov_b32_e32 v78, v76
	v_pk_add_f32 v[70:71], v[70:71], v[78:79] neg_lo:[0,1] neg_hi:[0,1]
	v_add_u32_e32 v78, 0x2120, v74
	v_add_u32_e32 v76, 0x2128, v74
	v_mov_b32_e32 v72, v77
	ds_read2_b32 v[76:77], v76 offset1:1
	ds_read2_b32 v[78:79], v78 offset1:1
	v_pk_mul_f32 v[70:71], v[70:71], v[72:73]
	v_lshlrev_b32_e32 v72, 16, v82
	v_and_b32_e32 v73, 0xffff0000, v82
	s_waitcnt lgkmcnt(1)
	v_mov_b32_e32 v81, v76
	s_waitcnt lgkmcnt(0)
	v_mov_b32_e32 v80, v78
	v_pk_add_f32 v[72:73], v[72:73], v[80:81] neg_lo:[0,1] neg_hi:[0,1]
	v_add_u32_e32 v80, 0x2130, v74
	v_add_u32_e32 v78, 0x2138, v74
	v_mov_b32_e32 v76, v79
	ds_read2_b32 v[78:79], v78 offset1:1
	ds_read2_b32 v[80:81], v80 offset1:1
	v_pk_mul_f32 v[72:73], v[72:73], v[76:77]
	v_lshlrev_b32_e32 v76, 16, v83
	v_and_b32_e32 v77, 0xffff0000, v83
	s_waitcnt lgkmcnt(1)
	v_mov_b32_e32 v83, v78
	s_waitcnt lgkmcnt(0)
	v_mov_b32_e32 v82, v80
	v_pk_add_f32 v[76:77], v[76:77], v[82:83] neg_lo:[0,1] neg_hi:[0,1]
	v_mov_b32_e32 v78, v81
	v_pk_mul_f32 v[76:77], v[76:77], v[78:79]
	v_pk_fma_f32 v[68:69], v[60:61], v[68:69], v[62:63] op_sel_hi:[0,1,0]
	v_pk_fma_f32 v[70:71], v[60:61], v[70:71], v[62:63] op_sel_hi:[0,1,0]
	v_pk_fma_f32 v[72:73], v[60:61], v[72:73], v[62:63] op_sel_hi:[0,1,0]
	v_pk_fma_f32 v[76:77], v[60:61], v[76:77], v[62:63] op_sel_hi:[0,1,0]
	v_cvt_pk_bf16_f32 v68, v68, v69
	v_cvt_pk_bf16_f32 v69, v70, v71
	v_cvt_pk_bf16_f32 v70, v72, v73
	v_cvt_pk_bf16_f32 v71, v76, v77
	v_add_u32_e32 v72, 0x2180, v74
	s_nop 0
	v_mfma_f32_32x32x16_bf16 v[0:15], v[68:71], v[84:87], v[0:15]
	v_mfma_f32_32x32x16_bf16 v[16:31], v[68:71], v[100:103], v[16:31]
	v_add_u32_e32 v70, 0x2188, v74
	ds_read2_b32 v[70:71], v70 offset1:1
	ds_read2_b32 v[72:73], v72 offset1:1
	v_lshlrev_b32_e32 v68, 16, v88
	v_and_b32_e32 v69, 0xffff0000, v88
	s_waitcnt lgkmcnt(1)
	v_mov_b32_e32 v77, v70
	s_waitcnt lgkmcnt(0)
	v_mov_b32_e32 v76, v72
	v_pk_add_f32 v[68:69], v[68:69], v[76:77] neg_lo:[0,1] neg_hi:[0,1]
	v_add_u32_e32 v76, 0x2190, v74
	v_add_u32_e32 v72, 0x2198, v74
	v_mov_b32_e32 v70, v73
	ds_read2_b32 v[72:73], v72 offset1:1
	ds_read2_b32 v[76:77], v76 offset1:1
	v_pk_mul_f32 v[68:69], v[68:69], v[70:71]
	v_lshlrev_b32_e32 v70, 16, v89
	v_and_b32_e32 v71, 0xffff0000, v89
	s_waitcnt lgkmcnt(1)
	v_mov_b32_e32 v79, v72
	s_waitcnt lgkmcnt(0)
	v_mov_b32_e32 v78, v76
	v_pk_add_f32 v[70:71], v[70:71], v[78:79] neg_lo:[0,1] neg_hi:[0,1]
	v_add_u32_e32 v78, 0x21a0, v74
	v_add_u32_e32 v76, 0x21a8, v74
	v_mov_b32_e32 v72, v77
	ds_read2_b32 v[76:77], v76 offset1:1
	ds_read2_b32 v[78:79], v78 offset1:1
	v_pk_mul_f32 v[70:71], v[70:71], v[72:73]
	v_lshlrev_b32_e32 v72, 16, v90
	v_and_b32_e32 v73, 0xffff0000, v90
	s_waitcnt lgkmcnt(1)
	v_mov_b32_e32 v81, v76
	s_waitcnt lgkmcnt(0)
	v_mov_b32_e32 v80, v78
	v_pk_add_f32 v[72:73], v[72:73], v[80:81] neg_lo:[0,1] neg_hi:[0,1]
	v_add_u32_e32 v80, 0x21b0, v74
	v_add_u32_e32 v78, 0x21b8, v74
	v_mov_b32_e32 v76, v79
	ds_read2_b32 v[78:79], v78 offset1:1
	ds_read2_b32 v[80:81], v80 offset1:1
	v_pk_mul_f32 v[72:73], v[72:73], v[76:77]
	v_lshlrev_b32_e32 v76, 16, v91
	v_and_b32_e32 v77, 0xffff0000, v91
	s_waitcnt lgkmcnt(1)
	v_mov_b32_e32 v83, v78
	s_waitcnt lgkmcnt(0)
	v_mov_b32_e32 v82, v80
	v_pk_add_f32 v[76:77], v[76:77], v[82:83] neg_lo:[0,1] neg_hi:[0,1]
	v_mov_b32_e32 v78, v81
	v_pk_mul_f32 v[76:77], v[76:77], v[78:79]
	v_pk_fma_f32 v[68:69], v[60:61], v[68:69], v[62:63] op_sel_hi:[0,1,0]
	v_pk_fma_f32 v[70:71], v[60:61], v[70:71], v[62:63] op_sel_hi:[0,1,0]
	v_pk_fma_f32 v[72:73], v[60:61], v[72:73], v[62:63] op_sel_hi:[0,1,0]
	v_pk_fma_f32 v[76:77], v[60:61], v[76:77], v[62:63] op_sel_hi:[0,1,0]
	v_cvt_pk_bf16_f32 v68, v68, v69
	v_cvt_pk_bf16_f32 v69, v70, v71
	v_cvt_pk_bf16_f32 v70, v72, v73
	v_cvt_pk_bf16_f32 v71, v76, v77
	v_add_u32_e32 v72, 0x2200, v74
	s_nop 0
	v_mfma_f32_32x32x16_bf16 v[0:15], v[68:71], v[92:95], v[0:15]
	v_mfma_f32_32x32x16_bf16 v[16:31], v[68:71], v[104:107], v[16:31]
	v_lshlrev_b32_e32 v68, 16, v44
	v_and_b32_e32 v69, 0xffff0000, v44
	v_add_u32_e32 v44, 0x2208, v74
	ds_read2_b32 v[70:71], v44 offset1:1
	ds_read2_b32 v[72:73], v72 offset1:1
	v_lshlrev_b32_e32 v44, 16, v45
	v_and_b32_e32 v45, 0xffff0000, v45
	s_waitcnt lgkmcnt(1)
	v_mov_b32_e32 v77, v70
	s_waitcnt lgkmcnt(0)
	v_mov_b32_e32 v76, v72
	v_pk_add_f32 v[68:69], v[68:69], v[76:77] neg_lo:[0,1] neg_hi:[0,1]
	v_mov_b32_e32 v70, v73
	v_pk_mul_f32 v[68:69], v[68:69], v[70:71]
	v_add_u32_e32 v72, 0x2210, v74
	v_add_u32_e32 v70, 0x2218, v74
	ds_read2_b32 v[70:71], v70 offset1:1
	ds_read2_b32 v[72:73], v72 offset1:1
	v_pk_fma_f32 v[68:69], v[60:61], v[68:69], v[62:63] op_sel_hi:[0,1,0]
	s_waitcnt lgkmcnt(1)
	v_mov_b32_e32 v77, v70
	s_waitcnt lgkmcnt(0)
; #define LAS __attribute__((address_space(3)))
; __device__ __forceinline__ unsigned pk2(float lo, float hi) { f32x2 v = {lo, hi}; bf16x2_t b = __builtin_convertvector(v, bf16x2_t); return __builtin_bit_cast(unsigned, b); }
; #define MFMA32(a, b, c) __builtin_amdgcn_mfma_f32_32x32x16_bf16((a), (b), (c), 0, 0, 0)
; __device__ __forceinline__ void unpack8(const u32x4 w, float* v) { v[0] = bflo(w.x); v[1] = bfhi(w.x); v[2] = bflo(w.y); v[3] = bfhi(w.y); v[4] = bflo(w.z); v[5] = bfhi(w.z); v[6] = bflo(w.w); v[7] = bfhi(w.w); }
; template <int tbA, int tbB> ...
;     ...
; #pragma unroll
;         for (int k = 0; k < NSB; ++k) {
;             float v[8]; unpack8(raw[k], v);
; #pragma unroll
;             for (int jj = 0; jj < 8; ++jj) { const float mean = stat[(16 * k + 8 * hh + jj) * 2 + so], rstd = stat[(16 * k + 8 * hh + jj) * 2 + 1 + so]; v[jj] = (v[jj] - mean) * rstd * gg + bb; }
;             u32x4 af; af.x = pk2(v[0], v[1]); af.y = pk2(v[2], v[3]); af.z = pk2(v[4], v[5]); af.w = pk2(v[6], v[7]);
;             accB = MFMA32(__builtin_bit_cast(bf16x8, af), wB[k], accB);
;             if (k < NSA) accA = MFMA32(__builtin_bit_cast(bf16x8, af), wA[k < NSA ? k : 0], accA);
;         }
; #pragma unroll
;         for (int which = 0; which < 2; ++which) {
;             const int tb = which ? tbB : tbA; const f32x16& acc = which ? accB : accA;
;             const float sbv = spb[g * 128 + tb * 32 + r];
; #pragma unroll
;             for (int q = 0; q < 4; ++q) {
;                 u32x2 w; w.x = pk2(acc[4 * q + 0] + sbv, acc[4 * q + 1] + sbv); w.y = pk2(acc[4 * q + 2] + sbv, acc[4 * q + 3] + sbv);
;                 *(LAS u32x2*)(stg + which * 2560 + r * 80 + (8 * q + 4 * hh) * 2) = w;
;             }
	v_mov_b32_e32 v76, v72
	v_pk_add_f32 v[44:45], v[44:45], v[76:77] neg_lo:[0,1] neg_hi:[0,1]
	v_mov_b32_e32 v70, v73
	v_pk_mul_f32 v[44:45], v[44:45], v[70:71]
	v_add_u32_e32 v76, 0x2220, v74
	v_pk_fma_f32 v[70:71], v[60:61], v[44:45], v[62:63] op_sel_hi:[0,1,0]
	v_lshlrev_b32_e32 v44, 16, v46
	v_and_b32_e32 v45, 0xffff0000, v46
	v_add_u32_e32 v46, 0x2228, v74
	ds_read2_b32 v[72:73], v46 offset1:1
	ds_read2_b32 v[76:77], v76 offset1:1
	v_add_u32_e32 v46, 0x2238, v74
	s_waitcnt lgkmcnt(1)
	v_mov_b32_e32 v79, v72
	s_waitcnt lgkmcnt(0)
	v_mov_b32_e32 v78, v76
	v_pk_add_f32 v[44:45], v[44:45], v[78:79] neg_lo:[0,1] neg_hi:[0,1]
	v_mov_b32_e32 v72, v77
	v_pk_mul_f32 v[44:45], v[44:45], v[72:73]
	v_add_u32_e32 v76, 0x2230, v74
	v_pk_fma_f32 v[72:73], v[60:61], v[44:45], v[62:63] op_sel_hi:[0,1,0]
	v_lshlrev_b32_e32 v44, 16, v47
	v_and_b32_e32 v45, 0xffff0000, v47
	ds_read2_b32 v[46:47], v46 offset1:1
	ds_read2_b32 v[76:77], v76 offset1:1
	s_waitcnt lgkmcnt(1)
	v_mov_b32_e32 v79, v46
	s_waitcnt lgkmcnt(0)
	v_mov_b32_e32 v78, v76
	v_pk_add_f32 v[44:45], v[44:45], v[78:79] neg_lo:[0,1] neg_hi:[0,1]
	v_mov_b32_e32 v46, v77
	v_pk_mul_f32 v[44:45], v[44:45], v[46:47]
	v_cvt_pk_bf16_f32 v46, v72, v73
	v_pk_fma_f32 v[76:77], v[60:61], v[44:45], v[62:63] op_sel_hi:[0,1,0]
	v_cvt_pk_bf16_f32 v44, v68, v69
	v_cvt_pk_bf16_f32 v45, v70, v71
	v_cvt_pk_bf16_f32 v47, v76, v77
	s_nop 1
	v_mfma_f32_32x32x16_bf16 v[0:15], v[44:47], v[40:43], v[0:15]
	v_add_u32_e32 v44, 0x2280, v74
	v_lshlrev_b32_e32 v40, 16, v36
	v_and_b32_e32 v41, 0xffff0000, v36
	v_add_u32_e32 v36, 0x2288, v74
	ds_read2_b32 v[42:43], v36 offset1:1
	ds_read2_b32 v[44:45], v44 offset1:1
	v_lshlrev_b32_e32 v36, 16, v37
	v_and_b32_e32 v37, 0xffff0000, v37
	s_waitcnt lgkmcnt(1)
	v_mov_b32_e32 v47, v42
	s_waitcnt lgkmcnt(0)
	v_mov_b32_e32 v46, v44
	v_pk_add_f32 v[40:41], v[40:41], v[46:47] neg_lo:[0,1] neg_hi:[0,1]
	v_mov_b32_e32 v42, v45
	v_pk_mul_f32 v[40:41], v[40:41], v[42:43]
	v_add_u32_e32 v44, 0x2290, v74
	v_add_u32_e32 v42, 0x2298, v74
	ds_read2_b32 v[42:43], v42 offset1:1
	ds_read2_b32 v[44:45], v44 offset1:1
	v_pk_fma_f32 v[40:41], v[60:61], v[40:41], v[62:63] op_sel_hi:[0,1,0]
	s_waitcnt lgkmcnt(1)
	v_mov_b32_e32 v47, v42
	s_waitcnt lgkmcnt(0)
	v_mov_b32_e32 v46, v44
	v_pk_add_f32 v[36:37], v[36:37], v[46:47] neg_lo:[0,1] neg_hi:[0,1]
	v_mov_b32_e32 v42, v45
	v_pk_mul_f32 v[36:37], v[36:37], v[42:43]
	v_add_u32_e32 v46, 0x22a0, v74
	v_pk_fma_f32 v[42:43], v[60:61], v[36:37], v[62:63] op_sel_hi:[0,1,0]
	v_lshlrev_b32_e32 v36, 16, v38
	v_and_b32_e32 v37, 0xffff0000, v38
	v_add_u32_e32 v38, 0x22a8, v74
	ds_read2_b32 v[44:45], v38 offset1:1
	ds_read2_b32 v[46:47], v46 offset1:1
	v_add_u32_e32 v38, 0x22b8, v74
	s_waitcnt lgkmcnt(1)
	v_mov_b32_e32 v69, v44
	s_waitcnt lgkmcnt(0)
	v_mov_b32_e32 v68, v46
	v_pk_add_f32 v[36:37], v[36:37], v[68:69] neg_lo:[0,1] neg_hi:[0,1]
	v_mov_b32_e32 v44, v47
	v_pk_mul_f32 v[36:37], v[36:37], v[44:45]
	v_add_u32_e32 v46, 0x22b0, v74
	v_pk_fma_f32 v[44:45], v[60:61], v[36:37], v[62:63] op_sel_hi:[0,1,0]
	v_lshlrev_b32_e32 v36, 16, v39
	v_and_b32_e32 v37, 0xffff0000, v39
	ds_read2_b32 v[38:39], v38 offset1:1
	ds_read2_b32 v[46:47], v46 offset1:1
	s_waitcnt lgkmcnt(1)
	v_mov_b32_e32 v69, v38
	s_waitcnt lgkmcnt(0)
	v_mov_b32_e32 v68, v46
	v_pk_add_f32 v[36:37], v[36:37], v[68:69] neg_lo:[0,1] neg_hi:[0,1]
	v_mov_b32_e32 v38, v47
	v_pk_mul_f32 v[36:37], v[36:37], v[38:39]
	v_cvt_pk_bf16_f32 v38, v44, v45
	v_pk_fma_f32 v[46:47], v[60:61], v[36:37], v[62:63] op_sel_hi:[0,1,0]
	v_cvt_pk_bf16_f32 v36, v40, v41
	v_cvt_pk_bf16_f32 v37, v42, v43
	v_cvt_pk_bf16_f32 v39, v46, v47
	s_nop 1
	v_mfma_f32_32x32x16_bf16 v[0:15], v[36:39], v[32:35], v[0:15]
	v_add_u32_e32 v120, s8, v66
	v_add_u32_e32 v122, 0xfa008000, v120
	v_mov_b32_e32 v123, 0
	v_lshlrev_b64 v[122:123], 1, v[122:123]
	v_lshl_add_u64 v[124:125], s[30:31], 0, v[122:123]
	global_load_dwordx4 v[80:83], v[124:125], off
	v_lshl_add_u64 v[124:125], s[34:35], 0, v[122:123]
	global_load_dwordx4 v[84:87], v[124:125], off
	v_add_u32_e32 v122, 0xfa00c000, v120
	v_mov_b32_e32 v123, 0
	v_lshlrev_b64 v[122:123], 1, v[122:123]
	v_lshl_add_u64 v[124:125], s[30:31], 0, v[122:123]
	global_load_dwordx4 v[88:91], v[124:125], off
	v_lshl_add_u64 v[124:125], s[34:35], 0, v[122:123]
	global_load_dwordx4 v[92:95], v[124:125], off
	v_add_u32_e32 v122, 0xfa010000, v120
	v_mov_b32_e32 v123, 0
	v_lshlrev_b64 v[122:123], 1, v[122:123]
	v_lshl_add_u64 v[124:125], s[30:31], 0, v[122:123]
	global_load_dwordx4 v[96:99], v[124:125], off
	v_lshl_add_u64 v[124:125], s[34:35], 0, v[122:123]
	global_load_dwordx4 v[100:103], v[124:125], off
	v_add_u32_e32 v122, 0xfa014000, v120
	v_mov_b32_e32 v123, 0
	v_lshlrev_b64 v[122:123], 1, v[122:123]
	v_lshl_add_u64 v[124:125], s[30:31], 0, v[122:123]
	global_load_dwordx4 v[104:107], v[124:125], off
	v_lshl_add_u64 v[124:125], s[34:35], 0, v[122:123]
	global_load_dwordx4 v[116:119], v[124:125], off
	global_load_dword v32, v[50:51], off offset:-128
	global_load_dword v126, v[50:51], off
	s_waitcnt vmcnt(0)
	v_add_f32_e64 v16, v16, v32
	v_add_f32_e64 v17, v17, v32
	v_add_f32_e64 v18, v18, v32
	v_add_f32_e64 v19, v19, v32
	v_cvt_pk_bf16_f32 v16, v16, v17
	v_cvt_pk_bf16_f32 v17, v18, v19
	v_pk_add_f32 v[18:19], v[20:21], v[32:33] op_sel_hi:[1,0]
	v_pk_add_f32 v[20:21], v[22:23], v[32:33] op_sel_hi:[1,0]
	v_cvt_pk_bf16_f32 v18, v18, v19
	v_cvt_pk_bf16_f32 v19, v20, v21
	v_add_u32_e32 v22, 0x4000, v67
	ds_write2_b64 v22, v[16:17], v[18:19] offset1:2
	v_pk_add_f32 v[16:17], v[24:25], v[32:33] op_sel_hi:[1,0]
	v_pk_add_f32 v[18:19], v[26:27], v[32:33] op_sel_hi:[1,0]
	v_cvt_pk_bf16_f32 v16, v16, v17
	v_cvt_pk_bf16_f32 v17, v18, v19
	v_pk_add_f32 v[18:19], v[28:29], v[32:33] op_sel_hi:[1,0]
	v_pk_add_f32 v[20:21], v[30:31], v[32:33] op_sel_hi:[1,0]
	v_cvt_pk_bf16_f32 v18, v18, v19
	v_cvt_pk_bf16_f32 v19, v20, v21
	ds_write2_b64 v22, v[16:17], v[18:19] offset0:4 offset1:6
	v_add_u32_e32 v18, s8, v66
	v_add_u32_e32 v132, 0xfa008000, v18
	s_addk_i32 s8, 0x80
	v_lshl_add_u64 v[50:51], v[50:51], 0, s[62:63]
	s_cmpk_lg_i32 s8, 0x200
	s_waitcnt vmcnt(0)
; #define LAS __attribute__((address_space(3)))
; __device__ __forceinline__ unsigned pk2(float lo, float hi) { f32x2 v = {lo, hi}; bf16x2_t b = __builtin_convertvector(v, bf16x2_t); return __builtin_bit_cast(unsigned, b); }
; __device__ __forceinline__ float bflo(unsigned u) { return __uint_as_float(u << 16); }
; __device__ __forceinline__ float bfhi(unsigned u) { return __uint_as_float(u & 0xffff0000u); }
; template <int tbA, int tbB> ...
;     ...
; #pragma unroll
;             for (int q = 0; q < 4; ++q) {
;                 u32x2 w; w.x = pk2(acc[4 * q + 0] + sbv, acc[4 * q + 1] + sbv); w.y = pk2(acc[4 * q + 2] + sbv, acc[4 * q + 3] + sbv);
;                 *(LAS u32x2*)(stg + which * 2560 + r * 80 + (8 * q + 4 * hh) * 2) = w;
;             }
;         }
; #pragma unroll
;         for (int which = 0; which < 2; ++which) {
;             const int tb = which ? tbB : tbA;
; #pragma unroll
;             for (int i = 0; i < 2; ++i) {
;                 const int t = (lane >> 2) + 16 * i, ck = lane & 3;
;                 const size_t a = (size_t)(tok0 + tb * 32 + t) * DH + g * 128 + cb * 32 + ck * 8;
;                 const u32x4 uu = *(const u32x4*)(U + a), gc = *(const u32x4*)(GC + a);
;                 const u32x4 mv = *(const LAS u32x4*)(stg + which * 2560 + t * 80 + ck * 16);
;                 u32x4 o; o.x = pk2(bflo(uu.x) * bflo(mv.x) * bflo(gc.x), bfhi(uu.x) * bfhi(mv.x) * bfhi(gc.x)); o.y = pk2(bflo(uu.y) * bflo(mv.y) * bflo(gc.y), bfhi(uu.y) * bfhi(mv.y) * bfhi(gc.y));
;                 o.z = pk2(bflo(uu.z) * bflo(mv.z) * bflo(gc.z), bfhi(uu.z) * bfhi(mv.z) * bfhi(gc.z)); o.w = pk2(bflo(uu.w) * bflo(mv.w) * bflo(gc.w), bfhi(uu.w) * bfhi(mv.w) * bfhi(gc.w));
;                 *(u32x4*)(OC + a) = o;
	v_pk_add_f32 v[0:1], v[0:1], v[126:127] op_sel_hi:[1,0]
	v_pk_add_f32 v[2:3], v[2:3], v[126:127] op_sel_hi:[1,0]
	v_cvt_pk_bf16_f32 v0, v0, v1
	v_cvt_pk_bf16_f32 v1, v2, v3
	v_pk_add_f32 v[2:3], v[4:5], v[126:127] op_sel_hi:[1,0]
	v_pk_add_f32 v[4:5], v[6:7], v[126:127] op_sel_hi:[1,0]
	v_cvt_pk_bf16_f32 v2, v2, v3
	v_cvt_pk_bf16_f32 v3, v4, v5
	v_add_u32_e32 v6, 0x4800, v67
	ds_write2_b64 v6, v[0:1], v[2:3] offset0:64 offset1:66
	v_pk_add_f32 v[0:1], v[8:9], v[126:127] op_sel_hi:[1,0]
	v_pk_add_f32 v[2:3], v[10:11], v[126:127] op_sel_hi:[1,0]
	v_cvt_pk_bf16_f32 v0, v0, v1
	v_cvt_pk_bf16_f32 v1, v2, v3
	v_pk_add_f32 v[2:3], v[12:13], v[126:127] op_sel_hi:[1,0]
	v_pk_add_f32 v[4:5], v[14:15], v[126:127] op_sel_hi:[1,0]
	v_cvt_pk_bf16_f32 v2, v2, v3
	v_cvt_pk_bf16_f32 v3, v4, v5
	v_lshlrev_b64 v[12:13], 1, v[132:133]
	ds_write2_b64 v6, v[0:1], v[2:3] offset0:68 offset1:70
	v_mov_b32_e32 v0, v80
	v_mov_b32_e32 v1, v81
	v_mov_b32_e32 v2, v82
	v_mov_b32_e32 v3, v83
	v_mov_b32_e32 v4, v84
	v_mov_b32_e32 v5, v85
	v_mov_b32_e32 v6, v86
	v_mov_b32_e32 v7, v87
	ds_read_b128 v[8:11], v75 offset:16384
	v_add_u32_e32 v132, 0xfa00c000, v18
	s_waitcnt lgkmcnt(0)
	v_lshlrev_b32_e32 v16, 16, v8
	v_and_b32_e32 v17, 0xffff0000, v8
	v_lshlrev_b32_e32 v8, 16, v9
	v_and_b32_e32 v9, 0xffff0000, v9
	v_lshlrev_b32_e32 v14, 16, v0
	v_and_b32_e32 v15, 0xffff0000, v0
	v_pk_mul_f32 v[14:15], v[14:15], v[16:17]
	v_lshlrev_b32_e32 v16, 16, v4
	v_and_b32_e32 v17, 0xffff0000, v4
	v_pk_mul_f32 v[14:15], v[14:15], v[16:17]
	v_lshlrev_b32_e32 v4, 16, v5
	v_cvt_pk_bf16_f32 v0, v14, v15
	v_lshlrev_b32_e32 v14, 16, v1
	v_and_b32_e32 v15, 0xffff0000, v1
	v_pk_mul_f32 v[8:9], v[14:15], v[8:9]
	v_and_b32_e32 v5, 0xffff0000, v5
	v_pk_mul_f32 v[4:5], v[8:9], v[4:5]
	v_lshlrev_b32_e32 v8, 16, v10
	v_cvt_pk_bf16_f32 v1, v4, v5
	v_lshlrev_b32_e32 v4, 16, v2
	v_and_b32_e32 v5, 0xffff0000, v2
	v_and_b32_e32 v9, 0xffff0000, v10
	v_pk_mul_f32 v[4:5], v[4:5], v[8:9]
	v_lshlrev_b32_e32 v8, 16, v6
	v_and_b32_e32 v9, 0xffff0000, v6
	v_pk_mul_f32 v[4:5], v[4:5], v[8:9]
	v_lshlrev_b32_e32 v8, 16, v11
	v_cvt_pk_bf16_f32 v2, v4, v5
	v_lshlrev_b32_e32 v4, 16, v3
	v_and_b32_e32 v5, 0xffff0000, v3
	v_and_b32_e32 v9, 0xffff0000, v11
	v_pk_mul_f32 v[4:5], v[4:5], v[8:9]
	v_lshlrev_b32_e32 v6, 16, v7
	v_and_b32_e32 v7, 0xffff0000, v7
	v_pk_mul_f32 v[4:5], v[4:5], v[6:7]
	ds_read_b128 v[8:11], v75 offset:17664
	v_cvt_pk_bf16_f32 v3, v4, v5
	v_lshl_add_u64 v[4:5], s[36:37], 0, v[12:13]
	v_lshlrev_b64 v[12:13], 1, v[132:133]
	global_store_dwordx4 v[4:5], v[0:3], off
	v_mov_b32_e32 v4, v92
	v_mov_b32_e32 v5, v93
	v_mov_b32_e32 v6, v94
	v_mov_b32_e32 v7, v95
	v_mov_b32_e32 v0, v88
	v_mov_b32_e32 v1, v89
	v_mov_b32_e32 v2, v90
	v_mov_b32_e32 v3, v91
	s_waitcnt lgkmcnt(0)
	v_lshlrev_b32_e32 v16, 16, v8
	v_and_b32_e32 v17, 0xffff0000, v8
	v_lshlrev_b32_e32 v8, 16, v9
	v_and_b32_e32 v9, 0xffff0000, v9
	v_add_u32_e32 v132, 0xfa010000, v18
	v_lshlrev_b32_e32 v14, 16, v0
	v_and_b32_e32 v15, 0xffff0000, v0
	v_pk_mul_f32 v[14:15], v[14:15], v[16:17]
	v_lshlrev_b32_e32 v16, 16, v4
	v_and_b32_e32 v17, 0xffff0000, v4
	v_pk_mul_f32 v[14:15], v[14:15], v[16:17]
	v_lshlrev_b32_e32 v4, 16, v5
	v_cvt_pk_bf16_f32 v0, v14, v15
	v_lshlrev_b32_e32 v14, 16, v1
	v_and_b32_e32 v15, 0xffff0000, v1
	v_pk_mul_f32 v[8:9], v[14:15], v[8:9]
	v_and_b32_e32 v5, 0xffff0000, v5
	v_pk_mul_f32 v[4:5], v[8:9], v[4:5]
	v_lshlrev_b32_e32 v8, 16, v10
	v_cvt_pk_bf16_f32 v1, v4, v5
	v_lshlrev_b32_e32 v4, 16, v2
	v_and_b32_e32 v5, 0xffff0000, v2
	v_and_b32_e32 v9, 0xffff0000, v10
	v_pk_mul_f32 v[4:5], v[4:5], v[8:9]
	v_lshlrev_b32_e32 v8, 16, v6
	v_and_b32_e32 v9, 0xffff0000, v6
	v_pk_mul_f32 v[4:5], v[4:5], v[8:9]
	v_lshlrev_b32_e32 v8, 16, v11
	v_cvt_pk_bf16_f32 v2, v4, v5
	v_lshlrev_b32_e32 v4, 16, v3
	v_and_b32_e32 v5, 0xffff0000, v3
	v_and_b32_e32 v9, 0xffff0000, v11
	v_pk_mul_f32 v[4:5], v[4:5], v[8:9]
	v_lshlrev_b32_e32 v6, 16, v7
	v_and_b32_e32 v7, 0xffff0000, v7
	v_pk_mul_f32 v[4:5], v[4:5], v[6:7]
	ds_read_b128 v[8:11], v75 offset:18944
	v_cvt_pk_bf16_f32 v3, v4, v5
	v_lshl_add_u64 v[4:5], s[36:37], 0, v[12:13]
	v_lshlrev_b64 v[12:13], 1, v[132:133]
	global_store_dwordx4 v[4:5], v[0:3], off
	v_mov_b32_e32 v4, v100
	v_mov_b32_e32 v5, v101
	v_mov_b32_e32 v6, v102
	v_mov_b32_e32 v7, v103
	v_mov_b32_e32 v0, v96
	v_mov_b32_e32 v1, v97
	v_mov_b32_e32 v2, v98
	v_mov_b32_e32 v3, v99
	s_waitcnt lgkmcnt(0)
; #define LAS __attribute__((address_space(3)))
; __device__ __forceinline__ unsigned pk2(float lo, float hi) { f32x2 v = {lo, hi}; bf16x2_t b = __builtin_convertvector(v, bf16x2_t); return __builtin_bit_cast(unsigned, b); }
; __device__ __forceinline__ float bflo(unsigned u) { return __uint_as_float(u << 16); }
; __device__ __forceinline__ float bfhi(unsigned u) { return __uint_as_float(u & 0xffff0000u); }
; template <int tbA, int tbB> ...
;     ...
;         for (int which = 0; which < 2; ++which) {
;             const int tb = which ? tbB : tbA;
; #pragma unroll
;             for (int i = 0; i < 2; ++i) {
;                 const int t = (lane >> 2) + 16 * i, ck = lane & 3;
;                 const size_t a = (size_t)(tok0 + tb * 32 + t) * DH + g * 128 + cb * 32 + ck * 8;
;                 const u32x4 uu = *(const u32x4*)(U + a), gc = *(const u32x4*)(GC + a);
;                 const u32x4 mv = *(const LAS u32x4*)(stg + which * 2560 + t * 80 + ck * 16);
;                 u32x4 o; o.x = pk2(bflo(uu.x) * bflo(mv.x) * bflo(gc.x), bfhi(uu.x) * bfhi(mv.x) * bfhi(gc.x)); o.y = pk2(bflo(uu.y) * bflo(mv.y) * bflo(gc.y), bfhi(uu.y) * bfhi(mv.y) * bfhi(gc.y));
;                 o.z = pk2(bflo(uu.z) * bflo(mv.z) * bflo(gc.z), bfhi(uu.z) * bfhi(mv.z) * bfhi(gc.z)); o.w = pk2(bflo(uu.w) * bflo(mv.w) * bflo(gc.w), bfhi(uu.w) * bfhi(mv.w) * bfhi(gc.w));
;                 *(u32x4*)(OC + a) = o;
;             }
	v_lshlrev_b32_e32 v16, 16, v8
	v_and_b32_e32 v17, 0xffff0000, v8
	v_lshlrev_b32_e32 v8, 16, v9
	v_and_b32_e32 v9, 0xffff0000, v9
	v_add_u32_e32 v132, 0xfa014000, v18
	v_lshlrev_b32_e32 v14, 16, v0
	v_and_b32_e32 v15, 0xffff0000, v0
	v_pk_mul_f32 v[14:15], v[14:15], v[16:17]
	v_lshlrev_b32_e32 v16, 16, v4
	v_and_b32_e32 v17, 0xffff0000, v4
	v_pk_mul_f32 v[14:15], v[14:15], v[16:17]
	v_lshlrev_b32_e32 v4, 16, v5
	v_cvt_pk_bf16_f32 v0, v14, v15
	v_lshlrev_b32_e32 v14, 16, v1
	v_and_b32_e32 v15, 0xffff0000, v1
	v_pk_mul_f32 v[8:9], v[14:15], v[8:9]
	v_and_b32_e32 v5, 0xffff0000, v5
	v_pk_mul_f32 v[4:5], v[8:9], v[4:5]
	v_lshlrev_b32_e32 v8, 16, v10
	v_cvt_pk_bf16_f32 v1, v4, v5
	v_lshlrev_b32_e32 v4, 16, v2
	v_and_b32_e32 v5, 0xffff0000, v2
	v_and_b32_e32 v9, 0xffff0000, v10
	v_pk_mul_f32 v[4:5], v[4:5], v[8:9]
	v_lshlrev_b32_e32 v8, 16, v6
	v_and_b32_e32 v9, 0xffff0000, v6
	v_pk_mul_f32 v[4:5], v[4:5], v[8:9]
	v_lshlrev_b32_e32 v8, 16, v11
	v_cvt_pk_bf16_f32 v2, v4, v5
	v_lshlrev_b32_e32 v4, 16, v3
	v_and_b32_e32 v5, 0xffff0000, v3
	v_and_b32_e32 v9, 0xffff0000, v11
	v_pk_mul_f32 v[4:5], v[4:5], v[8:9]
	v_lshlrev_b32_e32 v6, 16, v7
	v_and_b32_e32 v7, 0xffff0000, v7
	v_pk_mul_f32 v[4:5], v[4:5], v[6:7]
	ds_read_b128 v[8:11], v75 offset:20224
	v_cvt_pk_bf16_f32 v3, v4, v5
	v_lshl_add_u64 v[4:5], s[36:37], 0, v[12:13]
	v_lshlrev_b64 v[12:13], 1, v[132:133]
	global_store_dwordx4 v[4:5], v[0:3], off
	v_mov_b32_e32 v4, v116
	v_mov_b32_e32 v5, v117
	v_mov_b32_e32 v6, v118
	v_mov_b32_e32 v7, v119
	v_mov_b32_e32 v0, v104
	v_mov_b32_e32 v1, v105
	v_mov_b32_e32 v2, v106
	v_mov_b32_e32 v3, v107
	s_waitcnt lgkmcnt(0)
	v_lshlrev_b32_e32 v16, 16, v8
	v_and_b32_e32 v17, 0xffff0000, v8
	v_lshlrev_b32_e32 v8, 16, v9
	v_and_b32_e32 v9, 0xffff0000, v9
	v_lshlrev_b32_e32 v14, 16, v0
	v_and_b32_e32 v15, 0xffff0000, v0
	v_pk_mul_f32 v[14:15], v[14:15], v[16:17]
	v_lshlrev_b32_e32 v16, 16, v4
	v_and_b32_e32 v17, 0xffff0000, v4
	v_pk_mul_f32 v[14:15], v[14:15], v[16:17]
	v_lshlrev_b32_e32 v4, 16, v5
	v_cvt_pk_bf16_f32 v0, v14, v15
	v_lshlrev_b32_e32 v14, 16, v1
	v_and_b32_e32 v15, 0xffff0000, v1
	v_pk_mul_f32 v[8:9], v[14:15], v[8:9]
	v_and_b32_e32 v5, 0xffff0000, v5
	v_pk_mul_f32 v[4:5], v[8:9], v[4:5]
	v_lshlrev_b32_e32 v8, 16, v10
	v_cvt_pk_bf16_f32 v1, v4, v5
	v_lshlrev_b32_e32 v4, 16, v2
	v_and_b32_e32 v5, 0xffff0000, v2
	v_and_b32_e32 v9, 0xffff0000, v10
	v_pk_mul_f32 v[4:5], v[4:5], v[8:9]
	v_lshlrev_b32_e32 v8, 16, v6
	v_and_b32_e32 v9, 0xffff0000, v6
	v_pk_mul_f32 v[4:5], v[4:5], v[8:9]
	v_lshlrev_b32_e32 v8, 16, v11
	v_cvt_pk_bf16_f32 v2, v4, v5
	v_lshlrev_b32_e32 v4, 16, v3
	v_and_b32_e32 v5, 0xffff0000, v3
	v_and_b32_e32 v9, 0xffff0000, v11
	v_pk_mul_f32 v[4:5], v[4:5], v[8:9]
	v_lshlrev_b32_e32 v6, 16, v7
	v_and_b32_e32 v7, 0xffff0000, v7
	v_pk_mul_f32 v[4:5], v[4:5], v[6:7]
	s_nop 0
	v_cvt_pk_bf16_f32 v3, v4, v5
	v_lshl_add_u64 v[4:5], s[36:37], 0, v[12:13]
	global_store_dwordx4 v[4:5], v[0:3], off
	s_cbranch_scc1 .LBB0_653
	s_mov_b64 s[8:9], 0

; __device__ __forceinline__ unsigned pk2(float lo, float hi) { f32x2 v = {lo, hi}; bf16x2_t b = __builtin_convertvector(v, bf16x2_t); return __builtin_bit_cast(unsigned, b); }
; #define MFMA32(a, b, c) __builtin_amdgcn_mfma_f32_32x32x16_bf16((a), (b), (c), 0, 0, 0)
; __device__ __forceinline__ void unpack8(const u32x4 w, float* v) { v[0] = bflo(w.x); v[1] = bfhi(w.x); v[2] = bflo(w.y); v[3] = bfhi(w.y); v[4] = bflo(w.z); v[5] = bfhi(w.z); v[6] = bflo(w.w); v[7] = bfhi(w.w); }
; template <int tbA, int tbB> ...
;     for (int gi = 0; gi < 4; ++gi) {
;         const int g = gh * 4 + gi;
;         const int ch = g * 128 + cb * 32 + r;
;         const float gg = lng[ch], bb = lnb[ch];
;         const bf16_t* ap = VCT + (size_t)ch * PT + tok0 + 8 * hh;
;         const bf16_t* wp = Wbf + (size_t)g * 16384 + 8 * hh;
;         constexpr int NSB = (tbB + 1) * 2, NSA = (tbA + 1) * 2;
;         int so = 0; asm volatile("" : "+v"(so));
;         u32x4 raw[NSB]; bf16x8 wB[NSB], wA[NSA];
; #pragma unroll
;         for (int k = 0; k < NSB; ++k) { raw[k] = *(const u32x4*)(ap + 16 * k); wB[k] = *(const bf16x8*)(wp + (size_t)(tbB * 32 + r) * 128 + 16 * k); }
; #pragma unroll
;         for (int k = 0; k < NSA; ++k) wA[k] = *(const bf16x8*)(wp + (size_t)(tbA * 32 + r) * 128 + 16 * k);
;         f32x16 accA, accB;
; #pragma unroll
;         for (int i = 0; i < 16; ++i) { accA[i] = 0.f; accB[i] = 0.f; }
; #pragma unroll
;         for (int k = 0; k < NSB; ++k) {
;             float v[8]; unpack8(raw[k], v);
; #pragma unroll
;             for (int jj = 0; jj < 8; ++jj) { const float mean = stat[(16 * k + 8 * hh + jj) * 2 + so], rstd = stat[(16 * k + 8 * hh + jj) * 2 + 1 + so]; v[jj] = (v[jj] - mean) * rstd * gg + bb; }
;             u32x4 af; af.x = pk2(v[0], v[1]); af.y = pk2(v[2], v[3]); af.z = pk2(v[4], v[5]); af.w = pk2(v[6], v[7]);
;             accB = MFMA32(__builtin_bit_cast(bf16x8, af), wB[k], accB);
;             if (k < NSA) accA = MFMA32(__builtin_bit_cast(bf16x8, af), wA[k < NSA ? k : 0], accA);
;         }
.LBB0_657:
	v_lshl_add_u64 v[8:9], v[68:69], 0, v[148:149]
	v_mov_b32_e32 v14, 0
	global_load_dword v74, v[72:73], off
	global_load_dword v76, v[70:71], off
	global_load_dwordx4 v[0:3], v[8:9], off offset:-128
	v_lshl_add_u64 v[10:11], v[64:65], 0, v[148:149]
	v_add_co_u32_e32 v12, vcc, s94, v10
	v_lshl_add_u32 v79, v14, 2, v158
	s_nop 0
	v_addc_co_u32_e32 v13, vcc, 0, v11, vcc
	v_add_co_u32_e32 v20, vcc, s95, v10
	global_load_dwordx4 v[4:7], v[12:13], off
	global_load_dwordx4 v[80:83], v[8:9], off offset:-96
	global_load_dwordx4 v[84:87], v[12:13], off offset:32
	global_load_dwordx4 v[88:91], v[8:9], off offset:-64
	global_load_dwordx4 v[92:95], v[12:13], off offset:64
	global_load_dwordx4 v[96:99], v[8:9], off offset:-32
	global_load_dwordx4 v[100:103], v[12:13], off offset:96
	global_load_dwordx4 v[60:63], v[8:9], off
	global_load_dwordx4 v[56:59], v[12:13], off offset:128
	global_load_dwordx4 v[52:55], v[8:9], off offset:32
	global_load_dwordx4 v[48:51], v[12:13], off offset:160
	global_load_dwordx4 v[44:47], v[8:9], off offset:64
	global_load_dwordx4 v[40:43], v[12:13], off offset:192
	global_load_dwordx4 v[36:39], v[8:9], off offset:96
	global_load_dwordx4 v[32:35], v[12:13], off offset:224
	v_addc_co_u32_e32 v21, vcc, 0, v11, vcc
	v_add_u32_e32 v12, 0x2000, v79
	global_load_dwordx4 v[104:107], v[20:21], off offset:32
	v_add_u32_e32 v112, 0x2080, v79
	v_lshl_add_u64 v[64:65], v[64:65], 0, s[58:59]
	v_lshl_add_u64 v[68:69], v[68:69], 0, s[60:61]
	v_lshl_add_u64 v[70:71], v[70:71], 0, s[62:63]
	v_lshl_add_u64 v[72:73], v[72:73], 0, s[62:63]
	s_waitcnt vmcnt(14)
	v_lshlrev_b32_e32 v108, 16, v80
	v_and_b32_e32 v109, 0xffff0000, v80
	v_add_u32_e32 v80, 0x2088, v79
	v_lshlrev_b32_e32 v8, 16, v0
	v_and_b32_e32 v9, 0xffff0000, v0
	v_add_u32_e32 v0, 0x2008, v79
	ds_read2_b32 v[10:11], v0 offset1:1
	ds_read2_b32 v[12:13], v12 offset1:1
	v_lshlrev_b32_e32 v0, 16, v1
	v_and_b32_e32 v1, 0xffff0000, v1
	s_waitcnt lgkmcnt(1)
	v_mov_b32_e32 v15, v10
	s_waitcnt lgkmcnt(0)
	v_mov_b32_e32 v14, v12
	v_pk_add_f32 v[8:9], v[8:9], v[14:15] neg_lo:[0,1] neg_hi:[0,1]
	v_mov_b32_e32 v10, v13
	v_pk_mul_f32 v[8:9], v[8:9], v[10:11]
	v_add_u32_e32 v12, 0x2010, v79
	v_add_u32_e32 v10, 0x2018, v79
	ds_read2_b32 v[10:11], v10 offset1:1
	ds_read2_b32 v[12:13], v12 offset1:1
	v_pk_fma_f32 v[8:9], v[74:75], v[8:9], v[76:77] op_sel_hi:[0,1,0]
	s_waitcnt lgkmcnt(1)
	v_mov_b32_e32 v15, v10
	s_waitcnt lgkmcnt(0)
	v_mov_b32_e32 v14, v12
	v_pk_add_f32 v[0:1], v[0:1], v[14:15] neg_lo:[0,1] neg_hi:[0,1]
	v_mov_b32_e32 v10, v13
	v_pk_mul_f32 v[0:1], v[0:1], v[10:11]
	v_add_u32_e32 v14, 0x2020, v79
	v_lshlrev_b32_e32 v10, 16, v2
	v_and_b32_e32 v11, 0xffff0000, v2
	v_add_u32_e32 v2, 0x2028, v79
	ds_read2_b32 v[12:13], v2 offset1:1
	ds_read2_b32 v[14:15], v14 offset1:1
	v_lshlrev_b32_e32 v2, 16, v3
	v_and_b32_e32 v3, 0xffff0000, v3
	v_pk_fma_f32 v[0:1], v[74:75], v[0:1], v[76:77] op_sel_hi:[0,1,0]
	s_waitcnt lgkmcnt(1)
	v_mov_b32_e32 v17, v12
	s_waitcnt lgkmcnt(0)
	v_mov_b32_e32 v16, v14
	v_pk_add_f32 v[10:11], v[10:11], v[16:17] neg_lo:[0,1] neg_hi:[0,1]
	v_mov_b32_e32 v12, v15
	v_pk_mul_f32 v[10:11], v[10:11], v[12:13]
	v_add_u32_e32 v14, 0x2030, v79
	v_add_u32_e32 v12, 0x2038, v79
	ds_read2_b32 v[12:13], v12 offset1:1
	ds_read2_b32 v[14:15], v14 offset1:1
	global_load_dwordx4 v[20:23], v[20:21], off
	ds_read2_b32 v[110:111], v80 offset1:1
	ds_read2_b32 v[112:113], v112 offset1:1
	v_lshlrev_b32_e32 v80, 16, v81
	v_and_b32_e32 v81, 0xffff0000, v81
	s_waitcnt lgkmcnt(2)
	v_mov_b32_e32 v16, v14
	s_waitcnt lgkmcnt(1)
	v_mov_b32_e32 v115, v110
	s_waitcnt lgkmcnt(0)
	v_mov_b32_e32 v114, v112
	v_pk_add_f32 v[108:109], v[108:109], v[114:115] neg_lo:[0,1] neg_hi:[0,1]
	v_mov_b32_e32 v110, v113
	v_pk_mul_f32 v[108:109], v[108:109], v[110:111]
	v_add_u32_e32 v112, 0x2090, v79
	v_add_u32_e32 v110, 0x2098, v79
	ds_read2_b32 v[110:111], v110 offset1:1
	ds_read2_b32 v[112:113], v112 offset1:1
	v_mov_b32_e32 v17, v12
	v_pk_add_f32 v[2:3], v[2:3], v[16:17] neg_lo:[0,1] neg_hi:[0,1]
	v_mov_b32_e32 v12, v15
	s_waitcnt lgkmcnt(1)
	v_mov_b32_e32 v115, v110
	s_waitcnt lgkmcnt(0)
	v_mov_b32_e32 v114, v112
	v_pk_add_f32 v[80:81], v[80:81], v[114:115] neg_lo:[0,1] neg_hi:[0,1]
	v_mov_b32_e32 v110, v113
	v_pk_mul_f32 v[80:81], v[80:81], v[110:111]
	v_add_u32_e32 v114, 0x20a0, v79
	v_pk_fma_f32 v[110:111], v[74:75], v[80:81], v[76:77] op_sel_hi:[0,1,0]
	v_lshlrev_b32_e32 v80, 16, v82
	v_and_b32_e32 v81, 0xffff0000, v82
	v_add_u32_e32 v82, 0x20a8, v79
	ds_read2_b32 v[112:113], v82 offset1:1
	ds_read2_b32 v[114:115], v114 offset1:1
	v_pk_mul_f32 v[2:3], v[2:3], v[12:13]
	v_add_u32_e32 v82, 0x20b8, v79
	v_pk_fma_f32 v[10:11], v[74:75], v[10:11], v[76:77] op_sel_hi:[0,1,0]
	s_waitcnt lgkmcnt(1)
	v_mov_b32_e32 v117, v112
	s_waitcnt lgkmcnt(0)
	v_mov_b32_e32 v116, v114
	v_pk_add_f32 v[80:81], v[80:81], v[116:117] neg_lo:[0,1] neg_hi:[0,1]
	v_mov_b32_e32 v112, v115
	v_pk_mul_f32 v[80:81], v[80:81], v[112:113]
	v_add_u32_e32 v114, 0x20b0, v79
	v_pk_fma_f32 v[2:3], v[74:75], v[2:3], v[76:77] op_sel_hi:[0,1,0]
	v_pk_fma_f32 v[112:113], v[74:75], v[80:81], v[76:77] op_sel_hi:[0,1,0]
	v_lshlrev_b32_e32 v80, 16, v83
	v_and_b32_e32 v81, 0xffff0000, v83
	ds_read2_b32 v[82:83], v82 offset1:1
	ds_read2_b32 v[114:115], v114 offset1:1
	v_cvt_pk_bf16_f32 v16, v8, v9
	v_cvt_pk_bf16_f32 v17, v0, v1
	v_cvt_pk_bf16_f32 v18, v10, v11
	v_cvt_pk_bf16_f32 v19, v2, v3
	s_waitcnt lgkmcnt(0)
; __device__ __forceinline__ unsigned pk2(float lo, float hi) { f32x2 v = {lo, hi}; bf16x2_t b = __builtin_convertvector(v, bf16x2_t); return __builtin_bit_cast(unsigned, b); }
; #define MFMA32(a, b, c) __builtin_amdgcn_mfma_f32_32x32x16_bf16((a), (b), (c), 0, 0, 0)
; __device__ __forceinline__ void unpack8(const u32x4 w, float* v) { v[0] = bflo(w.x); v[1] = bfhi(w.x); v[2] = bflo(w.y); v[3] = bfhi(w.y); v[4] = bflo(w.z); v[5] = bfhi(w.z); v[6] = bflo(w.w); v[7] = bfhi(w.w); }
; template <int tbA, int tbB> ...
;     ...
; #pragma unroll
;         for (int k = 0; k < NSB; ++k) {
;             float v[8]; unpack8(raw[k], v);
; #pragma unroll
;             for (int jj = 0; jj < 8; ++jj) { const float mean = stat[(16 * k + 8 * hh + jj) * 2 + so], rstd = stat[(16 * k + 8 * hh + jj) * 2 + 1 + so]; v[jj] = (v[jj] - mean) * rstd * gg + bb; }
;             u32x4 af; af.x = pk2(v[0], v[1]); af.y = pk2(v[2], v[3]); af.z = pk2(v[4], v[5]); af.w = pk2(v[6], v[7]);
;             accB = MFMA32(__builtin_bit_cast(bf16x8, af), wB[k], accB);
;             if (k < NSA) accA = MFMA32(__builtin_bit_cast(bf16x8, af), wA[k < NSA ? k : 0], accA);
;         }
	v_mov_b32_e32 v116, v114
	v_mov_b32_e32 v117, v82
	v_mfma_f32_32x32x16_bf16 v[0:15], v[16:19], v[4:7], 0
	v_add_f32_e64 v80, v80, -v116
	v_add_f32_e64 v81, v81, -v117
	v_mov_b32_e32 v82, v115
	v_mul_f32_e64 v80, v80, v82
	v_mul_f32_e64 v81, v81, v83
	v_pk_fma_f32 v[108:109], v[74:75], v[108:109], v[76:77] op_sel_hi:[0,1,0]
	v_pk_fma_f32 v[114:115], v[74:75], v[80:81], v[76:77] op_sel_hi:[0,1,0]
	v_cvt_pk_bf16_f32 v80, v108, v109
	v_cvt_pk_bf16_f32 v81, v110, v111
	v_cvt_pk_bf16_f32 v82, v112, v113
	v_cvt_pk_bf16_f32 v83, v114, v115
	s_waitcnt vmcnt(0)
	v_mfma_f32_32x32x16_bf16 v[16:31], v[16:19], v[20:23], 0
	v_mfma_f32_32x32x16_bf16 v[0:15], v[80:83], v[84:87], v[0:15]
	v_add_u32_e32 v84, 0x2100, v79
	v_mfma_f32_32x32x16_bf16 v[16:31], v[80:83], v[104:107], v[16:31]
	v_add_u32_e32 v82, 0x2108, v79
	ds_read2_b32 v[82:83], v82 offset1:1
	ds_read2_b32 v[84:85], v84 offset1:1
	v_lshlrev_b32_e32 v80, 16, v88
	v_and_b32_e32 v81, 0xffff0000, v88
	s_waitcnt lgkmcnt(1)
	v_mov_b32_e32 v87, v82
	s_waitcnt lgkmcnt(0)
	v_mov_b32_e32 v86, v84
	v_pk_add_f32 v[80:81], v[80:81], v[86:87] neg_lo:[0,1] neg_hi:[0,1]
	v_add_u32_e32 v86, 0x2110, v79
	v_add_u32_e32 v84, 0x2118, v79
	v_mov_b32_e32 v82, v85
	ds_read2_b32 v[84:85], v84 offset1:1
	ds_read2_b32 v[86:87], v86 offset1:1
	v_pk_mul_f32 v[80:81], v[80:81], v[82:83]
	v_lshlrev_b32_e32 v82, 16, v89
	v_and_b32_e32 v83, 0xffff0000, v89
	s_waitcnt lgkmcnt(1)
	v_mov_b32_e32 v89, v84
	s_waitcnt lgkmcnt(0)
	v_mov_b32_e32 v88, v86
	v_pk_add_f32 v[82:83], v[82:83], v[88:89] neg_lo:[0,1] neg_hi:[0,1]
	v_add_u32_e32 v88, 0x2120, v79
	v_add_u32_e32 v86, 0x2128, v79
	v_mov_b32_e32 v84, v87
	ds_read2_b32 v[86:87], v86 offset1:1
	ds_read2_b32 v[88:89], v88 offset1:1
	v_pk_mul_f32 v[82:83], v[82:83], v[84:85]
	v_lshlrev_b32_e32 v84, 16, v90
	v_and_b32_e32 v85, 0xffff0000, v90
	s_waitcnt lgkmcnt(1)
	v_mov_b32_e32 v105, v86
	s_waitcnt lgkmcnt(0)
	v_mov_b32_e32 v104, v88
	v_pk_add_f32 v[84:85], v[84:85], v[104:105] neg_lo:[0,1] neg_hi:[0,1]
	v_mov_b32_e32 v86, v89
	v_add_u32_e32 v90, 0x2130, v79
	v_add_u32_e32 v88, 0x2138, v79
	v_pk_mul_f32 v[84:85], v[84:85], v[86:87]
	v_lshlrev_b32_e32 v86, 16, v91
	v_and_b32_e32 v87, 0xffff0000, v91
	ds_read2_b32 v[88:89], v88 offset1:1
	ds_read2_b32 v[90:91], v90 offset1:1
	v_pk_fma_f32 v[80:81], v[74:75], v[80:81], v[76:77] op_sel_hi:[0,1,0]
	v_pk_fma_f32 v[82:83], v[74:75], v[82:83], v[76:77] op_sel_hi:[0,1,0]
	v_pk_fma_f32 v[84:85], v[74:75], v[84:85], v[76:77] op_sel_hi:[0,1,0]
	s_waitcnt lgkmcnt(1)
	v_mov_b32_e32 v105, v88
	s_waitcnt lgkmcnt(0)
	v_mov_b32_e32 v104, v90
	v_pk_add_f32 v[86:87], v[86:87], v[104:105] neg_lo:[0,1] neg_hi:[0,1]
	v_mov_b32_e32 v88, v91
	v_pk_mul_f32 v[86:87], v[86:87], v[88:89]
	v_cvt_pk_bf16_f32 v80, v80, v81
	v_pk_fma_f32 v[86:87], v[74:75], v[86:87], v[76:77] op_sel_hi:[0,1,0]
	v_cvt_pk_bf16_f32 v81, v82, v83
	v_cvt_pk_bf16_f32 v82, v84, v85
	v_cvt_pk_bf16_f32 v83, v86, v87
	v_add_u32_e32 v84, 0x2180, v79
	s_nop 0
	v_mfma_f32_32x32x16_bf16 v[0:15], v[80:83], v[92:95], v[0:15]
	v_add_u32_e32 v82, 0x2188, v79
	ds_read2_b32 v[82:83], v82 offset1:1
	ds_read2_b32 v[84:85], v84 offset1:1
	v_lshlrev_b32_e32 v80, 16, v96
	v_and_b32_e32 v81, 0xffff0000, v96
	s_waitcnt lgkmcnt(1)
	v_mov_b32_e32 v87, v82
	s_waitcnt lgkmcnt(0)
	v_mov_b32_e32 v86, v84
	v_pk_add_f32 v[80:81], v[80:81], v[86:87] neg_lo:[0,1] neg_hi:[0,1]
	v_add_u32_e32 v86, 0x2190, v79
	v_add_u32_e32 v84, 0x2198, v79
	v_mov_b32_e32 v82, v85
	ds_read2_b32 v[84:85], v84 offset1:1
	ds_read2_b32 v[86:87], v86 offset1:1
	v_pk_mul_f32 v[80:81], v[80:81], v[82:83]
	v_lshlrev_b32_e32 v82, 16, v97
	v_and_b32_e32 v83, 0xffff0000, v97
	s_waitcnt lgkmcnt(1)
	v_mov_b32_e32 v89, v84
	s_waitcnt lgkmcnt(0)
	v_mov_b32_e32 v88, v86
	v_pk_add_f32 v[82:83], v[82:83], v[88:89] neg_lo:[0,1] neg_hi:[0,1]
	v_add_u32_e32 v88, 0x21a0, v79
	v_add_u32_e32 v86, 0x21a8, v79
	v_mov_b32_e32 v84, v87
	ds_read2_b32 v[86:87], v86 offset1:1
	ds_read2_b32 v[88:89], v88 offset1:1
	v_pk_mul_f32 v[82:83], v[82:83], v[84:85]
	v_lshlrev_b32_e32 v84, 16, v98
	v_and_b32_e32 v85, 0xffff0000, v98
	s_waitcnt lgkmcnt(1)
	v_mov_b32_e32 v91, v86
	s_waitcnt lgkmcnt(0)
	v_mov_b32_e32 v90, v88
	v_pk_add_f32 v[84:85], v[84:85], v[90:91] neg_lo:[0,1] neg_hi:[0,1]
	v_add_u32_e32 v90, 0x21b0, v79
	v_add_u32_e32 v88, 0x21b8, v79
	v_mov_b32_e32 v86, v89
	ds_read2_b32 v[88:89], v88 offset1:1
	ds_read2_b32 v[90:91], v90 offset1:1
	v_pk_mul_f32 v[84:85], v[84:85], v[86:87]
	v_lshlrev_b32_e32 v86, 16, v99
	v_and_b32_e32 v87, 0xffff0000, v99
	s_waitcnt lgkmcnt(1)
	v_mov_b32_e32 v93, v88
	s_waitcnt lgkmcnt(0)
	v_mov_b32_e32 v92, v90
	v_pk_add_f32 v[86:87], v[86:87], v[92:93] neg_lo:[0,1] neg_hi:[0,1]
	v_mov_b32_e32 v88, v91
	v_pk_mul_f32 v[86:87], v[86:87], v[88:89]
	v_pk_fma_f32 v[80:81], v[74:75], v[80:81], v[76:77] op_sel_hi:[0,1,0]
	v_pk_fma_f32 v[82:83], v[74:75], v[82:83], v[76:77] op_sel_hi:[0,1,0]
	v_pk_fma_f32 v[84:85], v[74:75], v[84:85], v[76:77] op_sel_hi:[0,1,0]
	v_pk_fma_f32 v[86:87], v[74:75], v[86:87], v[76:77] op_sel_hi:[0,1,0]
	v_cvt_pk_bf16_f32 v80, v80, v81
	v_cvt_pk_bf16_f32 v81, v82, v83
	v_cvt_pk_bf16_f32 v82, v84, v85
	v_cvt_pk_bf16_f32 v83, v86, v87
	v_add_u32_e32 v84, 0x2200, v79
	s_nop 0
	v_mfma_f32_32x32x16_bf16 v[0:15], v[80:83], v[100:103], v[0:15]
	v_lshlrev_b32_e32 v80, 16, v60
	v_and_b32_e32 v81, 0xffff0000, v60
	v_add_u32_e32 v60, 0x2208, v79
	ds_read2_b32 v[82:83], v60 offset1:1
	ds_read2_b32 v[84:85], v84 offset1:1
	v_lshlrev_b32_e32 v60, 16, v61
	v_and_b32_e32 v61, 0xffff0000, v61
	s_waitcnt lgkmcnt(1)
	v_mov_b32_e32 v87, v82
	s_waitcnt lgkmcnt(0)
; __device__ __forceinline__ unsigned pk2(float lo, float hi) { f32x2 v = {lo, hi}; bf16x2_t b = __builtin_convertvector(v, bf16x2_t); return __builtin_bit_cast(unsigned, b); }
; #define MFMA32(a, b, c) __builtin_amdgcn_mfma_f32_32x32x16_bf16((a), (b), (c), 0, 0, 0)
; __device__ __forceinline__ void unpack8(const u32x4 w, float* v) { v[0] = bflo(w.x); v[1] = bfhi(w.x); v[2] = bflo(w.y); v[3] = bfhi(w.y); v[4] = bflo(w.z); v[5] = bfhi(w.z); v[6] = bflo(w.w); v[7] = bfhi(w.w); }
; template <int tbA, int tbB> ...
;     ...
; #pragma unroll
;         for (int k = 0; k < NSB; ++k) {
;             float v[8]; unpack8(raw[k], v);
; #pragma unroll
;             for (int jj = 0; jj < 8; ++jj) { const float mean = stat[(16 * k + 8 * hh + jj) * 2 + so], rstd = stat[(16 * k + 8 * hh + jj) * 2 + 1 + so]; v[jj] = (v[jj] - mean) * rstd * gg + bb; }
;             u32x4 af; af.x = pk2(v[0], v[1]); af.y = pk2(v[2], v[3]); af.z = pk2(v[4], v[5]); af.w = pk2(v[6], v[7]);
;             accB = MFMA32(__builtin_bit_cast(bf16x8, af), wB[k], accB);
;             if (k < NSA) accA = MFMA32(__builtin_bit_cast(bf16x8, af), wA[k < NSA ? k : 0], accA);
;         }
	v_mov_b32_e32 v86, v84
	v_pk_add_f32 v[80:81], v[80:81], v[86:87] neg_lo:[0,1] neg_hi:[0,1]
	v_mov_b32_e32 v82, v85
	v_pk_mul_f32 v[80:81], v[80:81], v[82:83]
	v_add_u32_e32 v84, 0x2210, v79
	v_add_u32_e32 v82, 0x2218, v79
	ds_read2_b32 v[82:83], v82 offset1:1
	ds_read2_b32 v[84:85], v84 offset1:1
	v_pk_fma_f32 v[80:81], v[74:75], v[80:81], v[76:77] op_sel_hi:[0,1,0]
	s_waitcnt lgkmcnt(1)
	v_mov_b32_e32 v87, v82
	s_waitcnt lgkmcnt(0)
	v_mov_b32_e32 v86, v84
	v_pk_add_f32 v[60:61], v[60:61], v[86:87] neg_lo:[0,1] neg_hi:[0,1]
	v_mov_b32_e32 v82, v85
	v_pk_mul_f32 v[60:61], v[60:61], v[82:83]
	v_add_u32_e32 v86, 0x2220, v79
	v_pk_fma_f32 v[82:83], v[74:75], v[60:61], v[76:77] op_sel_hi:[0,1,0]
	v_lshlrev_b32_e32 v60, 16, v62
	v_and_b32_e32 v61, 0xffff0000, v62
	v_add_u32_e32 v62, 0x2228, v79
	ds_read2_b32 v[84:85], v62 offset1:1
	ds_read2_b32 v[86:87], v86 offset1:1
	v_add_u32_e32 v62, 0x2238, v79
	s_waitcnt lgkmcnt(1)
	v_mov_b32_e32 v89, v84
	s_waitcnt lgkmcnt(0)
	v_mov_b32_e32 v88, v86
	v_pk_add_f32 v[60:61], v[60:61], v[88:89] neg_lo:[0,1] neg_hi:[0,1]
	v_mov_b32_e32 v84, v87
	v_pk_mul_f32 v[60:61], v[60:61], v[84:85]
	v_add_u32_e32 v86, 0x2230, v79
	v_pk_fma_f32 v[84:85], v[74:75], v[60:61], v[76:77] op_sel_hi:[0,1,0]
	v_lshlrev_b32_e32 v60, 16, v63
	v_and_b32_e32 v61, 0xffff0000, v63
	ds_read2_b32 v[62:63], v62 offset1:1
	ds_read2_b32 v[86:87], v86 offset1:1
	s_waitcnt lgkmcnt(1)
	v_mov_b32_e32 v89, v62
	s_waitcnt lgkmcnt(0)
	v_mov_b32_e32 v88, v86
	v_pk_add_f32 v[60:61], v[60:61], v[88:89] neg_lo:[0,1] neg_hi:[0,1]
	v_mov_b32_e32 v62, v87
	v_pk_mul_f32 v[60:61], v[60:61], v[62:63]
	v_cvt_pk_bf16_f32 v62, v84, v85
	v_pk_fma_f32 v[86:87], v[74:75], v[60:61], v[76:77] op_sel_hi:[0,1,0]
	v_cvt_pk_bf16_f32 v60, v80, v81
	v_cvt_pk_bf16_f32 v61, v82, v83
	v_cvt_pk_bf16_f32 v63, v86, v87
	s_nop 1
	v_mfma_f32_32x32x16_bf16 v[0:15], v[60:63], v[56:59], v[0:15]
	v_add_u32_e32 v60, 0x2280, v79
	v_lshlrev_b32_e32 v56, 16, v52
	v_and_b32_e32 v57, 0xffff0000, v52
	v_add_u32_e32 v52, 0x2288, v79
	ds_read2_b32 v[58:59], v52 offset1:1
	ds_read2_b32 v[60:61], v60 offset1:1
	v_lshlrev_b32_e32 v52, 16, v53
	v_and_b32_e32 v53, 0xffff0000, v53
	s_waitcnt lgkmcnt(1)
	v_mov_b32_e32 v63, v58
	s_waitcnt lgkmcnt(0)
	v_mov_b32_e32 v62, v60
	v_pk_add_f32 v[56:57], v[56:57], v[62:63] neg_lo:[0,1] neg_hi:[0,1]
	v_mov_b32_e32 v58, v61
	v_pk_mul_f32 v[56:57], v[56:57], v[58:59]
	v_add_u32_e32 v60, 0x2290, v79
	v_add_u32_e32 v58, 0x2298, v79
	ds_read2_b32 v[58:59], v58 offset1:1
	ds_read2_b32 v[60:61], v60 offset1:1
	v_pk_fma_f32 v[56:57], v[74:75], v[56:57], v[76:77] op_sel_hi:[0,1,0]
	s_waitcnt lgkmcnt(1)
	v_mov_b32_e32 v63, v58
	s_waitcnt lgkmcnt(0)
	v_mov_b32_e32 v62, v60
	v_pk_add_f32 v[52:53], v[52:53], v[62:63] neg_lo:[0,1] neg_hi:[0,1]
	v_mov_b32_e32 v58, v61
	v_pk_mul_f32 v[52:53], v[52:53], v[58:59]
	v_add_u32_e32 v62, 0x22a0, v79
	v_pk_fma_f32 v[58:59], v[74:75], v[52:53], v[76:77] op_sel_hi:[0,1,0]
	v_lshlrev_b32_e32 v52, 16, v54
	v_and_b32_e32 v53, 0xffff0000, v54
	v_add_u32_e32 v54, 0x22a8, v79
	ds_read2_b32 v[60:61], v54 offset1:1
	ds_read2_b32 v[62:63], v62 offset1:1
	v_add_u32_e32 v54, 0x22b8, v79
	s_waitcnt lgkmcnt(1)
	v_mov_b32_e32 v81, v60
	s_waitcnt lgkmcnt(0)
	v_mov_b32_e32 v80, v62
	v_pk_add_f32 v[52:53], v[52:53], v[80:81] neg_lo:[0,1] neg_hi:[0,1]
	v_mov_b32_e32 v60, v63
	v_pk_mul_f32 v[52:53], v[52:53], v[60:61]
	v_add_u32_e32 v62, 0x22b0, v79
	v_pk_fma_f32 v[60:61], v[74:75], v[52:53], v[76:77] op_sel_hi:[0,1,0]
	v_lshlrev_b32_e32 v52, 16, v55
	v_and_b32_e32 v53, 0xffff0000, v55
	ds_read2_b32 v[54:55], v54 offset1:1
	ds_read2_b32 v[62:63], v62 offset1:1
	s_waitcnt lgkmcnt(1)
	v_mov_b32_e32 v81, v54
	s_waitcnt lgkmcnt(0)
	v_mov_b32_e32 v80, v62
	v_pk_add_f32 v[52:53], v[52:53], v[80:81] neg_lo:[0,1] neg_hi:[0,1]
	v_mov_b32_e32 v54, v63
	v_pk_mul_f32 v[52:53], v[52:53], v[54:55]
	v_cvt_pk_bf16_f32 v54, v60, v61
	v_pk_fma_f32 v[62:63], v[74:75], v[52:53], v[76:77] op_sel_hi:[0,1,0]
	v_cvt_pk_bf16_f32 v52, v56, v57
	v_cvt_pk_bf16_f32 v53, v58, v59
	v_cvt_pk_bf16_f32 v55, v62, v63
	s_nop 1
	v_mfma_f32_32x32x16_bf16 v[0:15], v[52:55], v[48:51], v[0:15]
	v_add_u32_e32 v52, 0x2300, v79
	v_lshlrev_b32_e32 v48, 16, v44
	v_and_b32_e32 v49, 0xffff0000, v44
	v_add_u32_e32 v44, 0x2308, v79
	ds_read2_b32 v[50:51], v44 offset1:1
	ds_read2_b32 v[52:53], v52 offset1:1
	v_lshlrev_b32_e32 v44, 16, v45
	v_and_b32_e32 v45, 0xffff0000, v45
	s_waitcnt lgkmcnt(1)
	v_mov_b32_e32 v55, v50
	s_waitcnt lgkmcnt(0)
	v_mov_b32_e32 v54, v52
	v_pk_add_f32 v[48:49], v[48:49], v[54:55] neg_lo:[0,1] neg_hi:[0,1]
	v_mov_b32_e32 v50, v53
	v_pk_mul_f32 v[48:49], v[48:49], v[50:51]
	v_add_u32_e32 v52, 0x2310, v79
	v_add_u32_e32 v50, 0x2318, v79
	ds_read2_b32 v[50:51], v50 offset1:1
	ds_read2_b32 v[52:53], v52 offset1:1
	v_pk_fma_f32 v[48:49], v[74:75], v[48:49], v[76:77] op_sel_hi:[0,1,0]
	s_waitcnt lgkmcnt(1)
	v_mov_b32_e32 v55, v50
	s_waitcnt lgkmcnt(0)
	v_mov_b32_e32 v54, v52
	v_pk_add_f32 v[44:45], v[44:45], v[54:55] neg_lo:[0,1] neg_hi:[0,1]
	v_mov_b32_e32 v50, v53
	v_pk_mul_f32 v[44:45], v[44:45], v[50:51]
	v_add_u32_e32 v54, 0x2320, v79
	v_pk_fma_f32 v[50:51], v[74:75], v[44:45], v[76:77] op_sel_hi:[0,1,0]
	v_lshlrev_b32_e32 v44, 16, v46
	v_and_b32_e32 v45, 0xffff0000, v46
	v_add_u32_e32 v46, 0x2328, v79
	ds_read2_b32 v[52:53], v46 offset1:1
	ds_read2_b32 v[54:55], v54 offset1:1
	v_add_u32_e32 v46, 0x2338, v79
	s_waitcnt lgkmcnt(1)
	v_mov_b32_e32 v57, v52
	s_waitcnt lgkmcnt(0)
; #define LAS __attribute__((address_space(3)))
; __device__ __forceinline__ unsigned pk2(float lo, float hi) { f32x2 v = {lo, hi}; bf16x2_t b = __builtin_convertvector(v, bf16x2_t); return __builtin_bit_cast(unsigned, b); }
; #define MFMA32(a, b, c) __builtin_amdgcn_mfma_f32_32x32x16_bf16((a), (b), (c), 0, 0, 0)
; __device__ __forceinline__ void unpack8(const u32x4 w, float* v) { v[0] = bflo(w.x); v[1] = bfhi(w.x); v[2] = bflo(w.y); v[3] = bfhi(w.y); v[4] = bflo(w.z); v[5] = bfhi(w.z); v[6] = bflo(w.w); v[7] = bfhi(w.w); }
; template <int tbA, int tbB> ...
;     ...
; #pragma unroll
;         for (int k = 0; k < NSB; ++k) {
;             float v[8]; unpack8(raw[k], v);
; #pragma unroll
;             for (int jj = 0; jj < 8; ++jj) { const float mean = stat[(16 * k + 8 * hh + jj) * 2 + so], rstd = stat[(16 * k + 8 * hh + jj) * 2 + 1 + so]; v[jj] = (v[jj] - mean) * rstd * gg + bb; }
;             u32x4 af; af.x = pk2(v[0], v[1]); af.y = pk2(v[2], v[3]); af.z = pk2(v[4], v[5]); af.w = pk2(v[6], v[7]);
;             accB = MFMA32(__builtin_bit_cast(bf16x8, af), wB[k], accB);
;             if (k < NSA) accA = MFMA32(__builtin_bit_cast(bf16x8, af), wA[k < NSA ? k : 0], accA);
;         }
; #pragma unroll
;         for (int which = 0; which < 2; ++which) {
;             const int tb = which ? tbB : tbA; const f32x16& acc = which ? accB : accA;
;             const float sbv = spb[g * 128 + tb * 32 + r];
; #pragma unroll
;             for (int q = 0; q < 4; ++q) {
;                 u32x2 w; w.x = pk2(acc[4 * q + 0] + sbv, acc[4 * q + 1] + sbv); w.y = pk2(acc[4 * q + 2] + sbv, acc[4 * q + 3] + sbv);
;                 *(LAS u32x2*)(stg + which * 2560 + r * 80 + (8 * q + 4 * hh) * 2) = w;
;             }
	v_mov_b32_e32 v56, v54
	v_pk_add_f32 v[44:45], v[44:45], v[56:57] neg_lo:[0,1] neg_hi:[0,1]
	v_mov_b32_e32 v52, v55
	v_pk_mul_f32 v[44:45], v[44:45], v[52:53]
	v_add_u32_e32 v54, 0x2330, v79
	v_pk_fma_f32 v[52:53], v[74:75], v[44:45], v[76:77] op_sel_hi:[0,1,0]
	v_lshlrev_b32_e32 v44, 16, v47
	v_and_b32_e32 v45, 0xffff0000, v47
	ds_read2_b32 v[46:47], v46 offset1:1
	ds_read2_b32 v[54:55], v54 offset1:1
	s_waitcnt lgkmcnt(1)
	v_mov_b32_e32 v57, v46
	s_waitcnt lgkmcnt(0)
	v_mov_b32_e32 v56, v54
	v_pk_add_f32 v[44:45], v[44:45], v[56:57] neg_lo:[0,1] neg_hi:[0,1]
	v_mov_b32_e32 v46, v55
	v_pk_mul_f32 v[44:45], v[44:45], v[46:47]
	v_cvt_pk_bf16_f32 v46, v52, v53
	v_pk_fma_f32 v[54:55], v[74:75], v[44:45], v[76:77] op_sel_hi:[0,1,0]
	v_cvt_pk_bf16_f32 v44, v48, v49
	v_cvt_pk_bf16_f32 v45, v50, v51
	v_cvt_pk_bf16_f32 v47, v54, v55
	s_nop 1
	v_mfma_f32_32x32x16_bf16 v[0:15], v[44:47], v[40:43], v[0:15]
	v_add_u32_e32 v44, 0x2380, v79
	v_lshlrev_b32_e32 v40, 16, v36
	v_and_b32_e32 v41, 0xffff0000, v36
	v_add_u32_e32 v36, 0x2388, v79
	ds_read2_b32 v[42:43], v36 offset1:1
	ds_read2_b32 v[44:45], v44 offset1:1
	v_lshlrev_b32_e32 v36, 16, v37
	v_and_b32_e32 v37, 0xffff0000, v37
	s_waitcnt lgkmcnt(1)
	v_mov_b32_e32 v47, v42
	s_waitcnt lgkmcnt(0)
	v_mov_b32_e32 v46, v44
	v_pk_add_f32 v[40:41], v[40:41], v[46:47] neg_lo:[0,1] neg_hi:[0,1]
	v_mov_b32_e32 v42, v45
	v_pk_mul_f32 v[40:41], v[40:41], v[42:43]
	v_add_u32_e32 v44, 0x2390, v79
	v_add_u32_e32 v42, 0x2398, v79
	ds_read2_b32 v[42:43], v42 offset1:1
	ds_read2_b32 v[44:45], v44 offset1:1
	v_pk_fma_f32 v[40:41], v[74:75], v[40:41], v[76:77] op_sel_hi:[0,1,0]
	s_waitcnt lgkmcnt(1)
	v_mov_b32_e32 v47, v42
	s_waitcnt lgkmcnt(0)
	v_mov_b32_e32 v46, v44
	v_pk_add_f32 v[36:37], v[36:37], v[46:47] neg_lo:[0,1] neg_hi:[0,1]
	v_mov_b32_e32 v42, v45
	v_pk_mul_f32 v[36:37], v[36:37], v[42:43]
	v_add_u32_e32 v46, 0x23a0, v79
	v_pk_fma_f32 v[42:43], v[74:75], v[36:37], v[76:77] op_sel_hi:[0,1,0]
	v_lshlrev_b32_e32 v36, 16, v38
	v_and_b32_e32 v37, 0xffff0000, v38
	v_add_u32_e32 v38, 0x23a8, v79
	ds_read2_b32 v[44:45], v38 offset1:1
	ds_read2_b32 v[46:47], v46 offset1:1
	v_add_u32_e32 v38, 0x23b8, v79
	s_waitcnt lgkmcnt(1)
	v_mov_b32_e32 v49, v44
	s_waitcnt lgkmcnt(0)
	v_mov_b32_e32 v48, v46
	v_pk_add_f32 v[36:37], v[36:37], v[48:49] neg_lo:[0,1] neg_hi:[0,1]
	v_mov_b32_e32 v44, v47
	v_pk_mul_f32 v[36:37], v[36:37], v[44:45]
	v_add_u32_e32 v46, 0x23b0, v79
	v_pk_fma_f32 v[44:45], v[74:75], v[36:37], v[76:77] op_sel_hi:[0,1,0]
	v_lshlrev_b32_e32 v36, 16, v39
	v_and_b32_e32 v37, 0xffff0000, v39
	ds_read2_b32 v[38:39], v38 offset1:1
	ds_read2_b32 v[46:47], v46 offset1:1
	s_waitcnt lgkmcnt(1)
	v_mov_b32_e32 v49, v38
	s_waitcnt lgkmcnt(0)
	v_mov_b32_e32 v48, v46
	v_pk_add_f32 v[36:37], v[36:37], v[48:49] neg_lo:[0,1] neg_hi:[0,1]
	v_mov_b32_e32 v38, v47
	v_pk_mul_f32 v[36:37], v[36:37], v[38:39]
	v_cvt_pk_bf16_f32 v38, v44, v45
	v_pk_fma_f32 v[46:47], v[74:75], v[36:37], v[76:77] op_sel_hi:[0,1,0]
	v_cvt_pk_bf16_f32 v36, v40, v41
	v_cvt_pk_bf16_f32 v37, v42, v43
	v_cvt_pk_bf16_f32 v39, v46, v47
	s_nop 1
	v_mfma_f32_32x32x16_bf16 v[0:15], v[36:39], v[32:35], v[0:15]
	v_add_u32_e32 v120, s8, v77
	v_add_u32_e32 v122, 0xfa000000, v120
	v_mov_b32_e32 v123, 0
	v_lshlrev_b64 v[122:123], 1, v[122:123]
	v_lshl_add_u64 v[124:125], s[30:31], 0, v[122:123]
	global_load_dwordx4 v[80:83], v[124:125], off
	v_lshl_add_u64 v[124:125], s[34:35], 0, v[122:123]
	global_load_dwordx4 v[84:87], v[124:125], off
	v_add_u32_e32 v122, 0xfa004000, v120
	v_mov_b32_e32 v123, 0
	v_lshlrev_b64 v[122:123], 1, v[122:123]
	v_lshl_add_u64 v[124:125], s[30:31], 0, v[122:123]
	global_load_dwordx4 v[88:91], v[124:125], off
	v_lshl_add_u64 v[124:125], s[34:35], 0, v[122:123]
	global_load_dwordx4 v[92:95], v[124:125], off
	v_add_u32_e32 v122, 0xfa018000, v120
	v_mov_b32_e32 v123, 0
	v_lshlrev_b64 v[122:123], 1, v[122:123]
	v_lshl_add_u64 v[124:125], s[30:31], 0, v[122:123]
	global_load_dwordx4 v[96:99], v[124:125], off
	v_lshl_add_u64 v[124:125], s[34:35], 0, v[122:123]
	global_load_dwordx4 v[100:103], v[124:125], off
	v_add_u32_e32 v122, 0xfa01c000, v120
	v_mov_b32_e32 v123, 0
	v_lshlrev_b64 v[122:123], 1, v[122:123]
	v_lshl_add_u64 v[124:125], s[30:31], 0, v[122:123]
	global_load_dwordx4 v[104:107], v[124:125], off
	v_lshl_add_u64 v[124:125], s[34:35], 0, v[122:123]
	global_load_dwordx4 v[116:119], v[124:125], off
	global_load_dword v32, v[66:67], off offset:-384
	global_load_dword v126, v[66:67], off
	s_waitcnt vmcnt(0)
	v_add_f32_e64 v16, v16, v32
	v_add_f32_e64 v17, v17, v32
	v_add_f32_e64 v18, v18, v32
	v_add_f32_e64 v19, v19, v32
	v_cvt_pk_bf16_f32 v16, v16, v17
	v_cvt_pk_bf16_f32 v17, v18, v19
	v_pk_add_f32 v[18:19], v[20:21], v[32:33] op_sel_hi:[1,0]
	v_pk_add_f32 v[20:21], v[22:23], v[32:33] op_sel_hi:[1,0]
	v_cvt_pk_bf16_f32 v18, v18, v19
	v_cvt_pk_bf16_f32 v19, v20, v21
	v_add_u32_e32 v22, 0x4000, v78
	ds_write2_b64 v22, v[16:17], v[18:19] offset1:2
	v_pk_add_f32 v[16:17], v[24:25], v[32:33] op_sel_hi:[1,0]
	v_pk_add_f32 v[18:19], v[26:27], v[32:33] op_sel_hi:[1,0]
	v_cvt_pk_bf16_f32 v16, v16, v17
	v_cvt_pk_bf16_f32 v17, v18, v19
	v_pk_add_f32 v[18:19], v[28:29], v[32:33] op_sel_hi:[1,0]
	v_pk_add_f32 v[20:21], v[30:31], v[32:33] op_sel_hi:[1,0]
	v_cvt_pk_bf16_f32 v18, v18, v19
	v_cvt_pk_bf16_f32 v19, v20, v21
	ds_write2_b64 v22, v[16:17], v[18:19] offset0:4 offset1:6
	v_add_u32_e32 v18, s8, v77
	v_add_u32_e32 v132, 0xfa000000, v18
	s_addk_i32 s8, 0x80
	v_lshl_add_u64 v[66:67], v[66:67], 0, s[62:63]
	s_cmpk_eq_i32 s8, 0x200
	s_waitcnt vmcnt(0)
; #define LAS __attribute__((address_space(3)))
; __device__ __forceinline__ unsigned pk2(float lo, float hi) { f32x2 v = {lo, hi}; bf16x2_t b = __builtin_convertvector(v, bf16x2_t); return __builtin_bit_cast(unsigned, b); }
; __device__ __forceinline__ float bflo(unsigned u) { return __uint_as_float(u << 16); }
; __device__ __forceinline__ float bfhi(unsigned u) { return __uint_as_float(u & 0xffff0000u); }
; template <int tbA, int tbB> ...
;     ...
; #pragma unroll
;             for (int q = 0; q < 4; ++q) {
;                 u32x2 w; w.x = pk2(acc[4 * q + 0] + sbv, acc[4 * q + 1] + sbv); w.y = pk2(acc[4 * q + 2] + sbv, acc[4 * q + 3] + sbv);
;                 *(LAS u32x2*)(stg + which * 2560 + r * 80 + (8 * q + 4 * hh) * 2) = w;
;             }
;         }
; #pragma unroll
;         for (int which = 0; which < 2; ++which) {
;             const int tb = which ? tbB : tbA;
; #pragma unroll
;             for (int i = 0; i < 2; ++i) {
;                 const int t = (lane >> 2) + 16 * i, ck = lane & 3;
;                 const size_t a = (size_t)(tok0 + tb * 32 + t) * DH + g * 128 + cb * 32 + ck * 8;
;                 const u32x4 uu = *(const u32x4*)(U + a), gc = *(const u32x4*)(GC + a);
;                 const u32x4 mv = *(const LAS u32x4*)(stg + which * 2560 + t * 80 + ck * 16);
;                 u32x4 o; o.x = pk2(bflo(uu.x) * bflo(mv.x) * bflo(gc.x), bfhi(uu.x) * bfhi(mv.x) * bfhi(gc.x)); o.y = pk2(bflo(uu.y) * bflo(mv.y) * bflo(gc.y), bfhi(uu.y) * bfhi(mv.y) * bfhi(gc.y));
;                 o.z = pk2(bflo(uu.z) * bflo(mv.z) * bflo(gc.z), bfhi(uu.z) * bfhi(mv.z) * bfhi(gc.z)); o.w = pk2(bflo(uu.w) * bflo(mv.w) * bflo(gc.w), bfhi(uu.w) * bfhi(mv.w) * bfhi(gc.w));
;                 *(u32x4*)(OC + a) = o;
	v_pk_add_f32 v[0:1], v[0:1], v[126:127] op_sel_hi:[1,0]
	v_pk_add_f32 v[2:3], v[2:3], v[126:127] op_sel_hi:[1,0]
	v_cvt_pk_bf16_f32 v0, v0, v1
	v_cvt_pk_bf16_f32 v1, v2, v3
	v_pk_add_f32 v[2:3], v[4:5], v[126:127] op_sel_hi:[1,0]
	v_pk_add_f32 v[4:5], v[6:7], v[126:127] op_sel_hi:[1,0]
	v_cvt_pk_bf16_f32 v2, v2, v3
	v_cvt_pk_bf16_f32 v3, v4, v5
	v_add_u32_e32 v6, 0x4800, v78
	ds_write2_b64 v6, v[0:1], v[2:3] offset0:64 offset1:66
	v_pk_add_f32 v[0:1], v[8:9], v[126:127] op_sel_hi:[1,0]
	v_pk_add_f32 v[2:3], v[10:11], v[126:127] op_sel_hi:[1,0]
	v_cvt_pk_bf16_f32 v0, v0, v1
	v_cvt_pk_bf16_f32 v1, v2, v3
	v_pk_add_f32 v[2:3], v[12:13], v[126:127] op_sel_hi:[1,0]
	v_pk_add_f32 v[4:5], v[14:15], v[126:127] op_sel_hi:[1,0]
	v_cvt_pk_bf16_f32 v2, v2, v3
	v_cvt_pk_bf16_f32 v3, v4, v5
	v_lshlrev_b64 v[12:13], 1, v[132:133]
	ds_write2_b64 v6, v[0:1], v[2:3] offset0:68 offset1:70
	v_mov_b32_e32 v0, v80
	v_mov_b32_e32 v1, v81
	v_mov_b32_e32 v2, v82
	v_mov_b32_e32 v3, v83
	v_mov_b32_e32 v4, v84
	v_mov_b32_e32 v5, v85
	v_mov_b32_e32 v6, v86
	v_mov_b32_e32 v7, v87
	ds_read_b128 v[8:11], v75 offset:16384
	v_add_u32_e32 v132, 0xfa004000, v18
	s_waitcnt lgkmcnt(0)
	v_lshlrev_b32_e32 v16, 16, v8
	v_and_b32_e32 v17, 0xffff0000, v8
	v_lshlrev_b32_e32 v8, 16, v9
	v_and_b32_e32 v9, 0xffff0000, v9
	v_lshlrev_b32_e32 v14, 16, v0
	v_and_b32_e32 v15, 0xffff0000, v0
	v_pk_mul_f32 v[14:15], v[14:15], v[16:17]
	v_lshlrev_b32_e32 v16, 16, v4
	v_and_b32_e32 v17, 0xffff0000, v4
	v_pk_mul_f32 v[14:15], v[14:15], v[16:17]
	v_lshlrev_b32_e32 v4, 16, v5
	v_cvt_pk_bf16_f32 v0, v14, v15
	v_lshlrev_b32_e32 v14, 16, v1
	v_and_b32_e32 v15, 0xffff0000, v1
	v_pk_mul_f32 v[8:9], v[14:15], v[8:9]
	v_and_b32_e32 v5, 0xffff0000, v5
	v_pk_mul_f32 v[4:5], v[8:9], v[4:5]
	v_lshlrev_b32_e32 v8, 16, v10
	v_cvt_pk_bf16_f32 v1, v4, v5
	v_lshlrev_b32_e32 v4, 16, v2
	v_and_b32_e32 v5, 0xffff0000, v2
	v_and_b32_e32 v9, 0xffff0000, v10
	v_pk_mul_f32 v[4:5], v[4:5], v[8:9]
	v_lshlrev_b32_e32 v8, 16, v6
	v_and_b32_e32 v9, 0xffff0000, v6
	v_pk_mul_f32 v[4:5], v[4:5], v[8:9]
	v_lshlrev_b32_e32 v8, 16, v11
	v_cvt_pk_bf16_f32 v2, v4, v5
	v_lshlrev_b32_e32 v4, 16, v3
	v_and_b32_e32 v5, 0xffff0000, v3
	v_and_b32_e32 v9, 0xffff0000, v11
	v_pk_mul_f32 v[4:5], v[4:5], v[8:9]
	v_lshlrev_b32_e32 v6, 16, v7
	v_and_b32_e32 v7, 0xffff0000, v7
	v_pk_mul_f32 v[4:5], v[4:5], v[6:7]
	ds_read_b128 v[8:11], v75 offset:17664
	v_cvt_pk_bf16_f32 v3, v4, v5
	v_lshl_add_u64 v[4:5], s[36:37], 0, v[12:13]
	v_lshlrev_b64 v[12:13], 1, v[132:133]
	global_store_dwordx4 v[4:5], v[0:3], off
	v_mov_b32_e32 v4, v92
	v_mov_b32_e32 v5, v93
	v_mov_b32_e32 v6, v94
	v_mov_b32_e32 v7, v95
	v_mov_b32_e32 v0, v88
	v_mov_b32_e32 v1, v89
	v_mov_b32_e32 v2, v90
	v_mov_b32_e32 v3, v91
	s_waitcnt lgkmcnt(0)
	v_lshlrev_b32_e32 v16, 16, v8
	v_and_b32_e32 v17, 0xffff0000, v8
	v_lshlrev_b32_e32 v8, 16, v9
	v_and_b32_e32 v9, 0xffff0000, v9
	v_add_u32_e32 v132, 0xfa018000, v18
	v_lshlrev_b32_e32 v14, 16, v0
	v_and_b32_e32 v15, 0xffff0000, v0
	v_pk_mul_f32 v[14:15], v[14:15], v[16:17]
	v_lshlrev_b32_e32 v16, 16, v4
	v_and_b32_e32 v17, 0xffff0000, v4
	v_pk_mul_f32 v[14:15], v[14:15], v[16:17]
	v_lshlrev_b32_e32 v4, 16, v5
	v_cvt_pk_bf16_f32 v0, v14, v15
	v_lshlrev_b32_e32 v14, 16, v1
	v_and_b32_e32 v15, 0xffff0000, v1
	v_pk_mul_f32 v[8:9], v[14:15], v[8:9]
	v_and_b32_e32 v5, 0xffff0000, v5
	v_pk_mul_f32 v[4:5], v[8:9], v[4:5]
	v_lshlrev_b32_e32 v8, 16, v10
	v_cvt_pk_bf16_f32 v1, v4, v5
	v_lshlrev_b32_e32 v4, 16, v2
	v_and_b32_e32 v5, 0xffff0000, v2
	v_and_b32_e32 v9, 0xffff0000, v10
	v_pk_mul_f32 v[4:5], v[4:5], v[8:9]
	v_lshlrev_b32_e32 v8, 16, v6
	v_and_b32_e32 v9, 0xffff0000, v6
	v_pk_mul_f32 v[4:5], v[4:5], v[8:9]
	v_lshlrev_b32_e32 v8, 16, v11
	v_cvt_pk_bf16_f32 v2, v4, v5
	v_lshlrev_b32_e32 v4, 16, v3
	v_and_b32_e32 v5, 0xffff0000, v3
	v_and_b32_e32 v9, 0xffff0000, v11
	v_pk_mul_f32 v[4:5], v[4:5], v[8:9]
	v_lshlrev_b32_e32 v6, 16, v7
	v_and_b32_e32 v7, 0xffff0000, v7
	v_pk_mul_f32 v[4:5], v[4:5], v[6:7]
	ds_read_b128 v[8:11], v75 offset:18944
	v_cvt_pk_bf16_f32 v3, v4, v5
	v_lshl_add_u64 v[4:5], s[36:37], 0, v[12:13]
	v_lshlrev_b64 v[12:13], 1, v[132:133]
	global_store_dwordx4 v[4:5], v[0:3], off
	v_mov_b32_e32 v4, v100
	v_mov_b32_e32 v5, v101
	v_mov_b32_e32 v6, v102
	v_mov_b32_e32 v7, v103
	v_mov_b32_e32 v0, v96
	v_mov_b32_e32 v1, v97
	v_mov_b32_e32 v2, v98
	v_mov_b32_e32 v3, v99
	s_waitcnt lgkmcnt(0)
; #define LAS __attribute__((address_space(3)))
; __device__ __forceinline__ unsigned pk2(float lo, float hi) { f32x2 v = {lo, hi}; bf16x2_t b = __builtin_convertvector(v, bf16x2_t); return __builtin_bit_cast(unsigned, b); }
; __device__ __forceinline__ float bflo(unsigned u) { return __uint_as_float(u << 16); }
; __device__ __forceinline__ float bfhi(unsigned u) { return __uint_as_float(u & 0xffff0000u); }
; template <int tbA, int tbB> ...
;     ...
;         for (int which = 0; which < 2; ++which) {
;             const int tb = which ? tbB : tbA;
; #pragma unroll
;             for (int i = 0; i < 2; ++i) {
;                 const int t = (lane >> 2) + 16 * i, ck = lane & 3;
;                 const size_t a = (size_t)(tok0 + tb * 32 + t) * DH + g * 128 + cb * 32 + ck * 8;
;                 const u32x4 uu = *(const u32x4*)(U + a), gc = *(const u32x4*)(GC + a);
;                 const u32x4 mv = *(const LAS u32x4*)(stg + which * 2560 + t * 80 + ck * 16);
;                 u32x4 o; o.x = pk2(bflo(uu.x) * bflo(mv.x) * bflo(gc.x), bfhi(uu.x) * bfhi(mv.x) * bfhi(gc.x)); o.y = pk2(bflo(uu.y) * bflo(mv.y) * bflo(gc.y), bfhi(uu.y) * bfhi(mv.y) * bfhi(gc.y));
;                 o.z = pk2(bflo(uu.z) * bflo(mv.z) * bflo(gc.z), bfhi(uu.z) * bfhi(mv.z) * bfhi(gc.z)); o.w = pk2(bflo(uu.w) * bflo(mv.w) * bflo(gc.w), bfhi(uu.w) * bfhi(mv.w) * bfhi(gc.w));
;                 *(u32x4*)(OC + a) = o;
;             }
	v_lshlrev_b32_e32 v16, 16, v8
	v_and_b32_e32 v17, 0xffff0000, v8
	v_lshlrev_b32_e32 v8, 16, v9
	v_and_b32_e32 v9, 0xffff0000, v9
	v_add_u32_e32 v132, 0xfa01c000, v18
	v_lshlrev_b32_e32 v14, 16, v0
	v_and_b32_e32 v15, 0xffff0000, v0
	v_pk_mul_f32 v[14:15], v[14:15], v[16:17]
	v_lshlrev_b32_e32 v16, 16, v4
	v_and_b32_e32 v17, 0xffff0000, v4
	v_pk_mul_f32 v[14:15], v[14:15], v[16:17]
	v_lshlrev_b32_e32 v4, 16, v5
	v_cvt_pk_bf16_f32 v0, v14, v15
	v_lshlrev_b32_e32 v14, 16, v1
	v_and_b32_e32 v15, 0xffff0000, v1
	v_pk_mul_f32 v[8:9], v[14:15], v[8:9]
	v_and_b32_e32 v5, 0xffff0000, v5
	v_pk_mul_f32 v[4:5], v[8:9], v[4:5]
	v_lshlrev_b32_e32 v8, 16, v10
	v_cvt_pk_bf16_f32 v1, v4, v5
	v_lshlrev_b32_e32 v4, 16, v2
	v_and_b32_e32 v5, 0xffff0000, v2
	v_and_b32_e32 v9, 0xffff0000, v10
	v_pk_mul_f32 v[4:5], v[4:5], v[8:9]
	v_lshlrev_b32_e32 v8, 16, v6
	v_and_b32_e32 v9, 0xffff0000, v6
	v_pk_mul_f32 v[4:5], v[4:5], v[8:9]
	v_lshlrev_b32_e32 v8, 16, v11
	v_cvt_pk_bf16_f32 v2, v4, v5
	v_lshlrev_b32_e32 v4, 16, v3
	v_and_b32_e32 v5, 0xffff0000, v3
	v_and_b32_e32 v9, 0xffff0000, v11
	v_pk_mul_f32 v[4:5], v[4:5], v[8:9]
	v_lshlrev_b32_e32 v6, 16, v7
	v_and_b32_e32 v7, 0xffff0000, v7
	v_pk_mul_f32 v[4:5], v[4:5], v[6:7]
	ds_read_b128 v[8:11], v75 offset:20224
	v_cvt_pk_bf16_f32 v3, v4, v5
	v_lshl_add_u64 v[4:5], s[36:37], 0, v[12:13]
	v_lshlrev_b64 v[12:13], 1, v[132:133]
	global_store_dwordx4 v[4:5], v[0:3], off
	v_mov_b32_e32 v4, v116
	v_mov_b32_e32 v5, v117
	v_mov_b32_e32 v6, v118
	v_mov_b32_e32 v7, v119
	v_mov_b32_e32 v0, v104
	v_mov_b32_e32 v1, v105
	v_mov_b32_e32 v2, v106
	v_mov_b32_e32 v3, v107
	s_waitcnt lgkmcnt(0)
	v_lshlrev_b32_e32 v16, 16, v8
	v_and_b32_e32 v17, 0xffff0000, v8
	v_lshlrev_b32_e32 v8, 16, v9
	v_and_b32_e32 v9, 0xffff0000, v9
	v_lshlrev_b32_e32 v14, 16, v0
	v_and_b32_e32 v15, 0xffff0000, v0
	v_pk_mul_f32 v[14:15], v[14:15], v[16:17]
	v_lshlrev_b32_e32 v16, 16, v4
	v_and_b32_e32 v17, 0xffff0000, v4
	v_pk_mul_f32 v[14:15], v[14:15], v[16:17]
	v_lshlrev_b32_e32 v4, 16, v5
	v_cvt_pk_bf16_f32 v0, v14, v15
	v_lshlrev_b32_e32 v14, 16, v1
	v_and_b32_e32 v15, 0xffff0000, v1
	v_pk_mul_f32 v[8:9], v[14:15], v[8:9]
	v_and_b32_e32 v5, 0xffff0000, v5
	v_pk_mul_f32 v[4:5], v[8:9], v[4:5]
	v_lshlrev_b32_e32 v8, 16, v10
	v_cvt_pk_bf16_f32 v1, v4, v5
	v_lshlrev_b32_e32 v4, 16, v2
	v_and_b32_e32 v5, 0xffff0000, v2
	v_and_b32_e32 v9, 0xffff0000, v10
	v_pk_mul_f32 v[4:5], v[4:5], v[8:9]
	v_lshlrev_b32_e32 v8, 16, v6
	v_and_b32_e32 v9, 0xffff0000, v6
	v_pk_mul_f32 v[4:5], v[4:5], v[8:9]
	v_lshlrev_b32_e32 v8, 16, v11
	v_cvt_pk_bf16_f32 v2, v4, v5
	v_lshlrev_b32_e32 v4, 16, v3
	v_and_b32_e32 v5, 0xffff0000, v3
	v_and_b32_e32 v9, 0xffff0000, v11
	v_pk_mul_f32 v[4:5], v[4:5], v[8:9]
	v_lshlrev_b32_e32 v6, 16, v7
	v_and_b32_e32 v7, 0xffff0000, v7
	v_pk_mul_f32 v[4:5], v[4:5], v[6:7]
	s_nop 0
	v_cvt_pk_bf16_f32 v3, v4, v5
	v_lshl_add_u64 v[4:5], s[36:37], 0, v[12:13]
	global_store_dwordx4 v[4:5], v[0:3], off
	s_cbranch_scc0 .LBB0_657
